# LDS-transposed coalesced residual epilogue (X f32, H bf16, 32-lane row-sumsq atomics) also in phases 6,10,15,19
# speedup vs baseline: 1.0229x; 1.0074x over previous
; #define GA_LOAD(pr_) do { _Pragma("unroll") for (int i = 0; i < 4; ++i) ra[i] = *(const u32x4*)(Ab + (i * 32) * lda + (pr_) * 64); } while (0)
; #define GB_LOAD(kt_) do { const bfr* bk_ = Bb + (kt_) * NB * 32; \
;     _Pragma("unroll") for (int i = 0; i < 4; ++i) rb[i] = *(const u32x4*)(bk_ + (i * 64) * 32); } while (0)
; #define G_STORE(kt_) do { bfr* as_ = S0 + ((kt_) & 1) * GSTAGE; bfr* bs_ = as_ + 128 * 40; \
;     if (apar == ((kt_) & 1)) { _Pragma("unroll") for (int i = 0; i < 4; ++i) *(u32x4*)(as_ + asoff + i * 32 * 40) = ra[i]; } \
;     _Pragma("unroll") for (int i = 0; i < 4; ++i) *(u32x4*)(bs_ + bsoff + i * 64 * 40) = rb[i]; } while (0)
; template <int lda>
; DI void gemm_mainloop(const bfr* __restrict__ A, const bfr* __restrict__ Bt, int NB, int K, int m0, int n0, char* smem, f32x16 (&acc)[2][4]) {
;     ...
;   const int nk = K >> 5;
;   const int arow = tid >> 3, ac8 = tid & 7, apar = ac8 >> 2;
;   const bfr* Ab = A + (m0 + arow) * lda + ac8 * 8;
;   const int asoff = arow * 40 + (ac8 & 3) * 8;
;   const int brow = tid >> 2, bc4 = tid & 3;
;   const bfr* Bb = Bt + (n0 + brow) * 32 + bc4 * 8;
;   const int bsoff = brow * 40 + bc4 * 8;
;     ...
;   GA_LOAD(0);
;   GB_LOAD(0);
;   G_STORE(0);
;   GB_LOAD(1);
;   __syncthreads();
; template <bool FIRST, bool HAS_H>
; DI void phase_gemm_resid(const Params& p, const bfr* A, const bfr* Wt, const float* gnext, float* ss, char* smem) {
;     ...
;   for (int t0 = blockIdx.x; t0 < 128 * 4; t0 += gridDim.x) {
;     const int t = ((gridDim.x & 7) == 0) ? xcd_tile(t0, 4) : t0;
;     const int mt = t >> 2, nt = t & 3, m0 = mt * 128, n0 = nt * 256;
;     f32x16 acc[2][4];
;     gemm_mainloop<1024>(A, Wt, 1024, 1024, m0, n0, smem, acc);
.LBB0_843:
	s_lshl_b32 s5, s4, 5
	s_and_b32 s40, s5, 0xffffff80
	s_lshl_b32 s4, s4, 8
	s_and_b32 s39, s4, 0x300
	s_mov_b32 s41, 0
	s_mov_b64 s[24:25], 0
	s_lshl_b32 s98, s40, 11
	s_add_u32 s98, s12, s98
	s_addc_u32 s99, s13, 0
	s_lshl_b32 s100, s39, 6
	s_add_u32 s100, s6, s100
	s_addc_u32 s101, s7, 0
	v_writelane_b32 v187, s64, 0
	v_writelane_b32 v187, s65, 1
	v_writelane_b32 v187, s66, 2
	v_writelane_b32 v187, s67, 3
	v_writelane_b32 v187, s68, 4
	v_writelane_b32 v187, s69, 5
	v_writelane_b32 v187, s70, 6
	v_writelane_b32 v187, s71, 7
	v_writelane_b32 v187, s72, 8
	v_writelane_b32 v187, s73, 9
	v_writelane_b32 v187, s74, 10
	v_writelane_b32 v187, s75, 11
	v_writelane_b32 v187, s76, 12
	v_writelane_b32 v187, s77, 13
	v_writelane_b32 v187, s78, 14
	v_writelane_b32 v187, s79, 15
	s_mov_b32 s77, s40
	s_mov_b32 s78, s39
	v_lshrrev_b32_e32 v188, 6, v196
	v_and_b32_e32 v190, 63, v196
	v_readfirstlane_b32 s73, v188
	v_lshrrev_b32_e32 v191, 2, v190
	v_bfe_u32 v192, v190, 4, 2
	v_and_b32_e32 v188, 3, v190
	v_xor_b32_e32 v188, v188, v192
	v_lshlrev_b32_e32 v188, 4, v188
	v_lshl_add_u32 v176, v191, 11, v188
	v_add_u32_e32 v177, 0x8000, v176
	v_lshl_add_u32 v178, v191, 6, v188
	v_and_b32_e32 v191, 31, v190
	v_lshrrev_b32_e32 v192, 5, v190
	v_bfe_u32 v188, v190, 2, 2
	v_xor_b32_e32 v188, v188, v192
	v_lshlrev_b32_e32 v188, 4, v188
	v_lshl_add_u32 v179, v191, 6, v188
	s_lshr_b32 s74, s73, 1
	s_lshl_b32 s74, s74, 12
	s_and_b32 s75, s73, 1
	s_lshl_b32 s75, s75, 13
	v_add_u32_e32 v181, s75, v179
	v_add_u32_e32 v179, s74, v179
	v_xor_b32_e32 v182, 32, v181
	v_xor_b32_e32 v180, 32, v179
	s_lshl_b32 s74, s73, 16
	s_add_u32 s64, s98, s74
	s_addc_u32 s65, s99, 0
	s_lshl_b32 s74, s73, 12
	s_add_u32 s66, s100, s74
	s_addc_u32 s67, s101, 0
	s_lshl_b32 s68, s73, 11
	s_lshl_b32 s69, s73, 12
	s_mov_b32 s70, 0
	s_mov_b32 s71, 0
	s_mov_b32 s72, 0
	s_waitcnt lgkmcnt(0)
	s_barrier
	s_mul_i32 s74, s70, 0x6000
	s_add_u32 s75, s74, s68
	s_mov_b32 m0, s75
	s_add_u32 s76, s74, 0x2000
	s_cmp_eq_u32 s70, 2
	s_cselect_b32 s76, 0x10000, s76
	global_load_lds_dwordx4 v176, s[64:65]
	s_add_u32 m0, s75, 0x400
	s_add_u32 s76, s76, s69
	global_load_lds_dwordx4 v177, s[64:65]
	s_mov_b32 m0, s76
	s_add_u32 s64, s64, 64
	s_addc_u32 s65, s65, 0
	global_load_lds_dwordx4 v178, s[66:67]
	global_load_lds_dwordx4 v178, s[66:67] offset:1024
	global_load_lds_dwordx4 v178, s[66:67] offset:2048
	global_load_lds_dwordx4 v178, s[66:67] offset:3072
	s_add_u32 s66, s66, 0x10000
	s_addc_u32 s67, s67, 0
	s_add_u32 s70, s70, 1
	s_cmp_eq_u32 s70, 3
	s_cselect_b32 s70, 0, s70
	s_mul_i32 s74, s70, 0x6000
	s_add_u32 s75, s74, s68
	s_mov_b32 m0, s75
	s_add_u32 s76, s74, 0x2000
	s_cmp_eq_u32 s70, 2
	s_cselect_b32 s76, 0x10000, s76
	global_load_lds_dwordx4 v176, s[64:65]
	s_add_u32 m0, s75, 0x400
	s_add_u32 s76, s76, s69
	global_load_lds_dwordx4 v177, s[64:65]
	s_mov_b32 m0, s76
	s_add_u32 s64, s64, 64
	s_addc_u32 s65, s65, 0
	global_load_lds_dwordx4 v178, s[66:67]
	global_load_lds_dwordx4 v178, s[66:67] offset:1024
	global_load_lds_dwordx4 v178, s[66:67] offset:2048
	global_load_lds_dwordx4 v178, s[66:67] offset:3072
	s_add_u32 s66, s66, 0x10000
	s_addc_u32 s67, s67, 0
	s_add_u32 s70, s70, 1
	s_cmp_eq_u32 s70, 3
	s_cselect_b32 s70, 0, s70
	s_cmp_lt_u32 s46, 0x100
	s_cbranch_scc1 .Lp6_nostag
	s_sleep 8

; #define MFMA32(a, b, c) __builtin_amdgcn_mfma_f32_32x32x16_bf16((a), (b), (c), 0, 0, 0)
; #define GA_LOAD(pr_) do { _Pragma("unroll") for (int i = 0; i < 4; ++i) ra[i] = *(const u32x4*)(Ab + (i * 32) * lda + (pr_) * 64); } while (0)
; #define GB_LOAD(kt_) do { const bfr* bk_ = Bb + (kt_) * NB * 32; \
;     _Pragma("unroll") for (int i = 0; i < 4; ++i) rb[i] = *(const u32x4*)(bk_ + (i * 64) * 32); } while (0)
; #define G_STORE(kt_) do { bfr* as_ = S0 + ((kt_) & 1) * GSTAGE; bfr* bs_ = as_ + 128 * 40; \
;     if (apar == ((kt_) & 1)) { _Pragma("unroll") for (int i = 0; i < 4; ++i) *(u32x4*)(as_ + asoff + i * 32 * 40) = ra[i]; } \
;     _Pragma("unroll") for (int i = 0; i < 4; ++i) *(u32x4*)(bs_ + bsoff + i * 64 * 40) = rb[i]; } while (0)
; template <int lda>
; DI void gemm_mainloop(const bfr* __restrict__ A, const bfr* __restrict__ Bt, int NB, int K, int m0, int n0, char* smem, f32x16 (&acc)[2][4]) {
;     ...
;   for (int kt = 0; kt < nk; ++kt) {
;     if (kt + 1 < nk) G_STORE(kt + 1);
;     if (kt + 2 < nk) {
;       GB_LOAD(kt + 2);
;       if ((kt & 1) == 0) GA_LOAD((kt >> 1) + 1);
;     }
;     const bfr* As = S0 + (kt & 1) * GSTAGE;
;     const bfr* Bs = As + 128 * 40;
; #pragma unroll
;     for (int ks = 0; ks < 2; ++ks) {
;       bf16x8 af[2], bfg[4];
; #pragma unroll
;       for (int i = 0; i < 2; ++i) af[i] = *(const bf16x8*)(As + (wr * 64 + i * 32 + r) * 40 + ks * 16 + hl * 8);
; #pragma unroll
;       for (int j = 0; j < 4; ++j) bfg[j] = *(const bf16x8*)(Bs + (wc * 128 + j * 32 + r) * 40 + ks * 16 + hl * 8);
; #pragma unroll
;       for (int i = 0; i < 2; ++i)
; #pragma unroll
;         for (int j = 0; j < 4; ++j) acc[i][j] = MFMA32(af[i], bfg[j], acc[i][j]);
;     }
;     __syncthreads();
;   }
.Lp6_loop:
	s_waitcnt vmcnt(6)
	s_barrier
	s_mul_i32 s74, s71, 0x6000
	s_add_u32 s75, s74, 0x2000
	s_cmp_eq_u32 s71, 2
	s_cselect_b32 s75, 0x10000, s75
	v_add_u32_e32 v183, s74, v179
	v_add_u32_e32 v185, s75, v181
	v_add_u32_e32 v184, s74, v180
	v_add_u32_e32 v186, s75, v182
	ds_read_b128 v[128:131], v183
	ds_read_b128 v[144:147], v185
	ds_read_b128 v[148:151], v185 offset:2048
	ds_read_b128 v[152:155], v185 offset:4096
	ds_read_b128 v[156:159], v185 offset:6144
	ds_read_b128 v[132:135], v183 offset:2048
	ds_read_b128 v[136:139], v184
	ds_read_b128 v[160:163], v186
	ds_read_b128 v[164:167], v186 offset:2048
	ds_read_b128 v[168:171], v186 offset:4096
	ds_read_b128 v[172:175], v186 offset:6144
	ds_read_b128 v[140:143], v184 offset:2048
	s_add_u32 s71, s71, 1
	s_cmp_eq_u32 s71, 3
	s_cselect_b32 s71, 0, s71
	s_waitcnt lgkmcnt(10)
	v_mfma_f32_32x32x16_bf16 v[112:127], v[144:147], v[128:131], v[112:127]
	s_mul_i32 s74, s70, 0x6000
	s_add_u32 s75, s74, s68
	s_mov_b32 m0, s75
	s_add_u32 s76, s74, 0x2000
	s_cmp_eq_u32 s70, 2
	s_cselect_b32 s76, 0x10000, s76
	global_load_lds_dwordx4 v176, s[64:65]
	s_waitcnt lgkmcnt(9)
	v_mfma_f32_32x32x16_bf16 v[96:111], v[148:151], v[128:131], v[96:111]
	s_add_u32 m0, s75, 0x400
	s_add_u32 s76, s76, s69
	global_load_lds_dwordx4 v177, s[64:65]
	s_waitcnt lgkmcnt(8)
	v_mfma_f32_32x32x16_bf16 v[80:95], v[152:155], v[128:131], v[80:95]
	s_mov_b32 m0, s76
	s_add_u32 s64, s64, 64
	s_addc_u32 s65, s65, 0
	global_load_lds_dwordx4 v178, s[66:67]
	s_waitcnt lgkmcnt(7)
	v_mfma_f32_32x32x16_bf16 v[64:79], v[156:159], v[128:131], v[64:79]
	global_load_lds_dwordx4 v178, s[66:67] offset:1024
	s_waitcnt lgkmcnt(6)
	v_mfma_f32_32x32x16_bf16 v[48:63], v[144:147], v[132:135], v[48:63]
	global_load_lds_dwordx4 v178, s[66:67] offset:2048
	v_mfma_f32_32x32x16_bf16 v[32:47], v[148:151], v[132:135], v[32:47]
	global_load_lds_dwordx4 v178, s[66:67] offset:3072
	s_add_u32 s66, s66, 0x10000
	s_addc_u32 s67, s67, 0
	v_mfma_f32_32x32x16_bf16 v[16:31], v[152:155], v[132:135], v[16:31]
	s_add_u32 s70, s70, 1
	s_cmp_eq_u32 s70, 3
	s_cselect_b32 s70, 0, s70
	v_mfma_f32_32x32x16_bf16 v[0:15], v[156:159], v[132:135], v[0:15]
	s_waitcnt lgkmcnt(4)
	v_mfma_f32_32x32x16_bf16 v[112:127], v[160:163], v[136:139], v[112:127]
	s_waitcnt lgkmcnt(3)
	v_mfma_f32_32x32x16_bf16 v[96:111], v[164:167], v[136:139], v[96:111]
	s_waitcnt lgkmcnt(2)
	v_mfma_f32_32x32x16_bf16 v[80:95], v[168:171], v[136:139], v[80:95]
	s_waitcnt lgkmcnt(1)
	v_mfma_f32_32x32x16_bf16 v[64:79], v[172:175], v[136:139], v[64:79]
	s_waitcnt lgkmcnt(0)
	v_mfma_f32_32x32x16_bf16 v[48:63], v[160:163], v[140:143], v[48:63]
	v_mfma_f32_32x32x16_bf16 v[32:47], v[164:167], v[140:143], v[32:47]
	v_mfma_f32_32x32x16_bf16 v[16:31], v[168:171], v[140:143], v[16:31]
	v_mfma_f32_32x32x16_bf16 v[0:15], v[172:175], v[140:143], v[0:15]
	s_add_u32 s72, s72, 1
	s_cmp_lt_u32 s72, 30
	s_cbranch_scc1 .Lp6_loop
	s_waitcnt vmcnt(6)
	s_barrier
	s_mul_i32 s74, s71, 0x6000
	s_add_u32 s75, s74, 0x2000
	s_cmp_eq_u32 s71, 2
	s_cselect_b32 s75, 0x10000, s75
	v_add_u32_e32 v183, s74, v179
	v_add_u32_e32 v185, s75, v181
	v_add_u32_e32 v184, s74, v180
	v_add_u32_e32 v186, s75, v182
	ds_read_b128 v[128:131], v183
	ds_read_b128 v[144:147], v185
	ds_read_b128 v[148:151], v185 offset:2048
	ds_read_b128 v[152:155], v185 offset:4096
	ds_read_b128 v[156:159], v185 offset:6144
	ds_read_b128 v[132:135], v183 offset:2048
	ds_read_b128 v[136:139], v184
	ds_read_b128 v[160:163], v186
	ds_read_b128 v[164:167], v186 offset:2048
	ds_read_b128 v[168:171], v186 offset:4096
	ds_read_b128 v[172:175], v186 offset:6144
	ds_read_b128 v[140:143], v184 offset:2048
	s_add_u32 s71, s71, 1
	s_cmp_eq_u32 s71, 3
	s_cselect_b32 s71, 0, s71
	s_waitcnt lgkmcnt(10)
	v_mfma_f32_32x32x16_bf16 v[112:127], v[144:147], v[128:131], v[112:127]
	s_waitcnt lgkmcnt(9)
	v_mfma_f32_32x32x16_bf16 v[96:111], v[148:151], v[128:131], v[96:111]
	s_waitcnt lgkmcnt(8)
	v_mfma_f32_32x32x16_bf16 v[80:95], v[152:155], v[128:131], v[80:95]
	s_waitcnt lgkmcnt(7)
	v_mfma_f32_32x32x16_bf16 v[64:79], v[156:159], v[128:131], v[64:79]
	s_waitcnt lgkmcnt(6)
	v_mfma_f32_32x32x16_bf16 v[48:63], v[144:147], v[132:135], v[48:63]
	v_mfma_f32_32x32x16_bf16 v[32:47], v[148:151], v[132:135], v[32:47]
	v_mfma_f32_32x32x16_bf16 v[16:31], v[152:155], v[132:135], v[16:31]
	v_mfma_f32_32x32x16_bf16 v[0:15], v[156:159], v[132:135], v[0:15]
	s_waitcnt lgkmcnt(4)
	v_mfma_f32_32x32x16_bf16 v[112:127], v[160:163], v[136:139], v[112:127]
	s_waitcnt lgkmcnt(3)
	v_mfma_f32_32x32x16_bf16 v[96:111], v[164:167], v[136:139], v[96:111]
	s_waitcnt lgkmcnt(2)
	v_mfma_f32_32x32x16_bf16 v[80:95], v[168:171], v[136:139], v[80:95]
	s_waitcnt lgkmcnt(1)
	v_mfma_f32_32x32x16_bf16 v[64:79], v[172:175], v[136:139], v[64:79]
	s_waitcnt lgkmcnt(0)
	v_mfma_f32_32x32x16_bf16 v[48:63], v[160:163], v[140:143], v[48:63]
	v_mfma_f32_32x32x16_bf16 v[32:47], v[164:167], v[140:143], v[32:47]
	v_mfma_f32_32x32x16_bf16 v[16:31], v[168:171], v[140:143], v[16:31]
	v_mfma_f32_32x32x16_bf16 v[0:15], v[172:175], v[140:143], v[0:15]
	s_waitcnt vmcnt(0)
	s_barrier
; #define MFMA32(a, b, c) __builtin_amdgcn_mfma_f32_32x32x16_bf16((a), (b), (c), 0, 0, 0)
; DI int crow(int reg, int h) { return (reg & 3) + 8 * (reg >> 2) + 4 * h; }
; template <int lda>
; DI void gemm_mainloop(const bfr* __restrict__ A, const bfr* __restrict__ Bt, int NB, int K, int m0, int n0, char* smem, f32x16 (&acc)[2][4]) {
;     ...
;     const bfr* As = S0 + (kt & 1) * GSTAGE;
;     const bfr* Bs = As + 128 * 40;
; #pragma unroll
;     for (int ks = 0; ks < 2; ++ks) {
;       bf16x8 af[2], bfg[4];
; #pragma unroll
;       for (int i = 0; i < 2; ++i) af[i] = *(const bf16x8*)(As + (wr * 64 + i * 32 + r) * 40 + ks * 16 + hl * 8);
; #pragma unroll
;       for (int j = 0; j < 4; ++j) bfg[j] = *(const bf16x8*)(Bs + (wc * 128 + j * 32 + r) * 40 + ks * 16 + hl * 8);
; #pragma unroll
;       for (int i = 0; i < 2; ++i)
; #pragma unroll
;         for (int j = 0; j < 4; ++j) acc[i][j] = MFMA32(af[i], bfg[j], acc[i][j]);
;     }
; template <bool FIRST, bool HAS_H>
; DI void phase_gemm_resid(const Params& p, const bfr* A, const bfr* Wt, const float* gnext, float* ss, char* smem) {
;     ...
;     int tid2 = threadIdx.x;
;     asm volatile("" : "+v"(tid2));
;     const int lane = tid2 & 63, wid = tid2 >> 6, wr = wid >> 1, wc = wid & 1, r = lane & 31, hl = lane >> 5;
;     const float* xsrc = FIRST ? p.x_prompt : X;
;     const int rbase = m0 + wr * 64 + 4 * hl, cbase = n0 + wc * 128 + r;
; #pragma unroll
;     for (int i = 0; i < 2; ++i) {
; #pragma unroll
;       for (int qh = 0; qh < 2; ++qh) {
;         float rs[8];
; #pragma unroll
;         for (int q = 0; q < 8; ++q) rs[q] = 0.f;
; #pragma unroll
;         for (int jh = 0; jh < 2; ++jh) {
;           float xo[2][8];
; #pragma unroll
;           for (int jj = 0; jj < 2; ++jj)
; #pragma unroll
;             for (int q = 0; q < 8; ++q)
;               xo[jj][q] = xsrc[(rbase + i * 32 + crow(qh * 8 + q, 0)) * 1024 + cbase + (jh * 2 + jj) * 32];
	s_mul_i32 s74, s71, 0x6000
	s_add_u32 s75, s74, 0x2000
	s_cmp_eq_u32 s71, 2
	s_cselect_b32 s75, 0x10000, s75
	v_add_u32_e32 v183, s74, v179
	v_add_u32_e32 v185, s75, v181
	v_add_u32_e32 v184, s74, v180
	v_add_u32_e32 v186, s75, v182
	ds_read_b128 v[128:131], v183
	ds_read_b128 v[144:147], v185
	ds_read_b128 v[148:151], v185 offset:2048
	ds_read_b128 v[152:155], v185 offset:4096
	ds_read_b128 v[156:159], v185 offset:6144
	ds_read_b128 v[132:135], v183 offset:2048
	ds_read_b128 v[136:139], v184
	ds_read_b128 v[160:163], v186
	ds_read_b128 v[164:167], v186 offset:2048
	ds_read_b128 v[168:171], v186 offset:4096
	ds_read_b128 v[172:175], v186 offset:6144
	ds_read_b128 v[140:143], v184 offset:2048
	s_add_u32 s71, s71, 1
	s_cmp_eq_u32 s71, 3
	s_cselect_b32 s71, 0, s71
	s_waitcnt lgkmcnt(10)
	v_mfma_f32_32x32x16_bf16 v[112:127], v[144:147], v[128:131], v[112:127]
	s_waitcnt lgkmcnt(9)
	v_mfma_f32_32x32x16_bf16 v[96:111], v[148:151], v[128:131], v[96:111]
	s_waitcnt lgkmcnt(8)
	v_mfma_f32_32x32x16_bf16 v[80:95], v[152:155], v[128:131], v[80:95]
	s_waitcnt lgkmcnt(7)
	v_mfma_f32_32x32x16_bf16 v[64:79], v[156:159], v[128:131], v[64:79]
	s_waitcnt lgkmcnt(6)
	v_mfma_f32_32x32x16_bf16 v[48:63], v[144:147], v[132:135], v[48:63]
	v_mfma_f32_32x32x16_bf16 v[32:47], v[148:151], v[132:135], v[32:47]
	v_mfma_f32_32x32x16_bf16 v[16:31], v[152:155], v[132:135], v[16:31]
	v_mfma_f32_32x32x16_bf16 v[0:15], v[156:159], v[132:135], v[0:15]
	s_waitcnt lgkmcnt(4)
	v_mfma_f32_32x32x16_bf16 v[112:127], v[160:163], v[136:139], v[112:127]
	s_waitcnt lgkmcnt(3)
	v_mfma_f32_32x32x16_bf16 v[96:111], v[164:167], v[136:139], v[96:111]
	s_waitcnt lgkmcnt(2)
	v_mfma_f32_32x32x16_bf16 v[80:95], v[168:171], v[136:139], v[80:95]
	s_waitcnt lgkmcnt(1)
	v_mfma_f32_32x32x16_bf16 v[64:79], v[172:175], v[136:139], v[64:79]
	s_waitcnt lgkmcnt(0)
	v_mfma_f32_32x32x16_bf16 v[48:63], v[160:163], v[140:143], v[48:63]
	v_mfma_f32_32x32x16_bf16 v[32:47], v[164:167], v[140:143], v[32:47]
	v_mfma_f32_32x32x16_bf16 v[16:31], v[168:171], v[140:143], v[16:31]
	v_mfma_f32_32x32x16_bf16 v[0:15], v[172:175], v[140:143], v[0:15]
	s_nop 7
	s_nop 3
	s_barrier
	s_load_dwordx2 s[64:65], s[92:93], 0x0
	s_load_dwordx2 s[66:67], s[92:93], 0x100
	s_load_dwordx2 s[68:69], s[92:93], 0x148
	s_load_dwordx2 s[70:71], s[92:93], 0x50
	s_mul_i32 s76, s73, 8704
	s_lshr_b32 s74, s73, 1
	s_lshl_b32 s74, s74, 6
	s_add_u32 s74, s74, s77
	s_and_b32 s75, s73, 1
	s_lshl_b32 s75, s75, 7
	s_add_u32 s75, s75, s78
	v_and_b32_e32 v188, 31, v196
	v_bfe_u32 v190, v196, 5, 1
	v_mul_u32_u24_e32 v191, 272, v188
	v_add_u32_e32 v191, s76, v191
	v_lshl_add_u32 v176, v190, 4, v191
	v_lshl_add_u32 v177, v190, 3, v191
	v_lshlrev_b32_e32 v191, 2, v190
	v_add_lshl_u32 v182, v191, s75, 2
	v_add_lshl_u32 v185, v188, s74, 2
	v_and_b32_e32 v191, 63, v196
	v_xor_b32_e32 v191, 32, v191
	v_lshlrev_b32_e32 v186, 2, v191
	v_bfe_u32 v188, v196, 4, 2
	v_and_b32_e32 v190, 15, v196
	v_mul_u32_u24_e32 v191, 272, v188
	v_lshl_add_u32 v191, v190, 4, v191
	v_add_u32_e32 v178, s76, v191
	v_add_u32_e32 v191, s74, v188
	v_lshlrev_b32_e32 v191, 10, v191
	v_lshl_add_u32 v191, v190, 2, v191
	v_add_lshl_u32 v180, v191, s75, 2
	v_bfe_u32 v188, v196, 3, 3
	v_and_b32_e32 v190, 7, v196
	v_mul_u32_u24_e32 v191, 272, v188
	v_lshl_add_u32 v191, v190, 4, v191
	v_add_u32_e32 v179, s76, v191
	v_add_u32_e32 v191, s74, v188
	v_lshlrev_b32_e32 v191, 10, v191
	v_lshl_add_u32 v191, v190, 3, v191
	v_add_lshl_u32 v181, v191, s75, 1
	v_mov_b32_e32 v183, 0
	v_mov_b32_e32 v184, 0
	s_waitcnt lgkmcnt(0)
	s_add_u32 s74, s64, 0x0
	s_addc_u32 s75, s65, 0
	global_load_dwordx4 v[128:131], v180, s[74:75]
	s_add_u32 s74, s64, 0x4000
	s_addc_u32 s75, s65, 0
	global_load_dwordx4 v[132:135], v180, s[74:75]
	s_add_u32 s74, s64, 0x8000
	s_addc_u32 s75, s65, 0
	global_load_dwordx4 v[136:139], v180, s[74:75]
	s_add_u32 s74, s64, 0xc000
	s_addc_u32 s75, s65, 0
	global_load_dwordx4 v[140:143], v180, s[74:75]
	s_add_u32 s74, s64, 0x10000
	s_addc_u32 s75, s65, 0
	global_load_dwordx4 v[144:147], v180, s[74:75]
	s_add_u32 s74, s64, 0x14000
	s_addc_u32 s75, s65, 0
	global_load_dwordx4 v[148:151], v180, s[74:75]
	s_add_u32 s74, s64, 0x18000
	s_addc_u32 s75, s65, 0
	global_load_dwordx4 v[152:155], v180, s[74:75]
	s_add_u32 s74, s64, 0x1c000
	s_addc_u32 s75, s65, 0
	global_load_dwordx4 v[156:159], v180, s[74:75]
	s_waitcnt vmcnt(7)
	ds_write_b128 v178, v[128:131]
	s_waitcnt vmcnt(6)
	ds_write_b128 v178, v[132:135] offset:1088
	s_waitcnt vmcnt(5)
	ds_write_b128 v178, v[136:139] offset:2176
	s_waitcnt vmcnt(4)
	ds_write_b128 v178, v[140:143] offset:3264
	s_waitcnt vmcnt(3)
	ds_write_b128 v178, v[144:147] offset:4352
	s_waitcnt vmcnt(2)
	ds_write_b128 v178, v[148:151] offset:5440
	s_waitcnt vmcnt(1)
	ds_write_b128 v178, v[152:155] offset:6528
	s_waitcnt vmcnt(0)
	ds_write_b128 v178, v[156:159] offset:7616
	ds_read_b128 v[128:131], v176
	ds_read_b128 v[132:135], v176 offset:32
	ds_read_b128 v[136:139], v176 offset:64
	ds_read_b128 v[140:143], v176 offset:96
	ds_read_b128 v[144:147], v176 offset:128
	ds_read_b128 v[148:151], v176 offset:160
	ds_read_b128 v[152:155], v176 offset:192
	ds_read_b128 v[156:159], v176 offset:224
	s_waitcnt lgkmcnt(7)
	v_add_f32_e32 v112, v128, v112
	v_add_f32_e32 v113, v129, v113
	v_add_f32_e32 v114, v130, v114
	v_add_f32_e32 v115, v131, v115
	v_fmac_f32_e32 v183, v112, v112
	v_fmac_f32_e32 v183, v113, v113
	v_fmac_f32_e32 v183, v114, v114
	v_fmac_f32_e32 v183, v115, v115
	ds_write_b128 v176, v[112:115]
	s_waitcnt lgkmcnt(7)
; DI bfr f2bf(float a) { return (bfr)(pack2(a, 0.f) & 0xffffu); }
; DI int crow(int reg, int h) { return (reg & 3) + 8 * (reg >> 2) + 4 * h; }
; template <bool FIRST, bool HAS_H>
; DI void phase_gemm_resid(const Params& p, const bfr* A, const bfr* Wt, const float* gnext, float* ss, char* smem) {
;     ...
; #pragma unroll
;     for (int i = 0; i < 2; ++i) {
; #pragma unroll
;       for (int qh = 0; qh < 2; ++qh) {
;         float rs[8];
; #pragma unroll
;         for (int q = 0; q < 8; ++q) rs[q] = 0.f;
; #pragma unroll
;         for (int jh = 0; jh < 2; ++jh) {
;           float xo[2][8];
; #pragma unroll
;           for (int jj = 0; jj < 2; ++jj)
; #pragma unroll
;             for (int q = 0; q < 8; ++q)
;               xo[jj][q] = xsrc[(rbase + i * 32 + crow(qh * 8 + q, 0)) * 1024 + cbase + (jh * 2 + jj) * 32];
; #pragma unroll
;           for (int q = 0; q < 8; ++q) {
;             const int o = (rbase + i * 32 + crow(qh * 8 + q, 0)) * 1024 + cbase;
; #pragma unroll
;             for (int jj = 0; jj < 2; ++jj) {
;               const int j = jh * 2 + jj;
;               const float xn = xo[jj][q] + acc[i][j][qh * 8 + q];
;               X[o + j * 32] = xn;
;               if (HAS_H) Hn[o + j * 32] = f2bf(xn * gnext[cbase + j * 32]);
;               rs[q] += xn * xn;
;             }
;           }
;         }
	v_add_f32_e32 v116, v132, v116
	v_add_f32_e32 v117, v133, v117
	v_add_f32_e32 v118, v134, v118
	v_add_f32_e32 v119, v135, v119
	v_fmac_f32_e32 v183, v116, v116
	v_fmac_f32_e32 v183, v117, v117
	v_fmac_f32_e32 v183, v118, v118
	v_fmac_f32_e32 v183, v119, v119
	ds_write_b128 v176, v[116:119] offset:32
	s_waitcnt lgkmcnt(7)
	v_add_f32_e32 v120, v136, v120
	v_add_f32_e32 v121, v137, v121
	v_add_f32_e32 v122, v138, v122
	v_add_f32_e32 v123, v139, v123
	v_fmac_f32_e32 v183, v120, v120
	v_fmac_f32_e32 v183, v121, v121
	v_fmac_f32_e32 v183, v122, v122
	v_fmac_f32_e32 v183, v123, v123
	ds_write_b128 v176, v[120:123] offset:64
	s_waitcnt lgkmcnt(7)
	v_add_f32_e32 v124, v140, v124
	v_add_f32_e32 v125, v141, v125
	v_add_f32_e32 v126, v142, v126
	v_add_f32_e32 v127, v143, v127
	v_fmac_f32_e32 v183, v124, v124
	v_fmac_f32_e32 v183, v125, v125
	v_fmac_f32_e32 v183, v126, v126
	v_fmac_f32_e32 v183, v127, v127
	ds_write_b128 v176, v[124:127] offset:96
	s_waitcnt lgkmcnt(7)
	v_add_f32_e32 v96, v144, v96
	v_add_f32_e32 v97, v145, v97
	v_add_f32_e32 v98, v146, v98
	v_add_f32_e32 v99, v147, v99
	v_fmac_f32_e32 v183, v96, v96
	v_fmac_f32_e32 v183, v97, v97
	v_fmac_f32_e32 v183, v98, v98
	v_fmac_f32_e32 v183, v99, v99
	ds_write_b128 v176, v[96:99] offset:128
	s_waitcnt lgkmcnt(7)
	v_add_f32_e32 v100, v148, v100
	v_add_f32_e32 v101, v149, v101
	v_add_f32_e32 v102, v150, v102
	v_add_f32_e32 v103, v151, v103
	v_fmac_f32_e32 v183, v100, v100
	v_fmac_f32_e32 v183, v101, v101
	v_fmac_f32_e32 v183, v102, v102
	v_fmac_f32_e32 v183, v103, v103
	ds_write_b128 v176, v[100:103] offset:160
	s_waitcnt lgkmcnt(7)
	v_add_f32_e32 v104, v152, v104
	v_add_f32_e32 v105, v153, v105
	v_add_f32_e32 v106, v154, v106
	v_add_f32_e32 v107, v155, v107
	v_fmac_f32_e32 v183, v104, v104
	v_fmac_f32_e32 v183, v105, v105
	v_fmac_f32_e32 v183, v106, v106
	v_fmac_f32_e32 v183, v107, v107
	ds_write_b128 v176, v[104:107] offset:192
	s_waitcnt lgkmcnt(7)
	v_add_f32_e32 v108, v156, v108
	v_add_f32_e32 v109, v157, v109
	v_add_f32_e32 v110, v158, v110
	v_add_f32_e32 v111, v159, v111
	v_fmac_f32_e32 v183, v108, v108
	v_fmac_f32_e32 v183, v109, v109
	v_fmac_f32_e32 v183, v110, v110
	v_fmac_f32_e32 v183, v111, v111
	ds_write_b128 v176, v[108:111] offset:224
	ds_read_b128 v[128:131], v178
	ds_read_b128 v[132:135], v178 offset:1088
	ds_read_b128 v[136:139], v178 offset:2176
	ds_read_b128 v[140:143], v178 offset:3264
	ds_read_b128 v[144:147], v178 offset:4352
	ds_read_b128 v[148:151], v178 offset:5440
	ds_read_b128 v[152:155], v178 offset:6528
	ds_read_b128 v[156:159], v178 offset:7616
	s_add_u32 s74, s66, 0x0
	s_addc_u32 s75, s67, 0
	s_waitcnt lgkmcnt(7)
	global_store_dwordx4 v180, v[128:131], s[74:75]
	s_add_u32 s74, s66, 0x4000
	s_addc_u32 s75, s67, 0
	s_waitcnt lgkmcnt(6)
	global_store_dwordx4 v180, v[132:135], s[74:75]
	s_add_u32 s74, s66, 0x8000
	s_addc_u32 s75, s67, 0
	s_waitcnt lgkmcnt(5)
	global_store_dwordx4 v180, v[136:139], s[74:75]
	s_add_u32 s74, s66, 0xc000
	s_addc_u32 s75, s67, 0
	s_waitcnt lgkmcnt(4)
	global_store_dwordx4 v180, v[140:143], s[74:75]
	s_add_u32 s74, s66, 0x10000
	s_addc_u32 s75, s67, 0
	s_waitcnt lgkmcnt(3)
	global_store_dwordx4 v180, v[144:147], s[74:75]
	s_add_u32 s74, s66, 0x14000
	s_addc_u32 s75, s67, 0
	s_waitcnt lgkmcnt(2)
	global_store_dwordx4 v180, v[148:151], s[74:75]
	s_add_u32 s74, s66, 0x18000
	s_addc_u32 s75, s67, 0
	s_waitcnt lgkmcnt(1)
	global_store_dwordx4 v180, v[152:155], s[74:75]
	s_add_u32 s74, s66, 0x1c000
	s_addc_u32 s75, s67, 0
	s_waitcnt lgkmcnt(0)
	global_store_dwordx4 v180, v[156:159], s[74:75]
	global_load_dwordx4 v[128:131], v182, s[70:71]
	global_load_dwordx4 v[132:135], v182, s[70:71] offset:32
	global_load_dwordx4 v[136:139], v182, s[70:71] offset:64
	global_load_dwordx4 v[140:143], v182, s[70:71] offset:96
	global_load_dwordx4 v[144:147], v182, s[70:71] offset:128
	global_load_dwordx4 v[148:151], v182, s[70:71] offset:160
	global_load_dwordx4 v[152:155], v182, s[70:71] offset:192
	global_load_dwordx4 v[156:159], v182, s[70:71] offset:224
	s_waitcnt vmcnt(7)
	v_mul_f32_e32 v112, v128, v112
	v_mul_f32_e32 v113, v129, v113
	v_mul_f32_e32 v114, v130, v114
	v_mul_f32_e32 v115, v131, v115
	v_cvt_pk_bf16_f32 v112, v112, v113
	v_cvt_pk_bf16_f32 v113, v114, v115
	ds_write_b64 v177, v[112:113]
	s_waitcnt vmcnt(6)
	v_mul_f32_e32 v116, v132, v116
	v_mul_f32_e32 v117, v133, v117
	v_mul_f32_e32 v118, v134, v118
	v_mul_f32_e32 v119, v135, v119
	v_cvt_pk_bf16_f32 v116, v116, v117
	v_cvt_pk_bf16_f32 v117, v118, v119
	ds_write_b64 v177, v[116:117] offset:16
	s_waitcnt vmcnt(5)
	v_mul_f32_e32 v120, v136, v120
	v_mul_f32_e32 v121, v137, v121
	v_mul_f32_e32 v122, v138, v122
	v_mul_f32_e32 v123, v139, v123
	v_cvt_pk_bf16_f32 v120, v120, v121
	v_cvt_pk_bf16_f32 v121, v122, v123
	ds_write_b64 v177, v[120:121] offset:32
	s_waitcnt vmcnt(4)
	v_mul_f32_e32 v124, v140, v124
	v_mul_f32_e32 v125, v141, v125
	v_mul_f32_e32 v126, v142, v126
	v_mul_f32_e32 v127, v143, v127
	v_cvt_pk_bf16_f32 v124, v124, v125
	v_cvt_pk_bf16_f32 v125, v126, v127
	ds_write_b64 v177, v[124:125] offset:48
	s_waitcnt vmcnt(3)
	v_mul_f32_e32 v96, v144, v96
	v_mul_f32_e32 v97, v145, v97
	v_mul_f32_e32 v98, v146, v98
	v_mul_f32_e32 v99, v147, v99
	v_cvt_pk_bf16_f32 v96, v96, v97
	v_cvt_pk_bf16_f32 v97, v98, v99
	ds_write_b64 v177, v[96:97] offset:64
	s_waitcnt vmcnt(2)
	v_mul_f32_e32 v100, v148, v100
	v_mul_f32_e32 v101, v149, v101
	v_mul_f32_e32 v102, v150, v102
	v_mul_f32_e32 v103, v151, v103
	v_cvt_pk_bf16_f32 v100, v100, v101
	v_cvt_pk_bf16_f32 v101, v102, v103
	ds_write_b64 v177, v[100:101] offset:80
	s_waitcnt vmcnt(1)
; DI bfr f2bf(float a) { return (bfr)(pack2(a, 0.f) & 0xffffu); }
; DI int crow(int reg, int h) { return (reg & 3) + 8 * (reg >> 2) + 4 * h; }
; template <bool FIRST, bool HAS_H>
; DI void phase_gemm_resid(const Params& p, const bfr* A, const bfr* Wt, const float* gnext, float* ss, char* smem) {
;     ...
; #pragma unroll
;     for (int i = 0; i < 2; ++i) {
; #pragma unroll
;       for (int qh = 0; qh < 2; ++qh) {
;         float rs[8];
; #pragma unroll
;         for (int q = 0; q < 8; ++q) rs[q] = 0.f;
; #pragma unroll
;         for (int jh = 0; jh < 2; ++jh) {
;           float xo[2][8];
; #pragma unroll
;           for (int jj = 0; jj < 2; ++jj)
; #pragma unroll
;             for (int q = 0; q < 8; ++q)
;               xo[jj][q] = xsrc[(rbase + i * 32 + crow(qh * 8 + q, 0)) * 1024 + cbase + (jh * 2 + jj) * 32];
; #pragma unroll
;           for (int q = 0; q < 8; ++q) {
;             const int o = (rbase + i * 32 + crow(qh * 8 + q, 0)) * 1024 + cbase;
; #pragma unroll
;             for (int jj = 0; jj < 2; ++jj) {
;               const int j = jh * 2 + jj;
;               const float xn = xo[jj][q] + acc[i][j][qh * 8 + q];
;               X[o + j * 32] = xn;
;               if (HAS_H) Hn[o + j * 32] = f2bf(xn * gnext[cbase + j * 32]);
;               rs[q] += xn * xn;
;             }
;           }
;         }
	v_mul_f32_e32 v104, v152, v104
	v_mul_f32_e32 v105, v153, v105
	v_mul_f32_e32 v106, v154, v106
	v_mul_f32_e32 v107, v155, v107
	v_cvt_pk_bf16_f32 v104, v104, v105
	v_cvt_pk_bf16_f32 v105, v106, v107
	ds_write_b64 v177, v[104:105] offset:96
	s_waitcnt vmcnt(0)
	v_mul_f32_e32 v108, v156, v108
	v_mul_f32_e32 v109, v157, v109
	v_mul_f32_e32 v110, v158, v110
	v_mul_f32_e32 v111, v159, v111
	v_cvt_pk_bf16_f32 v108, v108, v109
	v_cvt_pk_bf16_f32 v109, v110, v111
	ds_write_b64 v177, v[108:109] offset:112
	ds_read_b128 v[128:131], v179
	ds_read_b128 v[132:135], v179 offset:2176
	ds_read_b128 v[136:139], v179 offset:4352
	ds_read_b128 v[140:143], v179 offset:6528
	s_add_u32 s74, s68, 0x0
	s_addc_u32 s75, s69, 0
	s_waitcnt lgkmcnt(3)
	global_store_dwordx4 v181, v[128:131], s[74:75]
	s_add_u32 s74, s68, 0x4000
	s_addc_u32 s75, s69, 0
	s_waitcnt lgkmcnt(2)
	global_store_dwordx4 v181, v[132:135], s[74:75]
	s_add_u32 s74, s68, 0x8000
	s_addc_u32 s75, s69, 0
	s_waitcnt lgkmcnt(1)
	global_store_dwordx4 v181, v[136:139], s[74:75]
	s_add_u32 s74, s68, 0xc000
	s_addc_u32 s75, s69, 0
	s_waitcnt lgkmcnt(0)
	global_store_dwordx4 v181, v[140:143], s[74:75]
	s_add_u32 s74, s64, 0x100
	s_addc_u32 s75, s65, 0
	global_load_dwordx4 v[128:131], v180, s[74:75]
	s_add_u32 s74, s64, 0x4100
	s_addc_u32 s75, s65, 0
	global_load_dwordx4 v[132:135], v180, s[74:75]
	s_add_u32 s74, s64, 0x8100
	s_addc_u32 s75, s65, 0
	global_load_dwordx4 v[136:139], v180, s[74:75]
	s_add_u32 s74, s64, 0xc100
	s_addc_u32 s75, s65, 0
	global_load_dwordx4 v[140:143], v180, s[74:75]
	s_add_u32 s74, s64, 0x10100
	s_addc_u32 s75, s65, 0
	global_load_dwordx4 v[144:147], v180, s[74:75]
	s_add_u32 s74, s64, 0x14100
	s_addc_u32 s75, s65, 0
	global_load_dwordx4 v[148:151], v180, s[74:75]
	s_add_u32 s74, s64, 0x18100
	s_addc_u32 s75, s65, 0
	global_load_dwordx4 v[152:155], v180, s[74:75]
	s_add_u32 s74, s64, 0x1c100
	s_addc_u32 s75, s65, 0
	global_load_dwordx4 v[156:159], v180, s[74:75]
	s_waitcnt vmcnt(7)
	ds_write_b128 v178, v[128:131]
	s_waitcnt vmcnt(6)
	ds_write_b128 v178, v[132:135] offset:1088
	s_waitcnt vmcnt(5)
	ds_write_b128 v178, v[136:139] offset:2176
	s_waitcnt vmcnt(4)
	ds_write_b128 v178, v[140:143] offset:3264
	s_waitcnt vmcnt(3)
	ds_write_b128 v178, v[144:147] offset:4352
	s_waitcnt vmcnt(2)
	ds_write_b128 v178, v[148:151] offset:5440
	s_waitcnt vmcnt(1)
	ds_write_b128 v178, v[152:155] offset:6528
	s_waitcnt vmcnt(0)
	ds_write_b128 v178, v[156:159] offset:7616
	ds_read_b128 v[128:131], v176
	ds_read_b128 v[132:135], v176 offset:32
	ds_read_b128 v[136:139], v176 offset:64
	ds_read_b128 v[140:143], v176 offset:96
	ds_read_b128 v[144:147], v176 offset:128
	ds_read_b128 v[148:151], v176 offset:160
	ds_read_b128 v[152:155], v176 offset:192
	ds_read_b128 v[156:159], v176 offset:224
	s_waitcnt lgkmcnt(7)
	v_add_f32_e32 v80, v128, v80
	v_add_f32_e32 v81, v129, v81
	v_add_f32_e32 v82, v130, v82
	v_add_f32_e32 v83, v131, v83
	v_fmac_f32_e32 v183, v80, v80
	v_fmac_f32_e32 v183, v81, v81
	v_fmac_f32_e32 v183, v82, v82
	v_fmac_f32_e32 v183, v83, v83
	ds_write_b128 v176, v[80:83]
	s_waitcnt lgkmcnt(7)
	v_add_f32_e32 v84, v132, v84
	v_add_f32_e32 v85, v133, v85
	v_add_f32_e32 v86, v134, v86
	v_add_f32_e32 v87, v135, v87
	v_fmac_f32_e32 v183, v84, v84
	v_fmac_f32_e32 v183, v85, v85
	v_fmac_f32_e32 v183, v86, v86
	v_fmac_f32_e32 v183, v87, v87
	ds_write_b128 v176, v[84:87] offset:32
	s_waitcnt lgkmcnt(7)
	v_add_f32_e32 v88, v136, v88
	v_add_f32_e32 v89, v137, v89
	v_add_f32_e32 v90, v138, v90
	v_add_f32_e32 v91, v139, v91
	v_fmac_f32_e32 v183, v88, v88
	v_fmac_f32_e32 v183, v89, v89
	v_fmac_f32_e32 v183, v90, v90
	v_fmac_f32_e32 v183, v91, v91
	ds_write_b128 v176, v[88:91] offset:64
	s_waitcnt lgkmcnt(7)
	v_add_f32_e32 v92, v140, v92
	v_add_f32_e32 v93, v141, v93
	v_add_f32_e32 v94, v142, v94
	v_add_f32_e32 v95, v143, v95
	v_fmac_f32_e32 v183, v92, v92
	v_fmac_f32_e32 v183, v93, v93
	v_fmac_f32_e32 v183, v94, v94
	v_fmac_f32_e32 v183, v95, v95
	ds_write_b128 v176, v[92:95] offset:96
	s_waitcnt lgkmcnt(7)
	v_add_f32_e32 v64, v144, v64
	v_add_f32_e32 v65, v145, v65
	v_add_f32_e32 v66, v146, v66
	v_add_f32_e32 v67, v147, v67
	v_fmac_f32_e32 v183, v64, v64
	v_fmac_f32_e32 v183, v65, v65
	v_fmac_f32_e32 v183, v66, v66
	v_fmac_f32_e32 v183, v67, v67
	ds_write_b128 v176, v[64:67] offset:128
	s_waitcnt lgkmcnt(7)
	v_add_f32_e32 v68, v148, v68
	v_add_f32_e32 v69, v149, v69
	v_add_f32_e32 v70, v150, v70
	v_add_f32_e32 v71, v151, v71
	v_fmac_f32_e32 v183, v68, v68
	v_fmac_f32_e32 v183, v69, v69
	v_fmac_f32_e32 v183, v70, v70
	v_fmac_f32_e32 v183, v71, v71
	ds_write_b128 v176, v[68:71] offset:160
	s_waitcnt lgkmcnt(7)
	v_add_f32_e32 v72, v152, v72
	v_add_f32_e32 v73, v153, v73
	v_add_f32_e32 v74, v154, v74
	v_add_f32_e32 v75, v155, v75
	v_fmac_f32_e32 v183, v72, v72
	v_fmac_f32_e32 v183, v73, v73
	v_fmac_f32_e32 v183, v74, v74
	v_fmac_f32_e32 v183, v75, v75
	ds_write_b128 v176, v[72:75] offset:192
	s_waitcnt lgkmcnt(7)
	v_add_f32_e32 v76, v156, v76
	v_add_f32_e32 v77, v157, v77
	v_add_f32_e32 v78, v158, v78
	v_add_f32_e32 v79, v159, v79
	v_fmac_f32_e32 v183, v76, v76
	v_fmac_f32_e32 v183, v77, v77
	v_fmac_f32_e32 v183, v78, v78
	v_fmac_f32_e32 v183, v79, v79
	ds_write_b128 v176, v[76:79] offset:224
	ds_read_b128 v[128:131], v178
	ds_read_b128 v[132:135], v178 offset:1088
	ds_read_b128 v[136:139], v178 offset:2176
	ds_read_b128 v[140:143], v178 offset:3264
	ds_read_b128 v[144:147], v178 offset:4352
	ds_read_b128 v[148:151], v178 offset:5440
	ds_read_b128 v[152:155], v178 offset:6528
	ds_read_b128 v[156:159], v178 offset:7616
	s_add_u32 s74, s66, 0x100
	s_addc_u32 s75, s67, 0
	s_waitcnt lgkmcnt(7)
; DI bfr f2bf(float a) { return (bfr)(pack2(a, 0.f) & 0xffffu); }
; DI int crow(int reg, int h) { return (reg & 3) + 8 * (reg >> 2) + 4 * h; }
; template <bool FIRST, bool HAS_H>
; DI void phase_gemm_resid(const Params& p, const bfr* A, const bfr* Wt, const float* gnext, float* ss, char* smem) {
;     ...
; #pragma unroll
;     for (int i = 0; i < 2; ++i) {
; #pragma unroll
;       for (int qh = 0; qh < 2; ++qh) {
;         float rs[8];
; #pragma unroll
;         for (int q = 0; q < 8; ++q) rs[q] = 0.f;
; #pragma unroll
;         for (int jh = 0; jh < 2; ++jh) {
;           float xo[2][8];
; #pragma unroll
;           for (int jj = 0; jj < 2; ++jj)
; #pragma unroll
;             for (int q = 0; q < 8; ++q)
;               xo[jj][q] = xsrc[(rbase + i * 32 + crow(qh * 8 + q, 0)) * 1024 + cbase + (jh * 2 + jj) * 32];
; #pragma unroll
;           for (int q = 0; q < 8; ++q) {
;             const int o = (rbase + i * 32 + crow(qh * 8 + q, 0)) * 1024 + cbase;
; #pragma unroll
;             for (int jj = 0; jj < 2; ++jj) {
;               const int j = jh * 2 + jj;
;               const float xn = xo[jj][q] + acc[i][j][qh * 8 + q];
;               X[o + j * 32] = xn;
;               if (HAS_H) Hn[o + j * 32] = f2bf(xn * gnext[cbase + j * 32]);
;               rs[q] += xn * xn;
;             }
;           }
;         }
	global_store_dwordx4 v180, v[128:131], s[74:75]
	s_add_u32 s74, s66, 0x4100
	s_addc_u32 s75, s67, 0
	s_waitcnt lgkmcnt(6)
	global_store_dwordx4 v180, v[132:135], s[74:75]
	s_add_u32 s74, s66, 0x8100
	s_addc_u32 s75, s67, 0
	s_waitcnt lgkmcnt(5)
	global_store_dwordx4 v180, v[136:139], s[74:75]
	s_add_u32 s74, s66, 0xc100
	s_addc_u32 s75, s67, 0
	s_waitcnt lgkmcnt(4)
	global_store_dwordx4 v180, v[140:143], s[74:75]
	s_add_u32 s74, s66, 0x10100
	s_addc_u32 s75, s67, 0
	s_waitcnt lgkmcnt(3)
	global_store_dwordx4 v180, v[144:147], s[74:75]
	s_add_u32 s74, s66, 0x14100
	s_addc_u32 s75, s67, 0
	s_waitcnt lgkmcnt(2)
	global_store_dwordx4 v180, v[148:151], s[74:75]
	s_add_u32 s74, s66, 0x18100
	s_addc_u32 s75, s67, 0
	s_waitcnt lgkmcnt(1)
	global_store_dwordx4 v180, v[152:155], s[74:75]
	s_add_u32 s74, s66, 0x1c100
	s_addc_u32 s75, s67, 0
	s_waitcnt lgkmcnt(0)
	global_store_dwordx4 v180, v[156:159], s[74:75]
	global_load_dwordx4 v[128:131], v182, s[70:71] offset:256
	global_load_dwordx4 v[132:135], v182, s[70:71] offset:288
	global_load_dwordx4 v[136:139], v182, s[70:71] offset:320
	global_load_dwordx4 v[140:143], v182, s[70:71] offset:352
	global_load_dwordx4 v[144:147], v182, s[70:71] offset:384
	global_load_dwordx4 v[148:151], v182, s[70:71] offset:416
	global_load_dwordx4 v[152:155], v182, s[70:71] offset:448
	global_load_dwordx4 v[156:159], v182, s[70:71] offset:480
	s_waitcnt vmcnt(7)
	v_mul_f32_e32 v80, v128, v80
	v_mul_f32_e32 v81, v129, v81
	v_mul_f32_e32 v82, v130, v82
	v_mul_f32_e32 v83, v131, v83
	v_cvt_pk_bf16_f32 v80, v80, v81
	v_cvt_pk_bf16_f32 v81, v82, v83
	ds_write_b64 v177, v[80:81]
	s_waitcnt vmcnt(6)
	v_mul_f32_e32 v84, v132, v84
	v_mul_f32_e32 v85, v133, v85
	v_mul_f32_e32 v86, v134, v86
	v_mul_f32_e32 v87, v135, v87
	v_cvt_pk_bf16_f32 v84, v84, v85
	v_cvt_pk_bf16_f32 v85, v86, v87
	ds_write_b64 v177, v[84:85] offset:16
	s_waitcnt vmcnt(5)
	v_mul_f32_e32 v88, v136, v88
	v_mul_f32_e32 v89, v137, v89
	v_mul_f32_e32 v90, v138, v90
	v_mul_f32_e32 v91, v139, v91
	v_cvt_pk_bf16_f32 v88, v88, v89
	v_cvt_pk_bf16_f32 v89, v90, v91
	ds_write_b64 v177, v[88:89] offset:32
	s_waitcnt vmcnt(4)
	v_mul_f32_e32 v92, v140, v92
	v_mul_f32_e32 v93, v141, v93
	v_mul_f32_e32 v94, v142, v94
	v_mul_f32_e32 v95, v143, v95
	v_cvt_pk_bf16_f32 v92, v92, v93
	v_cvt_pk_bf16_f32 v93, v94, v95
	ds_write_b64 v177, v[92:93] offset:48
	s_waitcnt vmcnt(3)
	v_mul_f32_e32 v64, v144, v64
	v_mul_f32_e32 v65, v145, v65
	v_mul_f32_e32 v66, v146, v66
	v_mul_f32_e32 v67, v147, v67
	v_cvt_pk_bf16_f32 v64, v64, v65
	v_cvt_pk_bf16_f32 v65, v66, v67
	ds_write_b64 v177, v[64:65] offset:64
	s_waitcnt vmcnt(2)
	v_mul_f32_e32 v68, v148, v68
	v_mul_f32_e32 v69, v149, v69
	v_mul_f32_e32 v70, v150, v70
	v_mul_f32_e32 v71, v151, v71
	v_cvt_pk_bf16_f32 v68, v68, v69
	v_cvt_pk_bf16_f32 v69, v70, v71
	ds_write_b64 v177, v[68:69] offset:80
	s_waitcnt vmcnt(1)
	v_mul_f32_e32 v72, v152, v72
	v_mul_f32_e32 v73, v153, v73
	v_mul_f32_e32 v74, v154, v74
	v_mul_f32_e32 v75, v155, v75
	v_cvt_pk_bf16_f32 v72, v72, v73
	v_cvt_pk_bf16_f32 v73, v74, v75
	ds_write_b64 v177, v[72:73] offset:96
	s_waitcnt vmcnt(0)
	v_mul_f32_e32 v76, v156, v76
	v_mul_f32_e32 v77, v157, v77
	v_mul_f32_e32 v78, v158, v78
	v_mul_f32_e32 v79, v159, v79
	v_cvt_pk_bf16_f32 v76, v76, v77
	v_cvt_pk_bf16_f32 v77, v78, v79
	ds_write_b64 v177, v[76:77] offset:112
	ds_read_b128 v[128:131], v179
	ds_read_b128 v[132:135], v179 offset:2176
	ds_read_b128 v[136:139], v179 offset:4352
	ds_read_b128 v[140:143], v179 offset:6528
	s_add_u32 s74, s68, 0x80
	s_addc_u32 s75, s69, 0
	s_waitcnt lgkmcnt(3)
	global_store_dwordx4 v181, v[128:131], s[74:75]
	s_add_u32 s74, s68, 0x4080
	s_addc_u32 s75, s69, 0
	s_waitcnt lgkmcnt(2)
	global_store_dwordx4 v181, v[132:135], s[74:75]
	s_add_u32 s74, s68, 0x8080
	s_addc_u32 s75, s69, 0
	s_waitcnt lgkmcnt(1)
	global_store_dwordx4 v181, v[136:139], s[74:75]
	s_add_u32 s74, s68, 0xc080
	s_addc_u32 s75, s69, 0
	s_waitcnt lgkmcnt(0)
	global_store_dwordx4 v181, v[140:143], s[74:75]
	s_add_u32 s74, s64, 0x20000
	s_addc_u32 s75, s65, 0
	global_load_dwordx4 v[128:131], v180, s[74:75]
	s_add_u32 s74, s64, 0x24000
	s_addc_u32 s75, s65, 0
	global_load_dwordx4 v[132:135], v180, s[74:75]
	s_add_u32 s74, s64, 0x28000
	s_addc_u32 s75, s65, 0
	global_load_dwordx4 v[136:139], v180, s[74:75]
	s_add_u32 s74, s64, 0x2c000
	s_addc_u32 s75, s65, 0
	global_load_dwordx4 v[140:143], v180, s[74:75]
	s_add_u32 s74, s64, 0x30000
	s_addc_u32 s75, s65, 0
	global_load_dwordx4 v[144:147], v180, s[74:75]
	s_add_u32 s74, s64, 0x34000
	s_addc_u32 s75, s65, 0
	global_load_dwordx4 v[148:151], v180, s[74:75]
	s_add_u32 s74, s64, 0x38000
	s_addc_u32 s75, s65, 0
	global_load_dwordx4 v[152:155], v180, s[74:75]
	s_add_u32 s74, s64, 0x3c000
	s_addc_u32 s75, s65, 0
	global_load_dwordx4 v[156:159], v180, s[74:75]
	s_waitcnt vmcnt(7)
	ds_write_b128 v178, v[128:131]
	s_waitcnt vmcnt(6)
	ds_write_b128 v178, v[132:135] offset:1088
	s_waitcnt vmcnt(5)
	ds_write_b128 v178, v[136:139] offset:2176
	s_waitcnt vmcnt(4)
	ds_write_b128 v178, v[140:143] offset:3264
	s_waitcnt vmcnt(3)
	ds_write_b128 v178, v[144:147] offset:4352
	s_waitcnt vmcnt(2)
	ds_write_b128 v178, v[148:151] offset:5440
	s_waitcnt vmcnt(1)
	ds_write_b128 v178, v[152:155] offset:6528
	s_waitcnt vmcnt(0)
	ds_write_b128 v178, v[156:159] offset:7616
	ds_read_b128 v[128:131], v176
	ds_read_b128 v[132:135], v176 offset:32
	ds_read_b128 v[136:139], v176 offset:64
	ds_read_b128 v[140:143], v176 offset:96
	ds_read_b128 v[144:147], v176 offset:128
	ds_read_b128 v[148:151], v176 offset:160
	ds_read_b128 v[152:155], v176 offset:192
	ds_read_b128 v[156:159], v176 offset:224
	s_waitcnt lgkmcnt(7)
; DI bfr f2bf(float a) { return (bfr)(pack2(a, 0.f) & 0xffffu); }
; DI int crow(int reg, int h) { return (reg & 3) + 8 * (reg >> 2) + 4 * h; }
; template <bool FIRST, bool HAS_H>
; DI void phase_gemm_resid(const Params& p, const bfr* A, const bfr* Wt, const float* gnext, float* ss, char* smem) {
;     ...
; #pragma unroll
;     for (int i = 0; i < 2; ++i) {
; #pragma unroll
;       for (int qh = 0; qh < 2; ++qh) {
;         float rs[8];
; #pragma unroll
;         for (int q = 0; q < 8; ++q) rs[q] = 0.f;
; #pragma unroll
;         for (int jh = 0; jh < 2; ++jh) {
;           float xo[2][8];
; #pragma unroll
;           for (int jj = 0; jj < 2; ++jj)
; #pragma unroll
;             for (int q = 0; q < 8; ++q)
;               xo[jj][q] = xsrc[(rbase + i * 32 + crow(qh * 8 + q, 0)) * 1024 + cbase + (jh * 2 + jj) * 32];
; #pragma unroll
;           for (int q = 0; q < 8; ++q) {
;             const int o = (rbase + i * 32 + crow(qh * 8 + q, 0)) * 1024 + cbase;
; #pragma unroll
;             for (int jj = 0; jj < 2; ++jj) {
;               const int j = jh * 2 + jj;
;               const float xn = xo[jj][q] + acc[i][j][qh * 8 + q];
;               X[o + j * 32] = xn;
;               if (HAS_H) Hn[o + j * 32] = f2bf(xn * gnext[cbase + j * 32]);
;               rs[q] += xn * xn;
;             }
;           }
;         }
	v_add_f32_e32 v48, v128, v48
	v_add_f32_e32 v49, v129, v49
	v_add_f32_e32 v50, v130, v50
	v_add_f32_e32 v51, v131, v51
	v_fmac_f32_e32 v184, v48, v48
	v_fmac_f32_e32 v184, v49, v49
	v_fmac_f32_e32 v184, v50, v50
	v_fmac_f32_e32 v184, v51, v51
	ds_write_b128 v176, v[48:51]
	s_waitcnt lgkmcnt(7)
	v_add_f32_e32 v52, v132, v52
	v_add_f32_e32 v53, v133, v53
	v_add_f32_e32 v54, v134, v54
	v_add_f32_e32 v55, v135, v55
	v_fmac_f32_e32 v184, v52, v52
	v_fmac_f32_e32 v184, v53, v53
	v_fmac_f32_e32 v184, v54, v54
	v_fmac_f32_e32 v184, v55, v55
	ds_write_b128 v176, v[52:55] offset:32
	s_waitcnt lgkmcnt(7)
	v_add_f32_e32 v56, v136, v56
	v_add_f32_e32 v57, v137, v57
	v_add_f32_e32 v58, v138, v58
	v_add_f32_e32 v59, v139, v59
	v_fmac_f32_e32 v184, v56, v56
	v_fmac_f32_e32 v184, v57, v57
	v_fmac_f32_e32 v184, v58, v58
	v_fmac_f32_e32 v184, v59, v59
	ds_write_b128 v176, v[56:59] offset:64
	s_waitcnt lgkmcnt(7)
	v_add_f32_e32 v60, v140, v60
	v_add_f32_e32 v61, v141, v61
	v_add_f32_e32 v62, v142, v62
	v_add_f32_e32 v63, v143, v63
	v_fmac_f32_e32 v184, v60, v60
	v_fmac_f32_e32 v184, v61, v61
	v_fmac_f32_e32 v184, v62, v62
	v_fmac_f32_e32 v184, v63, v63
	ds_write_b128 v176, v[60:63] offset:96
	s_waitcnt lgkmcnt(7)
	v_add_f32_e32 v32, v144, v32
	v_add_f32_e32 v33, v145, v33
	v_add_f32_e32 v34, v146, v34
	v_add_f32_e32 v35, v147, v35
	v_fmac_f32_e32 v184, v32, v32
	v_fmac_f32_e32 v184, v33, v33
	v_fmac_f32_e32 v184, v34, v34
	v_fmac_f32_e32 v184, v35, v35
	ds_write_b128 v176, v[32:35] offset:128
	s_waitcnt lgkmcnt(7)
	v_add_f32_e32 v36, v148, v36
	v_add_f32_e32 v37, v149, v37
	v_add_f32_e32 v38, v150, v38
	v_add_f32_e32 v39, v151, v39
	v_fmac_f32_e32 v184, v36, v36
	v_fmac_f32_e32 v184, v37, v37
	v_fmac_f32_e32 v184, v38, v38
	v_fmac_f32_e32 v184, v39, v39
	ds_write_b128 v176, v[36:39] offset:160
	s_waitcnt lgkmcnt(7)
	v_add_f32_e32 v40, v152, v40
	v_add_f32_e32 v41, v153, v41
	v_add_f32_e32 v42, v154, v42
	v_add_f32_e32 v43, v155, v43
	v_fmac_f32_e32 v184, v40, v40
	v_fmac_f32_e32 v184, v41, v41
	v_fmac_f32_e32 v184, v42, v42
	v_fmac_f32_e32 v184, v43, v43
	ds_write_b128 v176, v[40:43] offset:192
	s_waitcnt lgkmcnt(7)
	v_add_f32_e32 v44, v156, v44
	v_add_f32_e32 v45, v157, v45
	v_add_f32_e32 v46, v158, v46
	v_add_f32_e32 v47, v159, v47
	v_fmac_f32_e32 v184, v44, v44
	v_fmac_f32_e32 v184, v45, v45
	v_fmac_f32_e32 v184, v46, v46
	v_fmac_f32_e32 v184, v47, v47
	ds_write_b128 v176, v[44:47] offset:224
	ds_read_b128 v[128:131], v178
	ds_read_b128 v[132:135], v178 offset:1088
	ds_read_b128 v[136:139], v178 offset:2176
	ds_read_b128 v[140:143], v178 offset:3264
	ds_read_b128 v[144:147], v178 offset:4352
	ds_read_b128 v[148:151], v178 offset:5440
	ds_read_b128 v[152:155], v178 offset:6528
	ds_read_b128 v[156:159], v178 offset:7616
	s_add_u32 s74, s66, 0x20000
	s_addc_u32 s75, s67, 0
	s_waitcnt lgkmcnt(7)
	global_store_dwordx4 v180, v[128:131], s[74:75]
	s_add_u32 s74, s66, 0x24000
	s_addc_u32 s75, s67, 0
	s_waitcnt lgkmcnt(6)
	global_store_dwordx4 v180, v[132:135], s[74:75]
	s_add_u32 s74, s66, 0x28000
	s_addc_u32 s75, s67, 0
	s_waitcnt lgkmcnt(5)
	global_store_dwordx4 v180, v[136:139], s[74:75]
	s_add_u32 s74, s66, 0x2c000
	s_addc_u32 s75, s67, 0
	s_waitcnt lgkmcnt(4)
	global_store_dwordx4 v180, v[140:143], s[74:75]
	s_add_u32 s74, s66, 0x30000
	s_addc_u32 s75, s67, 0
	s_waitcnt lgkmcnt(3)
	global_store_dwordx4 v180, v[144:147], s[74:75]
	s_add_u32 s74, s66, 0x34000
	s_addc_u32 s75, s67, 0
	s_waitcnt lgkmcnt(2)
	global_store_dwordx4 v180, v[148:151], s[74:75]
	s_add_u32 s74, s66, 0x38000
	s_addc_u32 s75, s67, 0
	s_waitcnt lgkmcnt(1)
	global_store_dwordx4 v180, v[152:155], s[74:75]
	s_add_u32 s74, s66, 0x3c000
	s_addc_u32 s75, s67, 0
	s_waitcnt lgkmcnt(0)
	global_store_dwordx4 v180, v[156:159], s[74:75]
	global_load_dwordx4 v[128:131], v182, s[70:71]
	global_load_dwordx4 v[132:135], v182, s[70:71] offset:32
	global_load_dwordx4 v[136:139], v182, s[70:71] offset:64
	global_load_dwordx4 v[140:143], v182, s[70:71] offset:96
	global_load_dwordx4 v[144:147], v182, s[70:71] offset:128
	global_load_dwordx4 v[148:151], v182, s[70:71] offset:160
	global_load_dwordx4 v[152:155], v182, s[70:71] offset:192
	global_load_dwordx4 v[156:159], v182, s[70:71] offset:224
	s_waitcnt vmcnt(7)
	v_mul_f32_e32 v48, v128, v48
	v_mul_f32_e32 v49, v129, v49
	v_mul_f32_e32 v50, v130, v50
	v_mul_f32_e32 v51, v131, v51
	v_cvt_pk_bf16_f32 v48, v48, v49
	v_cvt_pk_bf16_f32 v49, v50, v51
	ds_write_b64 v177, v[48:49]
	s_waitcnt vmcnt(6)
	v_mul_f32_e32 v52, v132, v52
	v_mul_f32_e32 v53, v133, v53
	v_mul_f32_e32 v54, v134, v54
	v_mul_f32_e32 v55, v135, v55
	v_cvt_pk_bf16_f32 v52, v52, v53
	v_cvt_pk_bf16_f32 v53, v54, v55
	ds_write_b64 v177, v[52:53] offset:16
	s_waitcnt vmcnt(5)
	v_mul_f32_e32 v56, v136, v56
	v_mul_f32_e32 v57, v137, v57
	v_mul_f32_e32 v58, v138, v58
	v_mul_f32_e32 v59, v139, v59
	v_cvt_pk_bf16_f32 v56, v56, v57
	v_cvt_pk_bf16_f32 v57, v58, v59
	ds_write_b64 v177, v[56:57] offset:32
	s_waitcnt vmcnt(4)
	v_mul_f32_e32 v60, v140, v60
	v_mul_f32_e32 v61, v141, v61
	v_mul_f32_e32 v62, v142, v62
	v_mul_f32_e32 v63, v143, v63
	v_cvt_pk_bf16_f32 v60, v60, v61
	v_cvt_pk_bf16_f32 v61, v62, v63
	ds_write_b64 v177, v[60:61] offset:48
	s_waitcnt vmcnt(3)
	v_mul_f32_e32 v32, v144, v32
	v_mul_f32_e32 v33, v145, v33
	v_mul_f32_e32 v34, v146, v34
	v_mul_f32_e32 v35, v147, v35
	v_cvt_pk_bf16_f32 v32, v32, v33
	v_cvt_pk_bf16_f32 v33, v34, v35
	ds_write_b64 v177, v[32:33] offset:64
	s_waitcnt vmcnt(2)
	v_mul_f32_e32 v36, v148, v36
	v_mul_f32_e32 v37, v149, v37
	v_mul_f32_e32 v38, v150, v38
	v_mul_f32_e32 v39, v151, v39
	v_cvt_pk_bf16_f32 v36, v36, v37
	v_cvt_pk_bf16_f32 v37, v38, v39
	ds_write_b64 v177, v[36:37] offset:80
	s_waitcnt vmcnt(1)
; DI bfr f2bf(float a) { return (bfr)(pack2(a, 0.f) & 0xffffu); }
; DI int crow(int reg, int h) { return (reg & 3) + 8 * (reg >> 2) + 4 * h; }
; template <bool FIRST, bool HAS_H>
; DI void phase_gemm_resid(const Params& p, const bfr* A, const bfr* Wt, const float* gnext, float* ss, char* smem) {
;     ...
; #pragma unroll
;     for (int i = 0; i < 2; ++i) {
; #pragma unroll
;       for (int qh = 0; qh < 2; ++qh) {
;         float rs[8];
; #pragma unroll
;         for (int q = 0; q < 8; ++q) rs[q] = 0.f;
; #pragma unroll
;         for (int jh = 0; jh < 2; ++jh) {
;           float xo[2][8];
; #pragma unroll
;           for (int jj = 0; jj < 2; ++jj)
; #pragma unroll
;             for (int q = 0; q < 8; ++q)
;               xo[jj][q] = xsrc[(rbase + i * 32 + crow(qh * 8 + q, 0)) * 1024 + cbase + (jh * 2 + jj) * 32];
; #pragma unroll
;           for (int q = 0; q < 8; ++q) {
;             const int o = (rbase + i * 32 + crow(qh * 8 + q, 0)) * 1024 + cbase;
; #pragma unroll
;             for (int jj = 0; jj < 2; ++jj) {
;               const int j = jh * 2 + jj;
;               const float xn = xo[jj][q] + acc[i][j][qh * 8 + q];
;               X[o + j * 32] = xn;
;               if (HAS_H) Hn[o + j * 32] = f2bf(xn * gnext[cbase + j * 32]);
;               rs[q] += xn * xn;
;             }
;           }
;         }
	v_mul_f32_e32 v40, v152, v40
	v_mul_f32_e32 v41, v153, v41
	v_mul_f32_e32 v42, v154, v42
	v_mul_f32_e32 v43, v155, v43
	v_cvt_pk_bf16_f32 v40, v40, v41
	v_cvt_pk_bf16_f32 v41, v42, v43
	ds_write_b64 v177, v[40:41] offset:96
	s_waitcnt vmcnt(0)
	v_mul_f32_e32 v44, v156, v44
	v_mul_f32_e32 v45, v157, v45
	v_mul_f32_e32 v46, v158, v46
	v_mul_f32_e32 v47, v159, v47
	v_cvt_pk_bf16_f32 v44, v44, v45
	v_cvt_pk_bf16_f32 v45, v46, v47
	ds_write_b64 v177, v[44:45] offset:112
	ds_read_b128 v[128:131], v179
	ds_read_b128 v[132:135], v179 offset:2176
	ds_read_b128 v[136:139], v179 offset:4352
	ds_read_b128 v[140:143], v179 offset:6528
	s_add_u32 s74, s68, 0x10000
	s_addc_u32 s75, s69, 0
	s_waitcnt lgkmcnt(3)
	global_store_dwordx4 v181, v[128:131], s[74:75]
	s_add_u32 s74, s68, 0x14000
	s_addc_u32 s75, s69, 0
	s_waitcnt lgkmcnt(2)
	global_store_dwordx4 v181, v[132:135], s[74:75]
	s_add_u32 s74, s68, 0x18000
	s_addc_u32 s75, s69, 0
	s_waitcnt lgkmcnt(1)
	global_store_dwordx4 v181, v[136:139], s[74:75]
	s_add_u32 s74, s68, 0x1c000
	s_addc_u32 s75, s69, 0
	s_waitcnt lgkmcnt(0)
	global_store_dwordx4 v181, v[140:143], s[74:75]
	s_add_u32 s74, s64, 0x20100
	s_addc_u32 s75, s65, 0
	global_load_dwordx4 v[128:131], v180, s[74:75]
	s_add_u32 s74, s64, 0x24100
	s_addc_u32 s75, s65, 0
	global_load_dwordx4 v[132:135], v180, s[74:75]
	s_add_u32 s74, s64, 0x28100
	s_addc_u32 s75, s65, 0
	global_load_dwordx4 v[136:139], v180, s[74:75]
	s_add_u32 s74, s64, 0x2c100
	s_addc_u32 s75, s65, 0
	global_load_dwordx4 v[140:143], v180, s[74:75]
	s_add_u32 s74, s64, 0x30100
	s_addc_u32 s75, s65, 0
	global_load_dwordx4 v[144:147], v180, s[74:75]
	s_add_u32 s74, s64, 0x34100
	s_addc_u32 s75, s65, 0
	global_load_dwordx4 v[148:151], v180, s[74:75]
	s_add_u32 s74, s64, 0x38100
	s_addc_u32 s75, s65, 0
	global_load_dwordx4 v[152:155], v180, s[74:75]
	s_add_u32 s74, s64, 0x3c100
	s_addc_u32 s75, s65, 0
	global_load_dwordx4 v[156:159], v180, s[74:75]
	s_waitcnt vmcnt(7)
	ds_write_b128 v178, v[128:131]
	s_waitcnt vmcnt(6)
	ds_write_b128 v178, v[132:135] offset:1088
	s_waitcnt vmcnt(5)
	ds_write_b128 v178, v[136:139] offset:2176
	s_waitcnt vmcnt(4)
	ds_write_b128 v178, v[140:143] offset:3264
	s_waitcnt vmcnt(3)
	ds_write_b128 v178, v[144:147] offset:4352
	s_waitcnt vmcnt(2)
	ds_write_b128 v178, v[148:151] offset:5440
	s_waitcnt vmcnt(1)
	ds_write_b128 v178, v[152:155] offset:6528
	s_waitcnt vmcnt(0)
	ds_write_b128 v178, v[156:159] offset:7616
	ds_read_b128 v[128:131], v176
	ds_read_b128 v[132:135], v176 offset:32
	ds_read_b128 v[136:139], v176 offset:64
	ds_read_b128 v[140:143], v176 offset:96
	ds_read_b128 v[144:147], v176 offset:128
	ds_read_b128 v[148:151], v176 offset:160
	ds_read_b128 v[152:155], v176 offset:192
	ds_read_b128 v[156:159], v176 offset:224
	s_waitcnt lgkmcnt(7)
	v_add_f32_e32 v16, v128, v16
	v_add_f32_e32 v17, v129, v17
	v_add_f32_e32 v18, v130, v18
	v_add_f32_e32 v19, v131, v19
	v_fmac_f32_e32 v184, v16, v16
	v_fmac_f32_e32 v184, v17, v17
	v_fmac_f32_e32 v184, v18, v18
	v_fmac_f32_e32 v184, v19, v19
	ds_write_b128 v176, v[16:19]
	s_waitcnt lgkmcnt(7)
	v_add_f32_e32 v20, v132, v20
	v_add_f32_e32 v21, v133, v21
	v_add_f32_e32 v22, v134, v22
	v_add_f32_e32 v23, v135, v23
	v_fmac_f32_e32 v184, v20, v20
	v_fmac_f32_e32 v184, v21, v21
	v_fmac_f32_e32 v184, v22, v22
	v_fmac_f32_e32 v184, v23, v23
	ds_write_b128 v176, v[20:23] offset:32
	s_waitcnt lgkmcnt(7)
	v_add_f32_e32 v24, v136, v24
	v_add_f32_e32 v25, v137, v25
	v_add_f32_e32 v26, v138, v26
	v_add_f32_e32 v27, v139, v27
	v_fmac_f32_e32 v184, v24, v24
	v_fmac_f32_e32 v184, v25, v25
	v_fmac_f32_e32 v184, v26, v26
	v_fmac_f32_e32 v184, v27, v27
	ds_write_b128 v176, v[24:27] offset:64
	s_waitcnt lgkmcnt(7)
	v_add_f32_e32 v28, v140, v28
	v_add_f32_e32 v29, v141, v29
	v_add_f32_e32 v30, v142, v30
	v_add_f32_e32 v31, v143, v31
	v_fmac_f32_e32 v184, v28, v28
	v_fmac_f32_e32 v184, v29, v29
	v_fmac_f32_e32 v184, v30, v30
	v_fmac_f32_e32 v184, v31, v31
	ds_write_b128 v176, v[28:31] offset:96
	s_waitcnt lgkmcnt(7)
	v_add_f32_e32 v0, v144, v0
	v_add_f32_e32 v1, v145, v1
	v_add_f32_e32 v2, v146, v2
	v_add_f32_e32 v3, v147, v3
	v_fmac_f32_e32 v184, v0, v0
	v_fmac_f32_e32 v184, v1, v1
	v_fmac_f32_e32 v184, v2, v2
	v_fmac_f32_e32 v184, v3, v3
	ds_write_b128 v176, v[0:3] offset:128
	s_waitcnt lgkmcnt(7)
	v_add_f32_e32 v4, v148, v4
	v_add_f32_e32 v5, v149, v5
	v_add_f32_e32 v6, v150, v6
	v_add_f32_e32 v7, v151, v7
	v_fmac_f32_e32 v184, v4, v4
	v_fmac_f32_e32 v184, v5, v5
	v_fmac_f32_e32 v184, v6, v6
	v_fmac_f32_e32 v184, v7, v7
	ds_write_b128 v176, v[4:7] offset:160
	s_waitcnt lgkmcnt(7)
	v_add_f32_e32 v8, v152, v8
	v_add_f32_e32 v9, v153, v9
	v_add_f32_e32 v10, v154, v10
	v_add_f32_e32 v11, v155, v11
	v_fmac_f32_e32 v184, v8, v8
	v_fmac_f32_e32 v184, v9, v9
	v_fmac_f32_e32 v184, v10, v10
	v_fmac_f32_e32 v184, v11, v11
	ds_write_b128 v176, v[8:11] offset:192
	s_waitcnt lgkmcnt(7)
; DI bfr f2bf(float a) { return (bfr)(pack2(a, 0.f) & 0xffffu); }
; DI int crow(int reg, int h) { return (reg & 3) + 8 * (reg >> 2) + 4 * h; }
; template <bool FIRST, bool HAS_H>
; DI void phase_gemm_resid(const Params& p, const bfr* A, const bfr* Wt, const float* gnext, float* ss, char* smem) {
;     ...
;         for (int jh = 0; jh < 2; ++jh) {
;           float xo[2][8];
; #pragma unroll
;           for (int jj = 0; jj < 2; ++jj)
; #pragma unroll
;             for (int q = 0; q < 8; ++q)
;               xo[jj][q] = xsrc[(rbase + i * 32 + crow(qh * 8 + q, 0)) * 1024 + cbase + (jh * 2 + jj) * 32];
; #pragma unroll
;           for (int q = 0; q < 8; ++q) {
;             const int o = (rbase + i * 32 + crow(qh * 8 + q, 0)) * 1024 + cbase;
; #pragma unroll
;             for (int jj = 0; jj < 2; ++jj) {
;               const int j = jh * 2 + jj;
;               const float xn = xo[jj][q] + acc[i][j][qh * 8 + q];
;               X[o + j * 32] = xn;
;               if (HAS_H) Hn[o + j * 32] = f2bf(xn * gnext[cbase + j * 32]);
;               rs[q] += xn * xn;
;             }
;           }
;         }
; #pragma unroll
;         for (int q = 0; q < 8; ++q) rs[q] = half32_sum_hi(rs[q]);
;         if (r == 31) {
; #pragma unroll
;           for (int q = 0; q < 8; ++q) unsafeAtomicAdd(ss + rbase + i * 32 + crow(qh * 8 + q, 0), rs[q]);
;         }
	v_add_f32_e32 v12, v156, v12
	v_add_f32_e32 v13, v157, v13
	v_add_f32_e32 v14, v158, v14
	v_add_f32_e32 v15, v159, v15
	v_fmac_f32_e32 v184, v12, v12
	v_fmac_f32_e32 v184, v13, v13
	v_fmac_f32_e32 v184, v14, v14
	v_fmac_f32_e32 v184, v15, v15
	ds_write_b128 v176, v[12:15] offset:224
	ds_read_b128 v[128:131], v178
	ds_read_b128 v[132:135], v178 offset:1088
	ds_read_b128 v[136:139], v178 offset:2176
	ds_read_b128 v[140:143], v178 offset:3264
	ds_read_b128 v[144:147], v178 offset:4352
	ds_read_b128 v[148:151], v178 offset:5440
	ds_read_b128 v[152:155], v178 offset:6528
	ds_read_b128 v[156:159], v178 offset:7616
	s_add_u32 s74, s66, 0x20100
	s_addc_u32 s75, s67, 0
	s_waitcnt lgkmcnt(7)
	global_store_dwordx4 v180, v[128:131], s[74:75]
	s_add_u32 s74, s66, 0x24100
	s_addc_u32 s75, s67, 0
	s_waitcnt lgkmcnt(6)
	global_store_dwordx4 v180, v[132:135], s[74:75]
	s_add_u32 s74, s66, 0x28100
	s_addc_u32 s75, s67, 0
	s_waitcnt lgkmcnt(5)
	global_store_dwordx4 v180, v[136:139], s[74:75]
	s_add_u32 s74, s66, 0x2c100
	s_addc_u32 s75, s67, 0
	s_waitcnt lgkmcnt(4)
	global_store_dwordx4 v180, v[140:143], s[74:75]
	s_add_u32 s74, s66, 0x30100
	s_addc_u32 s75, s67, 0
	s_waitcnt lgkmcnt(3)
	global_store_dwordx4 v180, v[144:147], s[74:75]
	s_add_u32 s74, s66, 0x34100
	s_addc_u32 s75, s67, 0
	s_waitcnt lgkmcnt(2)
	global_store_dwordx4 v180, v[148:151], s[74:75]
	s_add_u32 s74, s66, 0x38100
	s_addc_u32 s75, s67, 0
	s_waitcnt lgkmcnt(1)
	global_store_dwordx4 v180, v[152:155], s[74:75]
	s_add_u32 s74, s66, 0x3c100
	s_addc_u32 s75, s67, 0
	s_waitcnt lgkmcnt(0)
	global_store_dwordx4 v180, v[156:159], s[74:75]
	global_load_dwordx4 v[128:131], v182, s[70:71] offset:256
	global_load_dwordx4 v[132:135], v182, s[70:71] offset:288
	global_load_dwordx4 v[136:139], v182, s[70:71] offset:320
	global_load_dwordx4 v[140:143], v182, s[70:71] offset:352
	global_load_dwordx4 v[144:147], v182, s[70:71] offset:384
	global_load_dwordx4 v[148:151], v182, s[70:71] offset:416
	global_load_dwordx4 v[152:155], v182, s[70:71] offset:448
	global_load_dwordx4 v[156:159], v182, s[70:71] offset:480
	s_waitcnt vmcnt(7)
	v_mul_f32_e32 v16, v128, v16
	v_mul_f32_e32 v17, v129, v17
	v_mul_f32_e32 v18, v130, v18
	v_mul_f32_e32 v19, v131, v19
	v_cvt_pk_bf16_f32 v16, v16, v17
	v_cvt_pk_bf16_f32 v17, v18, v19
	ds_write_b64 v177, v[16:17]
	s_waitcnt vmcnt(6)
	v_mul_f32_e32 v20, v132, v20
	v_mul_f32_e32 v21, v133, v21
	v_mul_f32_e32 v22, v134, v22
	v_mul_f32_e32 v23, v135, v23
	v_cvt_pk_bf16_f32 v20, v20, v21
	v_cvt_pk_bf16_f32 v21, v22, v23
	ds_write_b64 v177, v[20:21] offset:16
	s_waitcnt vmcnt(5)
	v_mul_f32_e32 v24, v136, v24
	v_mul_f32_e32 v25, v137, v25
	v_mul_f32_e32 v26, v138, v26
	v_mul_f32_e32 v27, v139, v27
	v_cvt_pk_bf16_f32 v24, v24, v25
	v_cvt_pk_bf16_f32 v25, v26, v27
	ds_write_b64 v177, v[24:25] offset:32
	s_waitcnt vmcnt(4)
	v_mul_f32_e32 v28, v140, v28
	v_mul_f32_e32 v29, v141, v29
	v_mul_f32_e32 v30, v142, v30
	v_mul_f32_e32 v31, v143, v31
	v_cvt_pk_bf16_f32 v28, v28, v29
	v_cvt_pk_bf16_f32 v29, v30, v31
	ds_write_b64 v177, v[28:29] offset:48
	s_waitcnt vmcnt(3)
	v_mul_f32_e32 v0, v144, v0
	v_mul_f32_e32 v1, v145, v1
	v_mul_f32_e32 v2, v146, v2
	v_mul_f32_e32 v3, v147, v3
	v_cvt_pk_bf16_f32 v0, v0, v1
	v_cvt_pk_bf16_f32 v1, v2, v3
	ds_write_b64 v177, v[0:1] offset:64
	s_waitcnt vmcnt(2)
	v_mul_f32_e32 v4, v148, v4
	v_mul_f32_e32 v5, v149, v5
	v_mul_f32_e32 v6, v150, v6
	v_mul_f32_e32 v7, v151, v7
	v_cvt_pk_bf16_f32 v4, v4, v5
	v_cvt_pk_bf16_f32 v5, v6, v7
	ds_write_b64 v177, v[4:5] offset:80
	s_waitcnt vmcnt(1)
	v_mul_f32_e32 v8, v152, v8
	v_mul_f32_e32 v9, v153, v9
	v_mul_f32_e32 v10, v154, v10
	v_mul_f32_e32 v11, v155, v11
	v_cvt_pk_bf16_f32 v8, v8, v9
	v_cvt_pk_bf16_f32 v9, v10, v11
	ds_write_b64 v177, v[8:9] offset:96
	s_waitcnt vmcnt(0)
	v_mul_f32_e32 v12, v156, v12
	v_mul_f32_e32 v13, v157, v13
	v_mul_f32_e32 v14, v158, v14
	v_mul_f32_e32 v15, v159, v15
	v_cvt_pk_bf16_f32 v12, v12, v13
	v_cvt_pk_bf16_f32 v13, v14, v15
	ds_write_b64 v177, v[12:13] offset:112
	ds_read_b128 v[128:131], v179
	ds_read_b128 v[132:135], v179 offset:2176
	ds_read_b128 v[136:139], v179 offset:4352
	ds_read_b128 v[140:143], v179 offset:6528
	s_add_u32 s74, s68, 0x10080
	s_addc_u32 s75, s69, 0
	s_waitcnt lgkmcnt(3)
	global_store_dwordx4 v181, v[128:131], s[74:75]
	s_add_u32 s74, s68, 0x14080
	s_addc_u32 s75, s69, 0
	s_waitcnt lgkmcnt(2)
	global_store_dwordx4 v181, v[132:135], s[74:75]
	s_add_u32 s74, s68, 0x18080
	s_addc_u32 s75, s69, 0
	s_waitcnt lgkmcnt(1)
	global_store_dwordx4 v181, v[136:139], s[74:75]
	s_add_u32 s74, s68, 0x1c080
	s_addc_u32 s75, s69, 0
	s_waitcnt lgkmcnt(0)
	global_store_dwordx4 v181, v[140:143], s[74:75]
	s_load_dwordx2 s[64:65], s[92:93], 0x140
	ds_bpermute_b32 v188, v186, v183
	ds_bpermute_b32 v190, v186, v184
	s_waitcnt lgkmcnt(0)
	v_add_f32_e32 v188, v188, v183
	v_add_f32_e32 v190, v190, v184
	s_mov_b32 exec_hi, 0
	s_nop 1
	global_atomic_add_f32 v185, v188, s[64:65]
	global_atomic_add_f32 v185, v190, s[64:65] offset:128
	s_mov_b64 exec, -1
	v_readlane_b32 s64, v187, 0
	v_readlane_b32 s65, v187, 1
	v_readlane_b32 s66, v187, 2
	v_readlane_b32 s67, v187, 3
	v_readlane_b32 s68, v187, 4
	v_readlane_b32 s69, v187, 5
	v_readlane_b32 s70, v187, 6
	v_readlane_b32 s71, v187, 7
	v_readlane_b32 s72, v187, 8
	v_readlane_b32 s73, v187, 9
	v_readlane_b32 s74, v187, 10
	v_readlane_b32 s75, v187, 11
	v_readlane_b32 s76, v187, 12
	v_readlane_b32 s77, v187, 13
	v_readlane_b32 s78, v187, 14
	v_readlane_b32 s79, v187, 15
	s_nop 7
	s_branch .LBB0_840

; #define GA_LOAD(pr_) do { _Pragma("unroll") for (int i = 0; i < 4; ++i) ra[i] = *(const u32x4*)(Ab + (i * 32) * lda + (pr_) * 64); } while (0)
; #define GB_LOAD(kt_) do { const bfr* bk_ = Bb + (kt_) * NB * 32; \
;     _Pragma("unroll") for (int i = 0; i < 4; ++i) rb[i] = *(const u32x4*)(bk_ + (i * 64) * 32); } while (0)
; #define G_STORE(kt_) do { bfr* as_ = S0 + ((kt_) & 1) * GSTAGE; bfr* bs_ = as_ + 128 * 40; \
;     if (apar == ((kt_) & 1)) { _Pragma("unroll") for (int i = 0; i < 4; ++i) *(u32x4*)(as_ + asoff + i * 32 * 40) = ra[i]; } \
;     _Pragma("unroll") for (int i = 0; i < 4; ++i) *(u32x4*)(bs_ + bsoff + i * 64 * 40) = rb[i]; } while (0)
; template <int lda>
; DI void gemm_mainloop(const bfr* __restrict__ A, const bfr* __restrict__ Bt, int NB, int K, int m0, int n0, char* smem, f32x16 (&acc)[2][4]) {
;     ...
;   const int nk = K >> 5;
;   const int arow = tid >> 3, ac8 = tid & 7, apar = ac8 >> 2;
;   const bfr* Ab = A + (m0 + arow) * lda + ac8 * 8;
;   const int asoff = arow * 40 + (ac8 & 3) * 8;
;   const int brow = tid >> 2, bc4 = tid & 3;
;   const bfr* Bb = Bt + (n0 + brow) * 32 + bc4 * 8;
;   const int bsoff = brow * 40 + bc4 * 8;
;     ...
;   GA_LOAD(0);
;   GB_LOAD(0);
;   G_STORE(0);
;   GB_LOAD(1);
;   __syncthreads();
; template <bool FIRST, bool HAS_H>
; DI void phase_gemm_resid(const Params& p, const bfr* A, const bfr* Wt, const float* gnext, float* ss, char* smem) {
;     ...
;   for (int t0 = blockIdx.x; t0 < 128 * 4; t0 += gridDim.x) {
;     const int t = ((gridDim.x & 7) == 0) ? xcd_tile(t0, 4) : t0;
;     const int mt = t >> 2, nt = t & 3, m0 = mt * 128, n0 = nt * 256;
;     f32x16 acc[2][4];
;     gemm_mainloop<1024>(A, Wt, 1024, 1024, m0, n0, smem, acc);
.LBB0_1099:
	s_lshl_b32 s5, s4, 5
	s_and_b32 s36, s5, 0xffffff80
	s_lshl_b32 s4, s4, 8
	s_and_b32 s33, s4, 0x300
	s_mov_b32 s37, 0
	s_mov_b64 s[20:21], 0
	s_lshl_b32 s98, s36, 11
	s_add_u32 s98, s2, s98
	s_addc_u32 s99, s3, 0
	s_lshl_b32 s100, s33, 6
	s_add_u32 s100, s8, s100
	s_addc_u32 s101, s9, 0
	v_writelane_b32 v187, s64, 0
	v_writelane_b32 v187, s65, 1
	v_writelane_b32 v187, s66, 2
	v_writelane_b32 v187, s67, 3
	v_writelane_b32 v187, s68, 4
	v_writelane_b32 v187, s69, 5
	v_writelane_b32 v187, s70, 6
	v_writelane_b32 v187, s71, 7
	v_writelane_b32 v187, s72, 8
	v_writelane_b32 v187, s73, 9
	v_writelane_b32 v187, s74, 10
	v_writelane_b32 v187, s75, 11
	v_writelane_b32 v187, s76, 12
	v_writelane_b32 v187, s77, 13
	v_writelane_b32 v187, s78, 14
	v_writelane_b32 v187, s79, 15
	s_mov_b32 s77, s36
	s_mov_b32 s78, s33
	v_lshrrev_b32_e32 v188, 6, v196
	v_and_b32_e32 v189, 63, v196
	v_readfirstlane_b32 s73, v188
	v_lshrrev_b32_e32 v190, 2, v189
	v_bfe_u32 v191, v189, 4, 2
	v_and_b32_e32 v188, 3, v189
	v_xor_b32_e32 v188, v188, v191
	v_lshlrev_b32_e32 v188, 4, v188
	v_lshl_add_u32 v176, v190, 11, v188
	v_add_u32_e32 v177, 0x8000, v176
	v_lshl_add_u32 v178, v190, 6, v188
	v_and_b32_e32 v190, 31, v189
	v_lshrrev_b32_e32 v191, 5, v189
	v_bfe_u32 v188, v189, 2, 2
	v_xor_b32_e32 v188, v188, v191
	v_lshlrev_b32_e32 v188, 4, v188
	v_lshl_add_u32 v179, v190, 6, v188
	s_lshr_b32 s74, s73, 1
	s_lshl_b32 s74, s74, 12
	s_and_b32 s75, s73, 1
	s_lshl_b32 s75, s75, 13
	v_add_u32_e32 v181, s75, v179
	v_add_u32_e32 v179, s74, v179
	v_xor_b32_e32 v182, 32, v181
	v_xor_b32_e32 v180, 32, v179
	s_lshl_b32 s74, s73, 16
	s_add_u32 s64, s98, s74
	s_addc_u32 s65, s99, 0
	s_lshl_b32 s74, s73, 12
	s_add_u32 s66, s100, s74
	s_addc_u32 s67, s101, 0
	s_lshl_b32 s68, s73, 11
	s_lshl_b32 s69, s73, 12
	s_mov_b32 s70, 0
	s_mov_b32 s71, 0
	s_mov_b32 s72, 0
	s_waitcnt lgkmcnt(0)
	s_barrier
	s_mul_i32 s74, s70, 0x6000
	s_add_u32 s75, s74, s68
	s_mov_b32 m0, s75
	s_add_u32 s76, s74, 0x2000
	s_cmp_eq_u32 s70, 2
	s_cselect_b32 s76, 0x10000, s76
	global_load_lds_dwordx4 v176, s[64:65]
	s_add_u32 m0, s75, 0x400
	s_add_u32 s76, s76, s69
	global_load_lds_dwordx4 v177, s[64:65]
	s_mov_b32 m0, s76
	s_add_u32 s64, s64, 64
	s_addc_u32 s65, s65, 0
	global_load_lds_dwordx4 v178, s[66:67]
	global_load_lds_dwordx4 v178, s[66:67] offset:1024
	global_load_lds_dwordx4 v178, s[66:67] offset:2048
	global_load_lds_dwordx4 v178, s[66:67] offset:3072
	s_add_u32 s66, s66, 0x10000
	s_addc_u32 s67, s67, 0
	s_add_u32 s70, s70, 1
	s_cmp_eq_u32 s70, 3
	s_cselect_b32 s70, 0, s70
	s_mul_i32 s74, s70, 0x6000
	s_add_u32 s75, s74, s68
	s_mov_b32 m0, s75
	s_add_u32 s76, s74, 0x2000
	s_cmp_eq_u32 s70, 2
	s_cselect_b32 s76, 0x10000, s76
	global_load_lds_dwordx4 v176, s[64:65]
	s_add_u32 m0, s75, 0x400
	s_add_u32 s76, s76, s69
	global_load_lds_dwordx4 v177, s[64:65]
	s_mov_b32 m0, s76
	s_add_u32 s64, s64, 64
	s_addc_u32 s65, s65, 0
	global_load_lds_dwordx4 v178, s[66:67]
	global_load_lds_dwordx4 v178, s[66:67] offset:1024
	global_load_lds_dwordx4 v178, s[66:67] offset:2048
	global_load_lds_dwordx4 v178, s[66:67] offset:3072
	s_add_u32 s66, s66, 0x10000
	s_addc_u32 s67, s67, 0
	s_add_u32 s70, s70, 1
	s_cmp_eq_u32 s70, 3
	s_cselect_b32 s70, 0, s70
	s_cmp_lt_u32 s46, 0x100
	s_cbranch_scc1 .Lp10_nostag
	s_sleep 8

; #define MFMA32(a, b, c) __builtin_amdgcn_mfma_f32_32x32x16_bf16((a), (b), (c), 0, 0, 0)
; #define GA_LOAD(pr_) do { _Pragma("unroll") for (int i = 0; i < 4; ++i) ra[i] = *(const u32x4*)(Ab + (i * 32) * lda + (pr_) * 64); } while (0)
; #define GB_LOAD(kt_) do { const bfr* bk_ = Bb + (kt_) * NB * 32; \
;     _Pragma("unroll") for (int i = 0; i < 4; ++i) rb[i] = *(const u32x4*)(bk_ + (i * 64) * 32); } while (0)
; #define G_STORE(kt_) do { bfr* as_ = S0 + ((kt_) & 1) * GSTAGE; bfr* bs_ = as_ + 128 * 40; \
;     if (apar == ((kt_) & 1)) { _Pragma("unroll") for (int i = 0; i < 4; ++i) *(u32x4*)(as_ + asoff + i * 32 * 40) = ra[i]; } \
;     _Pragma("unroll") for (int i = 0; i < 4; ++i) *(u32x4*)(bs_ + bsoff + i * 64 * 40) = rb[i]; } while (0)
; template <int lda>
; DI void gemm_mainloop(const bfr* __restrict__ A, const bfr* __restrict__ Bt, int NB, int K, int m0, int n0, char* smem, f32x16 (&acc)[2][4]) {
;     ...
;   for (int kt = 0; kt < nk; ++kt) {
;     if (kt + 1 < nk) G_STORE(kt + 1);
;     if (kt + 2 < nk) {
;       GB_LOAD(kt + 2);
;       if ((kt & 1) == 0) GA_LOAD((kt >> 1) + 1);
;     }
;     const bfr* As = S0 + (kt & 1) * GSTAGE;
;     const bfr* Bs = As + 128 * 40;
; #pragma unroll
;     for (int ks = 0; ks < 2; ++ks) {
;       bf16x8 af[2], bfg[4];
; #pragma unroll
;       for (int i = 0; i < 2; ++i) af[i] = *(const bf16x8*)(As + (wr * 64 + i * 32 + r) * 40 + ks * 16 + hl * 8);
; #pragma unroll
;       for (int j = 0; j < 4; ++j) bfg[j] = *(const bf16x8*)(Bs + (wc * 128 + j * 32 + r) * 40 + ks * 16 + hl * 8);
; #pragma unroll
;       for (int i = 0; i < 2; ++i)
; #pragma unroll
;         for (int j = 0; j < 4; ++j) acc[i][j] = MFMA32(af[i], bfg[j], acc[i][j]);
;     }
;     __syncthreads();
;   }
.Lp10_loop:
	s_waitcnt vmcnt(6)
	s_barrier
	s_mul_i32 s74, s71, 0x6000
	s_add_u32 s75, s74, 0x2000
	s_cmp_eq_u32 s71, 2
	s_cselect_b32 s75, 0x10000, s75
	v_add_u32_e32 v183, s74, v179
	v_add_u32_e32 v185, s75, v181
	v_add_u32_e32 v184, s74, v180
	v_add_u32_e32 v186, s75, v182
	ds_read_b128 v[128:131], v183
	ds_read_b128 v[144:147], v185
	ds_read_b128 v[148:151], v185 offset:2048
	ds_read_b128 v[152:155], v185 offset:4096
	ds_read_b128 v[156:159], v185 offset:6144
	ds_read_b128 v[132:135], v183 offset:2048
	ds_read_b128 v[136:139], v184
	ds_read_b128 v[160:163], v186
	ds_read_b128 v[164:167], v186 offset:2048
	ds_read_b128 v[168:171], v186 offset:4096
	ds_read_b128 v[172:175], v186 offset:6144
	ds_read_b128 v[140:143], v184 offset:2048
	s_add_u32 s71, s71, 1
	s_cmp_eq_u32 s71, 3
	s_cselect_b32 s71, 0, s71
	s_waitcnt lgkmcnt(10)
	v_mfma_f32_32x32x16_bf16 v[112:127], v[144:147], v[128:131], v[112:127]
	s_mul_i32 s74, s70, 0x6000
	s_add_u32 s75, s74, s68
	s_mov_b32 m0, s75
	s_add_u32 s76, s74, 0x2000
	s_cmp_eq_u32 s70, 2
	s_cselect_b32 s76, 0x10000, s76
	global_load_lds_dwordx4 v176, s[64:65]
	s_waitcnt lgkmcnt(9)
	v_mfma_f32_32x32x16_bf16 v[96:111], v[148:151], v[128:131], v[96:111]
	s_add_u32 m0, s75, 0x400
	s_add_u32 s76, s76, s69
	global_load_lds_dwordx4 v177, s[64:65]
	s_waitcnt lgkmcnt(8)
	v_mfma_f32_32x32x16_bf16 v[80:95], v[152:155], v[128:131], v[80:95]
	s_mov_b32 m0, s76
	s_add_u32 s64, s64, 64
	s_addc_u32 s65, s65, 0
	global_load_lds_dwordx4 v178, s[66:67]
	s_waitcnt lgkmcnt(7)
	v_mfma_f32_32x32x16_bf16 v[64:79], v[156:159], v[128:131], v[64:79]
	global_load_lds_dwordx4 v178, s[66:67] offset:1024
	s_waitcnt lgkmcnt(6)
	v_mfma_f32_32x32x16_bf16 v[48:63], v[144:147], v[132:135], v[48:63]
	global_load_lds_dwordx4 v178, s[66:67] offset:2048
	v_mfma_f32_32x32x16_bf16 v[32:47], v[148:151], v[132:135], v[32:47]
	global_load_lds_dwordx4 v178, s[66:67] offset:3072
	s_add_u32 s66, s66, 0x10000
	s_addc_u32 s67, s67, 0
	v_mfma_f32_32x32x16_bf16 v[16:31], v[152:155], v[132:135], v[16:31]
	s_add_u32 s70, s70, 1
	s_cmp_eq_u32 s70, 3
	s_cselect_b32 s70, 0, s70
	v_mfma_f32_32x32x16_bf16 v[0:15], v[156:159], v[132:135], v[0:15]
	s_waitcnt lgkmcnt(4)
	v_mfma_f32_32x32x16_bf16 v[112:127], v[160:163], v[136:139], v[112:127]
	s_waitcnt lgkmcnt(3)
	v_mfma_f32_32x32x16_bf16 v[96:111], v[164:167], v[136:139], v[96:111]
	s_waitcnt lgkmcnt(2)
	v_mfma_f32_32x32x16_bf16 v[80:95], v[168:171], v[136:139], v[80:95]
	s_waitcnt lgkmcnt(1)
	v_mfma_f32_32x32x16_bf16 v[64:79], v[172:175], v[136:139], v[64:79]
	s_waitcnt lgkmcnt(0)
	v_mfma_f32_32x32x16_bf16 v[48:63], v[160:163], v[140:143], v[48:63]
	v_mfma_f32_32x32x16_bf16 v[32:47], v[164:167], v[140:143], v[32:47]
	v_mfma_f32_32x32x16_bf16 v[16:31], v[168:171], v[140:143], v[16:31]
	v_mfma_f32_32x32x16_bf16 v[0:15], v[172:175], v[140:143], v[0:15]
	s_add_u32 s72, s72, 1
	s_cmp_lt_u32 s72, 30
	s_cbranch_scc1 .Lp10_loop
	s_waitcnt vmcnt(6)
	s_barrier
	s_mul_i32 s74, s71, 0x6000
	s_add_u32 s75, s74, 0x2000
	s_cmp_eq_u32 s71, 2
	s_cselect_b32 s75, 0x10000, s75
	v_add_u32_e32 v183, s74, v179
	v_add_u32_e32 v185, s75, v181
	v_add_u32_e32 v184, s74, v180
	v_add_u32_e32 v186, s75, v182
	ds_read_b128 v[128:131], v183
	ds_read_b128 v[144:147], v185
	ds_read_b128 v[148:151], v185 offset:2048
	ds_read_b128 v[152:155], v185 offset:4096
	ds_read_b128 v[156:159], v185 offset:6144
	ds_read_b128 v[132:135], v183 offset:2048
	ds_read_b128 v[136:139], v184
	ds_read_b128 v[160:163], v186
	ds_read_b128 v[164:167], v186 offset:2048
	ds_read_b128 v[168:171], v186 offset:4096
	ds_read_b128 v[172:175], v186 offset:6144
	ds_read_b128 v[140:143], v184 offset:2048
	s_add_u32 s71, s71, 1
	s_cmp_eq_u32 s71, 3
	s_cselect_b32 s71, 0, s71
	s_waitcnt lgkmcnt(10)
	v_mfma_f32_32x32x16_bf16 v[112:127], v[144:147], v[128:131], v[112:127]
	s_waitcnt lgkmcnt(9)
	v_mfma_f32_32x32x16_bf16 v[96:111], v[148:151], v[128:131], v[96:111]
	s_waitcnt lgkmcnt(8)
	v_mfma_f32_32x32x16_bf16 v[80:95], v[152:155], v[128:131], v[80:95]
	s_waitcnt lgkmcnt(7)
	v_mfma_f32_32x32x16_bf16 v[64:79], v[156:159], v[128:131], v[64:79]
	s_waitcnt lgkmcnt(6)
	v_mfma_f32_32x32x16_bf16 v[48:63], v[144:147], v[132:135], v[48:63]
	v_mfma_f32_32x32x16_bf16 v[32:47], v[148:151], v[132:135], v[32:47]
	v_mfma_f32_32x32x16_bf16 v[16:31], v[152:155], v[132:135], v[16:31]
	v_mfma_f32_32x32x16_bf16 v[0:15], v[156:159], v[132:135], v[0:15]
	s_waitcnt lgkmcnt(4)
	v_mfma_f32_32x32x16_bf16 v[112:127], v[160:163], v[136:139], v[112:127]
	s_waitcnt lgkmcnt(3)
	v_mfma_f32_32x32x16_bf16 v[96:111], v[164:167], v[136:139], v[96:111]
	s_waitcnt lgkmcnt(2)
	v_mfma_f32_32x32x16_bf16 v[80:95], v[168:171], v[136:139], v[80:95]
	s_waitcnt lgkmcnt(1)
	v_mfma_f32_32x32x16_bf16 v[64:79], v[172:175], v[136:139], v[64:79]
	s_waitcnt lgkmcnt(0)
	v_mfma_f32_32x32x16_bf16 v[48:63], v[160:163], v[140:143], v[48:63]
	v_mfma_f32_32x32x16_bf16 v[32:47], v[164:167], v[140:143], v[32:47]
	v_mfma_f32_32x32x16_bf16 v[16:31], v[168:171], v[140:143], v[16:31]
	v_mfma_f32_32x32x16_bf16 v[0:15], v[172:175], v[140:143], v[0:15]
	s_waitcnt vmcnt(0)
	s_barrier
; #define MFMA32(a, b, c) __builtin_amdgcn_mfma_f32_32x32x16_bf16((a), (b), (c), 0, 0, 0)
; DI int crow(int reg, int h) { return (reg & 3) + 8 * (reg >> 2) + 4 * h; }
; template <int lda>
; DI void gemm_mainloop(const bfr* __restrict__ A, const bfr* __restrict__ Bt, int NB, int K, int m0, int n0, char* smem, f32x16 (&acc)[2][4]) {
;     ...
;     const bfr* As = S0 + (kt & 1) * GSTAGE;
;     const bfr* Bs = As + 128 * 40;
; #pragma unroll
;     for (int ks = 0; ks < 2; ++ks) {
;       bf16x8 af[2], bfg[4];
; #pragma unroll
;       for (int i = 0; i < 2; ++i) af[i] = *(const bf16x8*)(As + (wr * 64 + i * 32 + r) * 40 + ks * 16 + hl * 8);
; #pragma unroll
;       for (int j = 0; j < 4; ++j) bfg[j] = *(const bf16x8*)(Bs + (wc * 128 + j * 32 + r) * 40 + ks * 16 + hl * 8);
; #pragma unroll
;       for (int i = 0; i < 2; ++i)
; #pragma unroll
;         for (int j = 0; j < 4; ++j) acc[i][j] = MFMA32(af[i], bfg[j], acc[i][j]);
;     }
; template <bool FIRST, bool HAS_H>
; DI void phase_gemm_resid(const Params& p, const bfr* A, const bfr* Wt, const float* gnext, float* ss, char* smem) {
;     ...
;     int tid2 = threadIdx.x;
;     asm volatile("" : "+v"(tid2));
;     const int lane = tid2 & 63, wid = tid2 >> 6, wr = wid >> 1, wc = wid & 1, r = lane & 31, hl = lane >> 5;
;     const float* xsrc = FIRST ? p.x_prompt : X;
;     const int rbase = m0 + wr * 64 + 4 * hl, cbase = n0 + wc * 128 + r;
; #pragma unroll
;     for (int i = 0; i < 2; ++i) {
; #pragma unroll
;       for (int qh = 0; qh < 2; ++qh) {
;         float rs[8];
; #pragma unroll
;         for (int q = 0; q < 8; ++q) rs[q] = 0.f;
; #pragma unroll
;         for (int jh = 0; jh < 2; ++jh) {
;           float xo[2][8];
; #pragma unroll
;           for (int jj = 0; jj < 2; ++jj)
; #pragma unroll
;             for (int q = 0; q < 8; ++q)
;               xo[jj][q] = xsrc[(rbase + i * 32 + crow(qh * 8 + q, 0)) * 1024 + cbase + (jh * 2 + jj) * 32];
	s_mul_i32 s74, s71, 0x6000
	s_add_u32 s75, s74, 0x2000
	s_cmp_eq_u32 s71, 2
	s_cselect_b32 s75, 0x10000, s75
	v_add_u32_e32 v183, s74, v179
	v_add_u32_e32 v185, s75, v181
	v_add_u32_e32 v184, s74, v180
	v_add_u32_e32 v186, s75, v182
	ds_read_b128 v[128:131], v183
	ds_read_b128 v[144:147], v185
	ds_read_b128 v[148:151], v185 offset:2048
	ds_read_b128 v[152:155], v185 offset:4096
	ds_read_b128 v[156:159], v185 offset:6144
	ds_read_b128 v[132:135], v183 offset:2048
	ds_read_b128 v[136:139], v184
	ds_read_b128 v[160:163], v186
	ds_read_b128 v[164:167], v186 offset:2048
	ds_read_b128 v[168:171], v186 offset:4096
	ds_read_b128 v[172:175], v186 offset:6144
	ds_read_b128 v[140:143], v184 offset:2048
	s_add_u32 s71, s71, 1
	s_cmp_eq_u32 s71, 3
	s_cselect_b32 s71, 0, s71
	s_waitcnt lgkmcnt(10)
	v_mfma_f32_32x32x16_bf16 v[112:127], v[144:147], v[128:131], v[112:127]
	s_waitcnt lgkmcnt(9)
	v_mfma_f32_32x32x16_bf16 v[96:111], v[148:151], v[128:131], v[96:111]
	s_waitcnt lgkmcnt(8)
	v_mfma_f32_32x32x16_bf16 v[80:95], v[152:155], v[128:131], v[80:95]
	s_waitcnt lgkmcnt(7)
	v_mfma_f32_32x32x16_bf16 v[64:79], v[156:159], v[128:131], v[64:79]
	s_waitcnt lgkmcnt(6)
	v_mfma_f32_32x32x16_bf16 v[48:63], v[144:147], v[132:135], v[48:63]
	v_mfma_f32_32x32x16_bf16 v[32:47], v[148:151], v[132:135], v[32:47]
	v_mfma_f32_32x32x16_bf16 v[16:31], v[152:155], v[132:135], v[16:31]
	v_mfma_f32_32x32x16_bf16 v[0:15], v[156:159], v[132:135], v[0:15]
	s_waitcnt lgkmcnt(4)
	v_mfma_f32_32x32x16_bf16 v[112:127], v[160:163], v[136:139], v[112:127]
	s_waitcnt lgkmcnt(3)
	v_mfma_f32_32x32x16_bf16 v[96:111], v[164:167], v[136:139], v[96:111]
	s_waitcnt lgkmcnt(2)
	v_mfma_f32_32x32x16_bf16 v[80:95], v[168:171], v[136:139], v[80:95]
	s_waitcnt lgkmcnt(1)
	v_mfma_f32_32x32x16_bf16 v[64:79], v[172:175], v[136:139], v[64:79]
	s_waitcnt lgkmcnt(0)
	v_mfma_f32_32x32x16_bf16 v[48:63], v[160:163], v[140:143], v[48:63]
	v_mfma_f32_32x32x16_bf16 v[32:47], v[164:167], v[140:143], v[32:47]
	v_mfma_f32_32x32x16_bf16 v[16:31], v[168:171], v[140:143], v[16:31]
	v_mfma_f32_32x32x16_bf16 v[0:15], v[172:175], v[140:143], v[0:15]
	s_nop 7
	s_nop 3
	s_barrier
	s_load_dwordx2 s[64:65], s[92:93], 0x100
	s_load_dwordx2 s[66:67], s[92:93], 0x100
	s_load_dwordx2 s[68:69], s[92:93], 0x148
	s_load_dwordx2 s[70:71], s[92:93], 0x48
	s_mul_i32 s76, s73, 8704
	s_lshr_b32 s74, s73, 1
	s_lshl_b32 s74, s74, 6
	s_add_u32 s74, s74, s77
	s_and_b32 s75, s73, 1
	s_lshl_b32 s75, s75, 7
	s_add_u32 s75, s75, s78
	v_and_b32_e32 v188, 31, v196
	v_bfe_u32 v189, v196, 5, 1
	v_mul_u32_u24_e32 v190, 272, v188
	v_add_u32_e32 v190, s76, v190
	v_lshl_add_u32 v176, v189, 4, v190
	v_lshl_add_u32 v177, v189, 3, v190
	v_lshlrev_b32_e32 v190, 2, v189
	v_add_lshl_u32 v182, v190, s75, 2
	v_add_lshl_u32 v185, v188, s74, 2
	v_and_b32_e32 v190, 63, v196
	v_xor_b32_e32 v190, 32, v190
	v_lshlrev_b32_e32 v186, 2, v190
	v_bfe_u32 v188, v196, 4, 2
	v_and_b32_e32 v189, 15, v196
	v_mul_u32_u24_e32 v190, 272, v188
	v_lshl_add_u32 v190, v189, 4, v190
	v_add_u32_e32 v178, s76, v190
	v_add_u32_e32 v190, s74, v188
	v_lshlrev_b32_e32 v190, 10, v190
	v_lshl_add_u32 v190, v189, 2, v190
	v_add_lshl_u32 v180, v190, s75, 2
	v_bfe_u32 v188, v196, 3, 3
	v_and_b32_e32 v189, 7, v196
	v_mul_u32_u24_e32 v190, 272, v188
	v_lshl_add_u32 v190, v189, 4, v190
	v_add_u32_e32 v179, s76, v190
	v_add_u32_e32 v190, s74, v188
	v_lshlrev_b32_e32 v190, 10, v190
	v_lshl_add_u32 v190, v189, 3, v190
	v_add_lshl_u32 v181, v190, s75, 1
	v_mov_b32_e32 v183, 0
	v_mov_b32_e32 v184, 0
	s_waitcnt lgkmcnt(0)
	s_add_u32 s70, s70, 0x1000
	s_addc_u32 s71, s71, 0
	s_add_u32 s74, s64, 0x0
	s_addc_u32 s75, s65, 0
	global_load_dwordx4 v[128:131], v180, s[74:75]
	s_add_u32 s74, s64, 0x4000
	s_addc_u32 s75, s65, 0
	global_load_dwordx4 v[132:135], v180, s[74:75]
	s_add_u32 s74, s64, 0x8000
	s_addc_u32 s75, s65, 0
	global_load_dwordx4 v[136:139], v180, s[74:75]
	s_add_u32 s74, s64, 0xc000
	s_addc_u32 s75, s65, 0
	global_load_dwordx4 v[140:143], v180, s[74:75]
	s_add_u32 s74, s64, 0x10000
	s_addc_u32 s75, s65, 0
	global_load_dwordx4 v[144:147], v180, s[74:75]
	s_add_u32 s74, s64, 0x14000
	s_addc_u32 s75, s65, 0
	global_load_dwordx4 v[148:151], v180, s[74:75]
	s_add_u32 s74, s64, 0x18000
	s_addc_u32 s75, s65, 0
	global_load_dwordx4 v[152:155], v180, s[74:75]
	s_add_u32 s74, s64, 0x1c000
	s_addc_u32 s75, s65, 0
	global_load_dwordx4 v[156:159], v180, s[74:75]
	s_waitcnt vmcnt(7)
	ds_write_b128 v178, v[128:131]
	s_waitcnt vmcnt(6)
	ds_write_b128 v178, v[132:135] offset:1088
	s_waitcnt vmcnt(5)
	ds_write_b128 v178, v[136:139] offset:2176
	s_waitcnt vmcnt(4)
	ds_write_b128 v178, v[140:143] offset:3264
	s_waitcnt vmcnt(3)
	ds_write_b128 v178, v[144:147] offset:4352
	s_waitcnt vmcnt(2)
	ds_write_b128 v178, v[148:151] offset:5440
	s_waitcnt vmcnt(1)
	ds_write_b128 v178, v[152:155] offset:6528
	s_waitcnt vmcnt(0)
	ds_write_b128 v178, v[156:159] offset:7616
	ds_read_b128 v[128:131], v176
	ds_read_b128 v[132:135], v176 offset:32
	ds_read_b128 v[136:139], v176 offset:64
	ds_read_b128 v[140:143], v176 offset:96
	ds_read_b128 v[144:147], v176 offset:128
	ds_read_b128 v[148:151], v176 offset:160
	ds_read_b128 v[152:155], v176 offset:192
	ds_read_b128 v[156:159], v176 offset:224
	s_waitcnt lgkmcnt(7)
	v_add_f32_e32 v112, v128, v112
	v_add_f32_e32 v113, v129, v113
	v_add_f32_e32 v114, v130, v114
	v_add_f32_e32 v115, v131, v115
	v_fmac_f32_e32 v183, v112, v112
	v_fmac_f32_e32 v183, v113, v113
	v_fmac_f32_e32 v183, v114, v114
	v_fmac_f32_e32 v183, v115, v115
	ds_write_b128 v176, v[112:115]
	s_waitcnt lgkmcnt(7)
; DI bfr f2bf(float a) { return (bfr)(pack2(a, 0.f) & 0xffffu); }
; DI int crow(int reg, int h) { return (reg & 3) + 8 * (reg >> 2) + 4 * h; }
; template <bool FIRST, bool HAS_H>
; DI void phase_gemm_resid(const Params& p, const bfr* A, const bfr* Wt, const float* gnext, float* ss, char* smem) {
;     ...
; #pragma unroll
;     for (int i = 0; i < 2; ++i) {
; #pragma unroll
;       for (int qh = 0; qh < 2; ++qh) {
;         float rs[8];
; #pragma unroll
;         for (int q = 0; q < 8; ++q) rs[q] = 0.f;
; #pragma unroll
;         for (int jh = 0; jh < 2; ++jh) {
;           float xo[2][8];
; #pragma unroll
;           for (int jj = 0; jj < 2; ++jj)
; #pragma unroll
;             for (int q = 0; q < 8; ++q)
;               xo[jj][q] = xsrc[(rbase + i * 32 + crow(qh * 8 + q, 0)) * 1024 + cbase + (jh * 2 + jj) * 32];
; #pragma unroll
;           for (int q = 0; q < 8; ++q) {
;             const int o = (rbase + i * 32 + crow(qh * 8 + q, 0)) * 1024 + cbase;
; #pragma unroll
;             for (int jj = 0; jj < 2; ++jj) {
;               const int j = jh * 2 + jj;
;               const float xn = xo[jj][q] + acc[i][j][qh * 8 + q];
;               X[o + j * 32] = xn;
;               if (HAS_H) Hn[o + j * 32] = f2bf(xn * gnext[cbase + j * 32]);
;               rs[q] += xn * xn;
;             }
;           }
;         }
	v_add_f32_e32 v116, v132, v116
	v_add_f32_e32 v117, v133, v117
	v_add_f32_e32 v118, v134, v118
	v_add_f32_e32 v119, v135, v119
	v_fmac_f32_e32 v183, v116, v116
	v_fmac_f32_e32 v183, v117, v117
	v_fmac_f32_e32 v183, v118, v118
	v_fmac_f32_e32 v183, v119, v119
	ds_write_b128 v176, v[116:119] offset:32
	s_waitcnt lgkmcnt(7)
	v_add_f32_e32 v120, v136, v120
	v_add_f32_e32 v121, v137, v121
	v_add_f32_e32 v122, v138, v122
	v_add_f32_e32 v123, v139, v123
	v_fmac_f32_e32 v183, v120, v120
	v_fmac_f32_e32 v183, v121, v121
	v_fmac_f32_e32 v183, v122, v122
	v_fmac_f32_e32 v183, v123, v123
	ds_write_b128 v176, v[120:123] offset:64
	s_waitcnt lgkmcnt(7)
	v_add_f32_e32 v124, v140, v124
	v_add_f32_e32 v125, v141, v125
	v_add_f32_e32 v126, v142, v126
	v_add_f32_e32 v127, v143, v127
	v_fmac_f32_e32 v183, v124, v124
	v_fmac_f32_e32 v183, v125, v125
	v_fmac_f32_e32 v183, v126, v126
	v_fmac_f32_e32 v183, v127, v127
	ds_write_b128 v176, v[124:127] offset:96
	s_waitcnt lgkmcnt(7)
	v_add_f32_e32 v96, v144, v96
	v_add_f32_e32 v97, v145, v97
	v_add_f32_e32 v98, v146, v98
	v_add_f32_e32 v99, v147, v99
	v_fmac_f32_e32 v183, v96, v96
	v_fmac_f32_e32 v183, v97, v97
	v_fmac_f32_e32 v183, v98, v98
	v_fmac_f32_e32 v183, v99, v99
	ds_write_b128 v176, v[96:99] offset:128
	s_waitcnt lgkmcnt(7)
	v_add_f32_e32 v100, v148, v100
	v_add_f32_e32 v101, v149, v101
	v_add_f32_e32 v102, v150, v102
	v_add_f32_e32 v103, v151, v103
	v_fmac_f32_e32 v183, v100, v100
	v_fmac_f32_e32 v183, v101, v101
	v_fmac_f32_e32 v183, v102, v102
	v_fmac_f32_e32 v183, v103, v103
	ds_write_b128 v176, v[100:103] offset:160
	s_waitcnt lgkmcnt(7)
	v_add_f32_e32 v104, v152, v104
	v_add_f32_e32 v105, v153, v105
	v_add_f32_e32 v106, v154, v106
	v_add_f32_e32 v107, v155, v107
	v_fmac_f32_e32 v183, v104, v104
	v_fmac_f32_e32 v183, v105, v105
	v_fmac_f32_e32 v183, v106, v106
	v_fmac_f32_e32 v183, v107, v107
	ds_write_b128 v176, v[104:107] offset:192
	s_waitcnt lgkmcnt(7)
	v_add_f32_e32 v108, v156, v108
	v_add_f32_e32 v109, v157, v109
	v_add_f32_e32 v110, v158, v110
	v_add_f32_e32 v111, v159, v111
	v_fmac_f32_e32 v183, v108, v108
	v_fmac_f32_e32 v183, v109, v109
	v_fmac_f32_e32 v183, v110, v110
	v_fmac_f32_e32 v183, v111, v111
	ds_write_b128 v176, v[108:111] offset:224
	ds_read_b128 v[128:131], v178
	ds_read_b128 v[132:135], v178 offset:1088
	ds_read_b128 v[136:139], v178 offset:2176
	ds_read_b128 v[140:143], v178 offset:3264
	ds_read_b128 v[144:147], v178 offset:4352
	ds_read_b128 v[148:151], v178 offset:5440
	ds_read_b128 v[152:155], v178 offset:6528
	ds_read_b128 v[156:159], v178 offset:7616
	s_add_u32 s74, s66, 0x0
	s_addc_u32 s75, s67, 0
	s_waitcnt lgkmcnt(7)
	global_store_dwordx4 v180, v[128:131], s[74:75]
	s_add_u32 s74, s66, 0x4000
	s_addc_u32 s75, s67, 0
	s_waitcnt lgkmcnt(6)
	global_store_dwordx4 v180, v[132:135], s[74:75]
	s_add_u32 s74, s66, 0x8000
	s_addc_u32 s75, s67, 0
	s_waitcnt lgkmcnt(5)
	global_store_dwordx4 v180, v[136:139], s[74:75]
	s_add_u32 s74, s66, 0xc000
	s_addc_u32 s75, s67, 0
	s_waitcnt lgkmcnt(4)
	global_store_dwordx4 v180, v[140:143], s[74:75]
	s_add_u32 s74, s66, 0x10000
	s_addc_u32 s75, s67, 0
	s_waitcnt lgkmcnt(3)
	global_store_dwordx4 v180, v[144:147], s[74:75]
	s_add_u32 s74, s66, 0x14000
	s_addc_u32 s75, s67, 0
	s_waitcnt lgkmcnt(2)
	global_store_dwordx4 v180, v[148:151], s[74:75]
	s_add_u32 s74, s66, 0x18000
	s_addc_u32 s75, s67, 0
	s_waitcnt lgkmcnt(1)
	global_store_dwordx4 v180, v[152:155], s[74:75]
	s_add_u32 s74, s66, 0x1c000
	s_addc_u32 s75, s67, 0
	s_waitcnt lgkmcnt(0)
	global_store_dwordx4 v180, v[156:159], s[74:75]
	global_load_dwordx4 v[128:131], v182, s[70:71]
	global_load_dwordx4 v[132:135], v182, s[70:71] offset:32
	global_load_dwordx4 v[136:139], v182, s[70:71] offset:64
	global_load_dwordx4 v[140:143], v182, s[70:71] offset:96
	global_load_dwordx4 v[144:147], v182, s[70:71] offset:128
	global_load_dwordx4 v[148:151], v182, s[70:71] offset:160
	global_load_dwordx4 v[152:155], v182, s[70:71] offset:192
	global_load_dwordx4 v[156:159], v182, s[70:71] offset:224
	s_waitcnt vmcnt(7)
	v_mul_f32_e32 v112, v128, v112
	v_mul_f32_e32 v113, v129, v113
	v_mul_f32_e32 v114, v130, v114
	v_mul_f32_e32 v115, v131, v115
	v_cvt_pk_bf16_f32 v112, v112, v113
	v_cvt_pk_bf16_f32 v113, v114, v115
	ds_write_b64 v177, v[112:113]
	s_waitcnt vmcnt(6)
	v_mul_f32_e32 v116, v132, v116
	v_mul_f32_e32 v117, v133, v117
	v_mul_f32_e32 v118, v134, v118
	v_mul_f32_e32 v119, v135, v119
	v_cvt_pk_bf16_f32 v116, v116, v117
	v_cvt_pk_bf16_f32 v117, v118, v119
	ds_write_b64 v177, v[116:117] offset:16
	s_waitcnt vmcnt(5)
	v_mul_f32_e32 v120, v136, v120
	v_mul_f32_e32 v121, v137, v121
	v_mul_f32_e32 v122, v138, v122
	v_mul_f32_e32 v123, v139, v123
	v_cvt_pk_bf16_f32 v120, v120, v121
	v_cvt_pk_bf16_f32 v121, v122, v123
	ds_write_b64 v177, v[120:121] offset:32
	s_waitcnt vmcnt(4)
	v_mul_f32_e32 v124, v140, v124
	v_mul_f32_e32 v125, v141, v125
	v_mul_f32_e32 v126, v142, v126
	v_mul_f32_e32 v127, v143, v127
	v_cvt_pk_bf16_f32 v124, v124, v125
	v_cvt_pk_bf16_f32 v125, v126, v127
	ds_write_b64 v177, v[124:125] offset:48
	s_waitcnt vmcnt(3)
	v_mul_f32_e32 v96, v144, v96
	v_mul_f32_e32 v97, v145, v97
	v_mul_f32_e32 v98, v146, v98
	v_mul_f32_e32 v99, v147, v99
	v_cvt_pk_bf16_f32 v96, v96, v97
	v_cvt_pk_bf16_f32 v97, v98, v99
	ds_write_b64 v177, v[96:97] offset:64
	s_waitcnt vmcnt(2)
	v_mul_f32_e32 v100, v148, v100
	v_mul_f32_e32 v101, v149, v101
	v_mul_f32_e32 v102, v150, v102
	v_mul_f32_e32 v103, v151, v103
	v_cvt_pk_bf16_f32 v100, v100, v101
	v_cvt_pk_bf16_f32 v101, v102, v103
	ds_write_b64 v177, v[100:101] offset:80
	s_waitcnt vmcnt(1)
; DI bfr f2bf(float a) { return (bfr)(pack2(a, 0.f) & 0xffffu); }
; DI int crow(int reg, int h) { return (reg & 3) + 8 * (reg >> 2) + 4 * h; }
; template <bool FIRST, bool HAS_H>
; DI void phase_gemm_resid(const Params& p, const bfr* A, const bfr* Wt, const float* gnext, float* ss, char* smem) {
;     ...
; #pragma unroll
;     for (int i = 0; i < 2; ++i) {
; #pragma unroll
;       for (int qh = 0; qh < 2; ++qh) {
;         float rs[8];
; #pragma unroll
;         for (int q = 0; q < 8; ++q) rs[q] = 0.f;
; #pragma unroll
;         for (int jh = 0; jh < 2; ++jh) {
;           float xo[2][8];
; #pragma unroll
;           for (int jj = 0; jj < 2; ++jj)
; #pragma unroll
;             for (int q = 0; q < 8; ++q)
;               xo[jj][q] = xsrc[(rbase + i * 32 + crow(qh * 8 + q, 0)) * 1024 + cbase + (jh * 2 + jj) * 32];
; #pragma unroll
;           for (int q = 0; q < 8; ++q) {
;             const int o = (rbase + i * 32 + crow(qh * 8 + q, 0)) * 1024 + cbase;
; #pragma unroll
;             for (int jj = 0; jj < 2; ++jj) {
;               const int j = jh * 2 + jj;
;               const float xn = xo[jj][q] + acc[i][j][qh * 8 + q];
;               X[o + j * 32] = xn;
;               if (HAS_H) Hn[o + j * 32] = f2bf(xn * gnext[cbase + j * 32]);
;               rs[q] += xn * xn;
;             }
;           }
;         }
	v_mul_f32_e32 v104, v152, v104
	v_mul_f32_e32 v105, v153, v105
	v_mul_f32_e32 v106, v154, v106
	v_mul_f32_e32 v107, v155, v107
	v_cvt_pk_bf16_f32 v104, v104, v105
	v_cvt_pk_bf16_f32 v105, v106, v107
	ds_write_b64 v177, v[104:105] offset:96
	s_waitcnt vmcnt(0)
	v_mul_f32_e32 v108, v156, v108
	v_mul_f32_e32 v109, v157, v109
	v_mul_f32_e32 v110, v158, v110
	v_mul_f32_e32 v111, v159, v111
	v_cvt_pk_bf16_f32 v108, v108, v109
	v_cvt_pk_bf16_f32 v109, v110, v111
	ds_write_b64 v177, v[108:109] offset:112
	ds_read_b128 v[128:131], v179
	ds_read_b128 v[132:135], v179 offset:2176
	ds_read_b128 v[136:139], v179 offset:4352
	ds_read_b128 v[140:143], v179 offset:6528
	s_add_u32 s74, s68, 0x0
	s_addc_u32 s75, s69, 0
	s_waitcnt lgkmcnt(3)
	global_store_dwordx4 v181, v[128:131], s[74:75]
	s_add_u32 s74, s68, 0x4000
	s_addc_u32 s75, s69, 0
	s_waitcnt lgkmcnt(2)
	global_store_dwordx4 v181, v[132:135], s[74:75]
	s_add_u32 s74, s68, 0x8000
	s_addc_u32 s75, s69, 0
	s_waitcnt lgkmcnt(1)
	global_store_dwordx4 v181, v[136:139], s[74:75]
	s_add_u32 s74, s68, 0xc000
	s_addc_u32 s75, s69, 0
	s_waitcnt lgkmcnt(0)
	global_store_dwordx4 v181, v[140:143], s[74:75]
	s_add_u32 s74, s64, 0x100
	s_addc_u32 s75, s65, 0
	global_load_dwordx4 v[128:131], v180, s[74:75]
	s_add_u32 s74, s64, 0x4100
	s_addc_u32 s75, s65, 0
	global_load_dwordx4 v[132:135], v180, s[74:75]
	s_add_u32 s74, s64, 0x8100
	s_addc_u32 s75, s65, 0
	global_load_dwordx4 v[136:139], v180, s[74:75]
	s_add_u32 s74, s64, 0xc100
	s_addc_u32 s75, s65, 0
	global_load_dwordx4 v[140:143], v180, s[74:75]
	s_add_u32 s74, s64, 0x10100
	s_addc_u32 s75, s65, 0
	global_load_dwordx4 v[144:147], v180, s[74:75]
	s_add_u32 s74, s64, 0x14100
	s_addc_u32 s75, s65, 0
	global_load_dwordx4 v[148:151], v180, s[74:75]
	s_add_u32 s74, s64, 0x18100
	s_addc_u32 s75, s65, 0
	global_load_dwordx4 v[152:155], v180, s[74:75]
	s_add_u32 s74, s64, 0x1c100
	s_addc_u32 s75, s65, 0
	global_load_dwordx4 v[156:159], v180, s[74:75]
	s_waitcnt vmcnt(7)
	ds_write_b128 v178, v[128:131]
	s_waitcnt vmcnt(6)
	ds_write_b128 v178, v[132:135] offset:1088
	s_waitcnt vmcnt(5)
	ds_write_b128 v178, v[136:139] offset:2176
	s_waitcnt vmcnt(4)
	ds_write_b128 v178, v[140:143] offset:3264
	s_waitcnt vmcnt(3)
	ds_write_b128 v178, v[144:147] offset:4352
	s_waitcnt vmcnt(2)
	ds_write_b128 v178, v[148:151] offset:5440
	s_waitcnt vmcnt(1)
	ds_write_b128 v178, v[152:155] offset:6528
	s_waitcnt vmcnt(0)
	ds_write_b128 v178, v[156:159] offset:7616
	ds_read_b128 v[128:131], v176
	ds_read_b128 v[132:135], v176 offset:32
	ds_read_b128 v[136:139], v176 offset:64
	ds_read_b128 v[140:143], v176 offset:96
	ds_read_b128 v[144:147], v176 offset:128
	ds_read_b128 v[148:151], v176 offset:160
	ds_read_b128 v[152:155], v176 offset:192
	ds_read_b128 v[156:159], v176 offset:224
	s_waitcnt lgkmcnt(7)
	v_add_f32_e32 v80, v128, v80
	v_add_f32_e32 v81, v129, v81
	v_add_f32_e32 v82, v130, v82
	v_add_f32_e32 v83, v131, v83
	v_fmac_f32_e32 v183, v80, v80
	v_fmac_f32_e32 v183, v81, v81
	v_fmac_f32_e32 v183, v82, v82
	v_fmac_f32_e32 v183, v83, v83
	ds_write_b128 v176, v[80:83]
	s_waitcnt lgkmcnt(7)
	v_add_f32_e32 v84, v132, v84
	v_add_f32_e32 v85, v133, v85
	v_add_f32_e32 v86, v134, v86
	v_add_f32_e32 v87, v135, v87
	v_fmac_f32_e32 v183, v84, v84
	v_fmac_f32_e32 v183, v85, v85
	v_fmac_f32_e32 v183, v86, v86
	v_fmac_f32_e32 v183, v87, v87
	ds_write_b128 v176, v[84:87] offset:32
	s_waitcnt lgkmcnt(7)
	v_add_f32_e32 v88, v136, v88
	v_add_f32_e32 v89, v137, v89
	v_add_f32_e32 v90, v138, v90
	v_add_f32_e32 v91, v139, v91
	v_fmac_f32_e32 v183, v88, v88
	v_fmac_f32_e32 v183, v89, v89
	v_fmac_f32_e32 v183, v90, v90
	v_fmac_f32_e32 v183, v91, v91
	ds_write_b128 v176, v[88:91] offset:64
	s_waitcnt lgkmcnt(7)
	v_add_f32_e32 v92, v140, v92
	v_add_f32_e32 v93, v141, v93
	v_add_f32_e32 v94, v142, v94
	v_add_f32_e32 v95, v143, v95
	v_fmac_f32_e32 v183, v92, v92
	v_fmac_f32_e32 v183, v93, v93
	v_fmac_f32_e32 v183, v94, v94
	v_fmac_f32_e32 v183, v95, v95
	ds_write_b128 v176, v[92:95] offset:96
	s_waitcnt lgkmcnt(7)
	v_add_f32_e32 v64, v144, v64
	v_add_f32_e32 v65, v145, v65
	v_add_f32_e32 v66, v146, v66
	v_add_f32_e32 v67, v147, v67
	v_fmac_f32_e32 v183, v64, v64
	v_fmac_f32_e32 v183, v65, v65
	v_fmac_f32_e32 v183, v66, v66
	v_fmac_f32_e32 v183, v67, v67
	ds_write_b128 v176, v[64:67] offset:128
	s_waitcnt lgkmcnt(7)
	v_add_f32_e32 v68, v148, v68
	v_add_f32_e32 v69, v149, v69
	v_add_f32_e32 v70, v150, v70
	v_add_f32_e32 v71, v151, v71
	v_fmac_f32_e32 v183, v68, v68
	v_fmac_f32_e32 v183, v69, v69
	v_fmac_f32_e32 v183, v70, v70
	v_fmac_f32_e32 v183, v71, v71
	ds_write_b128 v176, v[68:71] offset:160
	s_waitcnt lgkmcnt(7)
	v_add_f32_e32 v72, v152, v72
	v_add_f32_e32 v73, v153, v73
	v_add_f32_e32 v74, v154, v74
	v_add_f32_e32 v75, v155, v75
	v_fmac_f32_e32 v183, v72, v72
	v_fmac_f32_e32 v183, v73, v73
	v_fmac_f32_e32 v183, v74, v74
	v_fmac_f32_e32 v183, v75, v75
	ds_write_b128 v176, v[72:75] offset:192
	s_waitcnt lgkmcnt(7)
	v_add_f32_e32 v76, v156, v76
	v_add_f32_e32 v77, v157, v77
	v_add_f32_e32 v78, v158, v78
	v_add_f32_e32 v79, v159, v79
	v_fmac_f32_e32 v183, v76, v76
	v_fmac_f32_e32 v183, v77, v77
	v_fmac_f32_e32 v183, v78, v78
	v_fmac_f32_e32 v183, v79, v79
	ds_write_b128 v176, v[76:79] offset:224
	ds_read_b128 v[128:131], v178
	ds_read_b128 v[132:135], v178 offset:1088
	ds_read_b128 v[136:139], v178 offset:2176
	ds_read_b128 v[140:143], v178 offset:3264
	ds_read_b128 v[144:147], v178 offset:4352
	ds_read_b128 v[148:151], v178 offset:5440
	ds_read_b128 v[152:155], v178 offset:6528
	ds_read_b128 v[156:159], v178 offset:7616
	s_add_u32 s74, s66, 0x100
	s_addc_u32 s75, s67, 0
	s_waitcnt lgkmcnt(7)
; DI bfr f2bf(float a) { return (bfr)(pack2(a, 0.f) & 0xffffu); }
; DI int crow(int reg, int h) { return (reg & 3) + 8 * (reg >> 2) + 4 * h; }
; template <bool FIRST, bool HAS_H>
; DI void phase_gemm_resid(const Params& p, const bfr* A, const bfr* Wt, const float* gnext, float* ss, char* smem) {
;     ...
; #pragma unroll
;     for (int i = 0; i < 2; ++i) {
; #pragma unroll
;       for (int qh = 0; qh < 2; ++qh) {
;         float rs[8];
; #pragma unroll
;         for (int q = 0; q < 8; ++q) rs[q] = 0.f;
; #pragma unroll
;         for (int jh = 0; jh < 2; ++jh) {
;           float xo[2][8];
; #pragma unroll
;           for (int jj = 0; jj < 2; ++jj)
; #pragma unroll
;             for (int q = 0; q < 8; ++q)
;               xo[jj][q] = xsrc[(rbase + i * 32 + crow(qh * 8 + q, 0)) * 1024 + cbase + (jh * 2 + jj) * 32];
; #pragma unroll
;           for (int q = 0; q < 8; ++q) {
;             const int o = (rbase + i * 32 + crow(qh * 8 + q, 0)) * 1024 + cbase;
; #pragma unroll
;             for (int jj = 0; jj < 2; ++jj) {
;               const int j = jh * 2 + jj;
;               const float xn = xo[jj][q] + acc[i][j][qh * 8 + q];
;               X[o + j * 32] = xn;
;               if (HAS_H) Hn[o + j * 32] = f2bf(xn * gnext[cbase + j * 32]);
;               rs[q] += xn * xn;
;             }
;           }
;         }
	global_store_dwordx4 v180, v[128:131], s[74:75]
	s_add_u32 s74, s66, 0x4100
	s_addc_u32 s75, s67, 0
	s_waitcnt lgkmcnt(6)
	global_store_dwordx4 v180, v[132:135], s[74:75]
	s_add_u32 s74, s66, 0x8100
	s_addc_u32 s75, s67, 0
	s_waitcnt lgkmcnt(5)
	global_store_dwordx4 v180, v[136:139], s[74:75]
	s_add_u32 s74, s66, 0xc100
	s_addc_u32 s75, s67, 0
	s_waitcnt lgkmcnt(4)
	global_store_dwordx4 v180, v[140:143], s[74:75]
	s_add_u32 s74, s66, 0x10100
	s_addc_u32 s75, s67, 0
	s_waitcnt lgkmcnt(3)
	global_store_dwordx4 v180, v[144:147], s[74:75]
	s_add_u32 s74, s66, 0x14100
	s_addc_u32 s75, s67, 0
	s_waitcnt lgkmcnt(2)
	global_store_dwordx4 v180, v[148:151], s[74:75]
	s_add_u32 s74, s66, 0x18100
	s_addc_u32 s75, s67, 0
	s_waitcnt lgkmcnt(1)
	global_store_dwordx4 v180, v[152:155], s[74:75]
	s_add_u32 s74, s66, 0x1c100
	s_addc_u32 s75, s67, 0
	s_waitcnt lgkmcnt(0)
	global_store_dwordx4 v180, v[156:159], s[74:75]
	global_load_dwordx4 v[128:131], v182, s[70:71] offset:256
	global_load_dwordx4 v[132:135], v182, s[70:71] offset:288
	global_load_dwordx4 v[136:139], v182, s[70:71] offset:320
	global_load_dwordx4 v[140:143], v182, s[70:71] offset:352
	global_load_dwordx4 v[144:147], v182, s[70:71] offset:384
	global_load_dwordx4 v[148:151], v182, s[70:71] offset:416
	global_load_dwordx4 v[152:155], v182, s[70:71] offset:448
	global_load_dwordx4 v[156:159], v182, s[70:71] offset:480
	s_waitcnt vmcnt(7)
	v_mul_f32_e32 v80, v128, v80
	v_mul_f32_e32 v81, v129, v81
	v_mul_f32_e32 v82, v130, v82
	v_mul_f32_e32 v83, v131, v83
	v_cvt_pk_bf16_f32 v80, v80, v81
	v_cvt_pk_bf16_f32 v81, v82, v83
	ds_write_b64 v177, v[80:81]
	s_waitcnt vmcnt(6)
	v_mul_f32_e32 v84, v132, v84
	v_mul_f32_e32 v85, v133, v85
	v_mul_f32_e32 v86, v134, v86
	v_mul_f32_e32 v87, v135, v87
	v_cvt_pk_bf16_f32 v84, v84, v85
	v_cvt_pk_bf16_f32 v85, v86, v87
	ds_write_b64 v177, v[84:85] offset:16
	s_waitcnt vmcnt(5)
	v_mul_f32_e32 v88, v136, v88
	v_mul_f32_e32 v89, v137, v89
	v_mul_f32_e32 v90, v138, v90
	v_mul_f32_e32 v91, v139, v91
	v_cvt_pk_bf16_f32 v88, v88, v89
	v_cvt_pk_bf16_f32 v89, v90, v91
	ds_write_b64 v177, v[88:89] offset:32
	s_waitcnt vmcnt(4)
	v_mul_f32_e32 v92, v140, v92
	v_mul_f32_e32 v93, v141, v93
	v_mul_f32_e32 v94, v142, v94
	v_mul_f32_e32 v95, v143, v95
	v_cvt_pk_bf16_f32 v92, v92, v93
	v_cvt_pk_bf16_f32 v93, v94, v95
	ds_write_b64 v177, v[92:93] offset:48
	s_waitcnt vmcnt(3)
	v_mul_f32_e32 v64, v144, v64
	v_mul_f32_e32 v65, v145, v65
	v_mul_f32_e32 v66, v146, v66
	v_mul_f32_e32 v67, v147, v67
	v_cvt_pk_bf16_f32 v64, v64, v65
	v_cvt_pk_bf16_f32 v65, v66, v67
	ds_write_b64 v177, v[64:65] offset:64
	s_waitcnt vmcnt(2)
	v_mul_f32_e32 v68, v148, v68
	v_mul_f32_e32 v69, v149, v69
	v_mul_f32_e32 v70, v150, v70
	v_mul_f32_e32 v71, v151, v71
	v_cvt_pk_bf16_f32 v68, v68, v69
	v_cvt_pk_bf16_f32 v69, v70, v71
	ds_write_b64 v177, v[68:69] offset:80
	s_waitcnt vmcnt(1)
	v_mul_f32_e32 v72, v152, v72
	v_mul_f32_e32 v73, v153, v73
	v_mul_f32_e32 v74, v154, v74
	v_mul_f32_e32 v75, v155, v75
	v_cvt_pk_bf16_f32 v72, v72, v73
	v_cvt_pk_bf16_f32 v73, v74, v75
	ds_write_b64 v177, v[72:73] offset:96
	s_waitcnt vmcnt(0)
	v_mul_f32_e32 v76, v156, v76
	v_mul_f32_e32 v77, v157, v77
	v_mul_f32_e32 v78, v158, v78
	v_mul_f32_e32 v79, v159, v79
	v_cvt_pk_bf16_f32 v76, v76, v77
	v_cvt_pk_bf16_f32 v77, v78, v79
	ds_write_b64 v177, v[76:77] offset:112
	ds_read_b128 v[128:131], v179
	ds_read_b128 v[132:135], v179 offset:2176
	ds_read_b128 v[136:139], v179 offset:4352
	ds_read_b128 v[140:143], v179 offset:6528
	s_add_u32 s74, s68, 0x80
	s_addc_u32 s75, s69, 0
	s_waitcnt lgkmcnt(3)
	global_store_dwordx4 v181, v[128:131], s[74:75]
	s_add_u32 s74, s68, 0x4080
	s_addc_u32 s75, s69, 0
	s_waitcnt lgkmcnt(2)
	global_store_dwordx4 v181, v[132:135], s[74:75]
	s_add_u32 s74, s68, 0x8080
	s_addc_u32 s75, s69, 0
	s_waitcnt lgkmcnt(1)
	global_store_dwordx4 v181, v[136:139], s[74:75]
	s_add_u32 s74, s68, 0xc080
	s_addc_u32 s75, s69, 0
	s_waitcnt lgkmcnt(0)
	global_store_dwordx4 v181, v[140:143], s[74:75]
	s_add_u32 s74, s64, 0x20000
	s_addc_u32 s75, s65, 0
	global_load_dwordx4 v[128:131], v180, s[74:75]
	s_add_u32 s74, s64, 0x24000
	s_addc_u32 s75, s65, 0
	global_load_dwordx4 v[132:135], v180, s[74:75]
	s_add_u32 s74, s64, 0x28000
	s_addc_u32 s75, s65, 0
	global_load_dwordx4 v[136:139], v180, s[74:75]
	s_add_u32 s74, s64, 0x2c000
	s_addc_u32 s75, s65, 0
	global_load_dwordx4 v[140:143], v180, s[74:75]
	s_add_u32 s74, s64, 0x30000
	s_addc_u32 s75, s65, 0
	global_load_dwordx4 v[144:147], v180, s[74:75]
	s_add_u32 s74, s64, 0x34000
	s_addc_u32 s75, s65, 0
	global_load_dwordx4 v[148:151], v180, s[74:75]
	s_add_u32 s74, s64, 0x38000
	s_addc_u32 s75, s65, 0
	global_load_dwordx4 v[152:155], v180, s[74:75]
	s_add_u32 s74, s64, 0x3c000
	s_addc_u32 s75, s65, 0
	global_load_dwordx4 v[156:159], v180, s[74:75]
	s_waitcnt vmcnt(7)
	ds_write_b128 v178, v[128:131]
	s_waitcnt vmcnt(6)
	ds_write_b128 v178, v[132:135] offset:1088
	s_waitcnt vmcnt(5)
	ds_write_b128 v178, v[136:139] offset:2176
	s_waitcnt vmcnt(4)
	ds_write_b128 v178, v[140:143] offset:3264
	s_waitcnt vmcnt(3)
	ds_write_b128 v178, v[144:147] offset:4352
	s_waitcnt vmcnt(2)
	ds_write_b128 v178, v[148:151] offset:5440
	s_waitcnt vmcnt(1)
	ds_write_b128 v178, v[152:155] offset:6528
	s_waitcnt vmcnt(0)
	ds_write_b128 v178, v[156:159] offset:7616
	ds_read_b128 v[128:131], v176
	ds_read_b128 v[132:135], v176 offset:32
	ds_read_b128 v[136:139], v176 offset:64
	ds_read_b128 v[140:143], v176 offset:96
	ds_read_b128 v[144:147], v176 offset:128
	ds_read_b128 v[148:151], v176 offset:160
	ds_read_b128 v[152:155], v176 offset:192
	ds_read_b128 v[156:159], v176 offset:224
	s_waitcnt lgkmcnt(7)
; DI bfr f2bf(float a) { return (bfr)(pack2(a, 0.f) & 0xffffu); }
; DI int crow(int reg, int h) { return (reg & 3) + 8 * (reg >> 2) + 4 * h; }
; template <bool FIRST, bool HAS_H>
; DI void phase_gemm_resid(const Params& p, const bfr* A, const bfr* Wt, const float* gnext, float* ss, char* smem) {
;     ...
; #pragma unroll
;     for (int i = 0; i < 2; ++i) {
; #pragma unroll
;       for (int qh = 0; qh < 2; ++qh) {
;         float rs[8];
; #pragma unroll
;         for (int q = 0; q < 8; ++q) rs[q] = 0.f;
; #pragma unroll
;         for (int jh = 0; jh < 2; ++jh) {
;           float xo[2][8];
; #pragma unroll
;           for (int jj = 0; jj < 2; ++jj)
; #pragma unroll
;             for (int q = 0; q < 8; ++q)
;               xo[jj][q] = xsrc[(rbase + i * 32 + crow(qh * 8 + q, 0)) * 1024 + cbase + (jh * 2 + jj) * 32];
; #pragma unroll
;           for (int q = 0; q < 8; ++q) {
;             const int o = (rbase + i * 32 + crow(qh * 8 + q, 0)) * 1024 + cbase;
; #pragma unroll
;             for (int jj = 0; jj < 2; ++jj) {
;               const int j = jh * 2 + jj;
;               const float xn = xo[jj][q] + acc[i][j][qh * 8 + q];
;               X[o + j * 32] = xn;
;               if (HAS_H) Hn[o + j * 32] = f2bf(xn * gnext[cbase + j * 32]);
;               rs[q] += xn * xn;
;             }
;           }
;         }
	v_add_f32_e32 v48, v128, v48
	v_add_f32_e32 v49, v129, v49
	v_add_f32_e32 v50, v130, v50
	v_add_f32_e32 v51, v131, v51
	v_fmac_f32_e32 v184, v48, v48
	v_fmac_f32_e32 v184, v49, v49
	v_fmac_f32_e32 v184, v50, v50
	v_fmac_f32_e32 v184, v51, v51
	ds_write_b128 v176, v[48:51]
	s_waitcnt lgkmcnt(7)
	v_add_f32_e32 v52, v132, v52
	v_add_f32_e32 v53, v133, v53
	v_add_f32_e32 v54, v134, v54
	v_add_f32_e32 v55, v135, v55
	v_fmac_f32_e32 v184, v52, v52
	v_fmac_f32_e32 v184, v53, v53
	v_fmac_f32_e32 v184, v54, v54
	v_fmac_f32_e32 v184, v55, v55
	ds_write_b128 v176, v[52:55] offset:32
	s_waitcnt lgkmcnt(7)
	v_add_f32_e32 v56, v136, v56
	v_add_f32_e32 v57, v137, v57
	v_add_f32_e32 v58, v138, v58
	v_add_f32_e32 v59, v139, v59
	v_fmac_f32_e32 v184, v56, v56
	v_fmac_f32_e32 v184, v57, v57
	v_fmac_f32_e32 v184, v58, v58
	v_fmac_f32_e32 v184, v59, v59
	ds_write_b128 v176, v[56:59] offset:64
	s_waitcnt lgkmcnt(7)
	v_add_f32_e32 v60, v140, v60
	v_add_f32_e32 v61, v141, v61
	v_add_f32_e32 v62, v142, v62
	v_add_f32_e32 v63, v143, v63
	v_fmac_f32_e32 v184, v60, v60
	v_fmac_f32_e32 v184, v61, v61
	v_fmac_f32_e32 v184, v62, v62
	v_fmac_f32_e32 v184, v63, v63
	ds_write_b128 v176, v[60:63] offset:96
	s_waitcnt lgkmcnt(7)
	v_add_f32_e32 v32, v144, v32
	v_add_f32_e32 v33, v145, v33
	v_add_f32_e32 v34, v146, v34
	v_add_f32_e32 v35, v147, v35
	v_fmac_f32_e32 v184, v32, v32
	v_fmac_f32_e32 v184, v33, v33
	v_fmac_f32_e32 v184, v34, v34
	v_fmac_f32_e32 v184, v35, v35
	ds_write_b128 v176, v[32:35] offset:128
	s_waitcnt lgkmcnt(7)
	v_add_f32_e32 v36, v148, v36
	v_add_f32_e32 v37, v149, v37
	v_add_f32_e32 v38, v150, v38
	v_add_f32_e32 v39, v151, v39
	v_fmac_f32_e32 v184, v36, v36
	v_fmac_f32_e32 v184, v37, v37
	v_fmac_f32_e32 v184, v38, v38
	v_fmac_f32_e32 v184, v39, v39
	ds_write_b128 v176, v[36:39] offset:160
	s_waitcnt lgkmcnt(7)
	v_add_f32_e32 v40, v152, v40
	v_add_f32_e32 v41, v153, v41
	v_add_f32_e32 v42, v154, v42
	v_add_f32_e32 v43, v155, v43
	v_fmac_f32_e32 v184, v40, v40
	v_fmac_f32_e32 v184, v41, v41
	v_fmac_f32_e32 v184, v42, v42
	v_fmac_f32_e32 v184, v43, v43
	ds_write_b128 v176, v[40:43] offset:192
	s_waitcnt lgkmcnt(7)
	v_add_f32_e32 v44, v156, v44
	v_add_f32_e32 v45, v157, v45
	v_add_f32_e32 v46, v158, v46
	v_add_f32_e32 v47, v159, v47
	v_fmac_f32_e32 v184, v44, v44
	v_fmac_f32_e32 v184, v45, v45
	v_fmac_f32_e32 v184, v46, v46
	v_fmac_f32_e32 v184, v47, v47
	ds_write_b128 v176, v[44:47] offset:224
	ds_read_b128 v[128:131], v178
	ds_read_b128 v[132:135], v178 offset:1088
	ds_read_b128 v[136:139], v178 offset:2176
	ds_read_b128 v[140:143], v178 offset:3264
	ds_read_b128 v[144:147], v178 offset:4352
	ds_read_b128 v[148:151], v178 offset:5440
	ds_read_b128 v[152:155], v178 offset:6528
	ds_read_b128 v[156:159], v178 offset:7616
	s_add_u32 s74, s66, 0x20000
	s_addc_u32 s75, s67, 0
	s_waitcnt lgkmcnt(7)
	global_store_dwordx4 v180, v[128:131], s[74:75]
	s_add_u32 s74, s66, 0x24000
	s_addc_u32 s75, s67, 0
	s_waitcnt lgkmcnt(6)
	global_store_dwordx4 v180, v[132:135], s[74:75]
	s_add_u32 s74, s66, 0x28000
	s_addc_u32 s75, s67, 0
	s_waitcnt lgkmcnt(5)
	global_store_dwordx4 v180, v[136:139], s[74:75]
	s_add_u32 s74, s66, 0x2c000
	s_addc_u32 s75, s67, 0
	s_waitcnt lgkmcnt(4)
	global_store_dwordx4 v180, v[140:143], s[74:75]
	s_add_u32 s74, s66, 0x30000
	s_addc_u32 s75, s67, 0
	s_waitcnt lgkmcnt(3)
	global_store_dwordx4 v180, v[144:147], s[74:75]
	s_add_u32 s74, s66, 0x34000
	s_addc_u32 s75, s67, 0
	s_waitcnt lgkmcnt(2)
	global_store_dwordx4 v180, v[148:151], s[74:75]
	s_add_u32 s74, s66, 0x38000
	s_addc_u32 s75, s67, 0
	s_waitcnt lgkmcnt(1)
	global_store_dwordx4 v180, v[152:155], s[74:75]
	s_add_u32 s74, s66, 0x3c000
	s_addc_u32 s75, s67, 0
	s_waitcnt lgkmcnt(0)
	global_store_dwordx4 v180, v[156:159], s[74:75]
	global_load_dwordx4 v[128:131], v182, s[70:71]
	global_load_dwordx4 v[132:135], v182, s[70:71] offset:32
	global_load_dwordx4 v[136:139], v182, s[70:71] offset:64
	global_load_dwordx4 v[140:143], v182, s[70:71] offset:96
	global_load_dwordx4 v[144:147], v182, s[70:71] offset:128
	global_load_dwordx4 v[148:151], v182, s[70:71] offset:160
	global_load_dwordx4 v[152:155], v182, s[70:71] offset:192
	global_load_dwordx4 v[156:159], v182, s[70:71] offset:224
	s_waitcnt vmcnt(7)
	v_mul_f32_e32 v48, v128, v48
	v_mul_f32_e32 v49, v129, v49
	v_mul_f32_e32 v50, v130, v50
	v_mul_f32_e32 v51, v131, v51
	v_cvt_pk_bf16_f32 v48, v48, v49
	v_cvt_pk_bf16_f32 v49, v50, v51
	ds_write_b64 v177, v[48:49]
	s_waitcnt vmcnt(6)
	v_mul_f32_e32 v52, v132, v52
	v_mul_f32_e32 v53, v133, v53
	v_mul_f32_e32 v54, v134, v54
	v_mul_f32_e32 v55, v135, v55
	v_cvt_pk_bf16_f32 v52, v52, v53
	v_cvt_pk_bf16_f32 v53, v54, v55
	ds_write_b64 v177, v[52:53] offset:16
	s_waitcnt vmcnt(5)
	v_mul_f32_e32 v56, v136, v56
	v_mul_f32_e32 v57, v137, v57
	v_mul_f32_e32 v58, v138, v58
	v_mul_f32_e32 v59, v139, v59
	v_cvt_pk_bf16_f32 v56, v56, v57
	v_cvt_pk_bf16_f32 v57, v58, v59
	ds_write_b64 v177, v[56:57] offset:32
	s_waitcnt vmcnt(4)
	v_mul_f32_e32 v60, v140, v60
	v_mul_f32_e32 v61, v141, v61
	v_mul_f32_e32 v62, v142, v62
	v_mul_f32_e32 v63, v143, v63
	v_cvt_pk_bf16_f32 v60, v60, v61
	v_cvt_pk_bf16_f32 v61, v62, v63
	ds_write_b64 v177, v[60:61] offset:48
	s_waitcnt vmcnt(3)
	v_mul_f32_e32 v32, v144, v32
	v_mul_f32_e32 v33, v145, v33
	v_mul_f32_e32 v34, v146, v34
	v_mul_f32_e32 v35, v147, v35
	v_cvt_pk_bf16_f32 v32, v32, v33
	v_cvt_pk_bf16_f32 v33, v34, v35
	ds_write_b64 v177, v[32:33] offset:64
	s_waitcnt vmcnt(2)
	v_mul_f32_e32 v36, v148, v36
	v_mul_f32_e32 v37, v149, v37
	v_mul_f32_e32 v38, v150, v38
	v_mul_f32_e32 v39, v151, v39
	v_cvt_pk_bf16_f32 v36, v36, v37
	v_cvt_pk_bf16_f32 v37, v38, v39
	ds_write_b64 v177, v[36:37] offset:80
	s_waitcnt vmcnt(1)
; DI bfr f2bf(float a) { return (bfr)(pack2(a, 0.f) & 0xffffu); }
; DI int crow(int reg, int h) { return (reg & 3) + 8 * (reg >> 2) + 4 * h; }
; template <bool FIRST, bool HAS_H>
; DI void phase_gemm_resid(const Params& p, const bfr* A, const bfr* Wt, const float* gnext, float* ss, char* smem) {
;     ...
; #pragma unroll
;     for (int i = 0; i < 2; ++i) {
; #pragma unroll
;       for (int qh = 0; qh < 2; ++qh) {
;         float rs[8];
; #pragma unroll
;         for (int q = 0; q < 8; ++q) rs[q] = 0.f;
; #pragma unroll
;         for (int jh = 0; jh < 2; ++jh) {
;           float xo[2][8];
; #pragma unroll
;           for (int jj = 0; jj < 2; ++jj)
; #pragma unroll
;             for (int q = 0; q < 8; ++q)
;               xo[jj][q] = xsrc[(rbase + i * 32 + crow(qh * 8 + q, 0)) * 1024 + cbase + (jh * 2 + jj) * 32];
; #pragma unroll
;           for (int q = 0; q < 8; ++q) {
;             const int o = (rbase + i * 32 + crow(qh * 8 + q, 0)) * 1024 + cbase;
; #pragma unroll
;             for (int jj = 0; jj < 2; ++jj) {
;               const int j = jh * 2 + jj;
;               const float xn = xo[jj][q] + acc[i][j][qh * 8 + q];
;               X[o + j * 32] = xn;
;               if (HAS_H) Hn[o + j * 32] = f2bf(xn * gnext[cbase + j * 32]);
;               rs[q] += xn * xn;
;             }
;           }
;         }
	v_mul_f32_e32 v40, v152, v40
	v_mul_f32_e32 v41, v153, v41
	v_mul_f32_e32 v42, v154, v42
	v_mul_f32_e32 v43, v155, v43
	v_cvt_pk_bf16_f32 v40, v40, v41
	v_cvt_pk_bf16_f32 v41, v42, v43
	ds_write_b64 v177, v[40:41] offset:96
	s_waitcnt vmcnt(0)
	v_mul_f32_e32 v44, v156, v44
	v_mul_f32_e32 v45, v157, v45
	v_mul_f32_e32 v46, v158, v46
	v_mul_f32_e32 v47, v159, v47
	v_cvt_pk_bf16_f32 v44, v44, v45
	v_cvt_pk_bf16_f32 v45, v46, v47
	ds_write_b64 v177, v[44:45] offset:112
	ds_read_b128 v[128:131], v179
	ds_read_b128 v[132:135], v179 offset:2176
	ds_read_b128 v[136:139], v179 offset:4352
	ds_read_b128 v[140:143], v179 offset:6528
	s_add_u32 s74, s68, 0x10000
	s_addc_u32 s75, s69, 0
	s_waitcnt lgkmcnt(3)
	global_store_dwordx4 v181, v[128:131], s[74:75]
	s_add_u32 s74, s68, 0x14000
	s_addc_u32 s75, s69, 0
	s_waitcnt lgkmcnt(2)
	global_store_dwordx4 v181, v[132:135], s[74:75]
	s_add_u32 s74, s68, 0x18000
	s_addc_u32 s75, s69, 0
	s_waitcnt lgkmcnt(1)
	global_store_dwordx4 v181, v[136:139], s[74:75]
	s_add_u32 s74, s68, 0x1c000
	s_addc_u32 s75, s69, 0
	s_waitcnt lgkmcnt(0)
	global_store_dwordx4 v181, v[140:143], s[74:75]
	s_add_u32 s74, s64, 0x20100
	s_addc_u32 s75, s65, 0
	global_load_dwordx4 v[128:131], v180, s[74:75]
	s_add_u32 s74, s64, 0x24100
	s_addc_u32 s75, s65, 0
	global_load_dwordx4 v[132:135], v180, s[74:75]
	s_add_u32 s74, s64, 0x28100
	s_addc_u32 s75, s65, 0
	global_load_dwordx4 v[136:139], v180, s[74:75]
	s_add_u32 s74, s64, 0x2c100
	s_addc_u32 s75, s65, 0
	global_load_dwordx4 v[140:143], v180, s[74:75]
	s_add_u32 s74, s64, 0x30100
	s_addc_u32 s75, s65, 0
	global_load_dwordx4 v[144:147], v180, s[74:75]
	s_add_u32 s74, s64, 0x34100
	s_addc_u32 s75, s65, 0
	global_load_dwordx4 v[148:151], v180, s[74:75]
	s_add_u32 s74, s64, 0x38100
	s_addc_u32 s75, s65, 0
	global_load_dwordx4 v[152:155], v180, s[74:75]
	s_add_u32 s74, s64, 0x3c100
	s_addc_u32 s75, s65, 0
	global_load_dwordx4 v[156:159], v180, s[74:75]
	s_waitcnt vmcnt(7)
	ds_write_b128 v178, v[128:131]
	s_waitcnt vmcnt(6)
	ds_write_b128 v178, v[132:135] offset:1088
	s_waitcnt vmcnt(5)
	ds_write_b128 v178, v[136:139] offset:2176
	s_waitcnt vmcnt(4)
	ds_write_b128 v178, v[140:143] offset:3264
	s_waitcnt vmcnt(3)
	ds_write_b128 v178, v[144:147] offset:4352
	s_waitcnt vmcnt(2)
	ds_write_b128 v178, v[148:151] offset:5440
	s_waitcnt vmcnt(1)
	ds_write_b128 v178, v[152:155] offset:6528
	s_waitcnt vmcnt(0)
	ds_write_b128 v178, v[156:159] offset:7616
	ds_read_b128 v[128:131], v176
	ds_read_b128 v[132:135], v176 offset:32
	ds_read_b128 v[136:139], v176 offset:64
	ds_read_b128 v[140:143], v176 offset:96
	ds_read_b128 v[144:147], v176 offset:128
	ds_read_b128 v[148:151], v176 offset:160
	ds_read_b128 v[152:155], v176 offset:192
	ds_read_b128 v[156:159], v176 offset:224
	s_waitcnt lgkmcnt(7)
	v_add_f32_e32 v16, v128, v16
	v_add_f32_e32 v17, v129, v17
	v_add_f32_e32 v18, v130, v18
	v_add_f32_e32 v19, v131, v19
	v_fmac_f32_e32 v184, v16, v16
	v_fmac_f32_e32 v184, v17, v17
	v_fmac_f32_e32 v184, v18, v18
	v_fmac_f32_e32 v184, v19, v19
	ds_write_b128 v176, v[16:19]
	s_waitcnt lgkmcnt(7)
	v_add_f32_e32 v20, v132, v20
	v_add_f32_e32 v21, v133, v21
	v_add_f32_e32 v22, v134, v22
	v_add_f32_e32 v23, v135, v23
	v_fmac_f32_e32 v184, v20, v20
	v_fmac_f32_e32 v184, v21, v21
	v_fmac_f32_e32 v184, v22, v22
	v_fmac_f32_e32 v184, v23, v23
	ds_write_b128 v176, v[20:23] offset:32
	s_waitcnt lgkmcnt(7)
	v_add_f32_e32 v24, v136, v24
	v_add_f32_e32 v25, v137, v25
	v_add_f32_e32 v26, v138, v26
	v_add_f32_e32 v27, v139, v27
	v_fmac_f32_e32 v184, v24, v24
	v_fmac_f32_e32 v184, v25, v25
	v_fmac_f32_e32 v184, v26, v26
	v_fmac_f32_e32 v184, v27, v27
	ds_write_b128 v176, v[24:27] offset:64
	s_waitcnt lgkmcnt(7)
	v_add_f32_e32 v28, v140, v28
	v_add_f32_e32 v29, v141, v29
	v_add_f32_e32 v30, v142, v30
	v_add_f32_e32 v31, v143, v31
	v_fmac_f32_e32 v184, v28, v28
	v_fmac_f32_e32 v184, v29, v29
	v_fmac_f32_e32 v184, v30, v30
	v_fmac_f32_e32 v184, v31, v31
	ds_write_b128 v176, v[28:31] offset:96
	s_waitcnt lgkmcnt(7)
	v_add_f32_e32 v0, v144, v0
	v_add_f32_e32 v1, v145, v1
	v_add_f32_e32 v2, v146, v2
	v_add_f32_e32 v3, v147, v3
	v_fmac_f32_e32 v184, v0, v0
	v_fmac_f32_e32 v184, v1, v1
	v_fmac_f32_e32 v184, v2, v2
	v_fmac_f32_e32 v184, v3, v3
	ds_write_b128 v176, v[0:3] offset:128
	s_waitcnt lgkmcnt(7)
	v_add_f32_e32 v4, v148, v4
	v_add_f32_e32 v5, v149, v5
	v_add_f32_e32 v6, v150, v6
	v_add_f32_e32 v7, v151, v7
	v_fmac_f32_e32 v184, v4, v4
	v_fmac_f32_e32 v184, v5, v5
	v_fmac_f32_e32 v184, v6, v6
	v_fmac_f32_e32 v184, v7, v7
	ds_write_b128 v176, v[4:7] offset:160
	s_waitcnt lgkmcnt(7)
	v_add_f32_e32 v8, v152, v8
	v_add_f32_e32 v9, v153, v9
	v_add_f32_e32 v10, v154, v10
	v_add_f32_e32 v11, v155, v11
	v_fmac_f32_e32 v184, v8, v8
	v_fmac_f32_e32 v184, v9, v9
	v_fmac_f32_e32 v184, v10, v10
	v_fmac_f32_e32 v184, v11, v11
	ds_write_b128 v176, v[8:11] offset:192
	s_waitcnt lgkmcnt(7)
; DI bfr f2bf(float a) { return (bfr)(pack2(a, 0.f) & 0xffffu); }
; DI int crow(int reg, int h) { return (reg & 3) + 8 * (reg >> 2) + 4 * h; }
; template <bool FIRST, bool HAS_H>
; DI void phase_gemm_resid(const Params& p, const bfr* A, const bfr* Wt, const float* gnext, float* ss, char* smem) {
;     ...
;         for (int jh = 0; jh < 2; ++jh) {
;           float xo[2][8];
; #pragma unroll
;           for (int jj = 0; jj < 2; ++jj)
; #pragma unroll
;             for (int q = 0; q < 8; ++q)
;               xo[jj][q] = xsrc[(rbase + i * 32 + crow(qh * 8 + q, 0)) * 1024 + cbase + (jh * 2 + jj) * 32];
; #pragma unroll
;           for (int q = 0; q < 8; ++q) {
;             const int o = (rbase + i * 32 + crow(qh * 8 + q, 0)) * 1024 + cbase;
; #pragma unroll
;             for (int jj = 0; jj < 2; ++jj) {
;               const int j = jh * 2 + jj;
;               const float xn = xo[jj][q] + acc[i][j][qh * 8 + q];
;               X[o + j * 32] = xn;
;               if (HAS_H) Hn[o + j * 32] = f2bf(xn * gnext[cbase + j * 32]);
;               rs[q] += xn * xn;
;             }
;           }
;         }
; #pragma unroll
;         for (int q = 0; q < 8; ++q) rs[q] = half32_sum_hi(rs[q]);
;         if (r == 31) {
; #pragma unroll
;           for (int q = 0; q < 8; ++q) unsafeAtomicAdd(ss + rbase + i * 32 + crow(qh * 8 + q, 0), rs[q]);
;         }
	v_add_f32_e32 v12, v156, v12
	v_add_f32_e32 v13, v157, v13
	v_add_f32_e32 v14, v158, v14
	v_add_f32_e32 v15, v159, v15
	v_fmac_f32_e32 v184, v12, v12
	v_fmac_f32_e32 v184, v13, v13
	v_fmac_f32_e32 v184, v14, v14
	v_fmac_f32_e32 v184, v15, v15
	ds_write_b128 v176, v[12:15] offset:224
	ds_read_b128 v[128:131], v178
	ds_read_b128 v[132:135], v178 offset:1088
	ds_read_b128 v[136:139], v178 offset:2176
	ds_read_b128 v[140:143], v178 offset:3264
	ds_read_b128 v[144:147], v178 offset:4352
	ds_read_b128 v[148:151], v178 offset:5440
	ds_read_b128 v[152:155], v178 offset:6528
	ds_read_b128 v[156:159], v178 offset:7616
	s_add_u32 s74, s66, 0x20100
	s_addc_u32 s75, s67, 0
	s_waitcnt lgkmcnt(7)
	global_store_dwordx4 v180, v[128:131], s[74:75]
	s_add_u32 s74, s66, 0x24100
	s_addc_u32 s75, s67, 0
	s_waitcnt lgkmcnt(6)
	global_store_dwordx4 v180, v[132:135], s[74:75]
	s_add_u32 s74, s66, 0x28100
	s_addc_u32 s75, s67, 0
	s_waitcnt lgkmcnt(5)
	global_store_dwordx4 v180, v[136:139], s[74:75]
	s_add_u32 s74, s66, 0x2c100
	s_addc_u32 s75, s67, 0
	s_waitcnt lgkmcnt(4)
	global_store_dwordx4 v180, v[140:143], s[74:75]
	s_add_u32 s74, s66, 0x30100
	s_addc_u32 s75, s67, 0
	s_waitcnt lgkmcnt(3)
	global_store_dwordx4 v180, v[144:147], s[74:75]
	s_add_u32 s74, s66, 0x34100
	s_addc_u32 s75, s67, 0
	s_waitcnt lgkmcnt(2)
	global_store_dwordx4 v180, v[148:151], s[74:75]
	s_add_u32 s74, s66, 0x38100
	s_addc_u32 s75, s67, 0
	s_waitcnt lgkmcnt(1)
	global_store_dwordx4 v180, v[152:155], s[74:75]
	s_add_u32 s74, s66, 0x3c100
	s_addc_u32 s75, s67, 0
	s_waitcnt lgkmcnt(0)
	global_store_dwordx4 v180, v[156:159], s[74:75]
	global_load_dwordx4 v[128:131], v182, s[70:71] offset:256
	global_load_dwordx4 v[132:135], v182, s[70:71] offset:288
	global_load_dwordx4 v[136:139], v182, s[70:71] offset:320
	global_load_dwordx4 v[140:143], v182, s[70:71] offset:352
	global_load_dwordx4 v[144:147], v182, s[70:71] offset:384
	global_load_dwordx4 v[148:151], v182, s[70:71] offset:416
	global_load_dwordx4 v[152:155], v182, s[70:71] offset:448
	global_load_dwordx4 v[156:159], v182, s[70:71] offset:480
	s_waitcnt vmcnt(7)
	v_mul_f32_e32 v16, v128, v16
	v_mul_f32_e32 v17, v129, v17
	v_mul_f32_e32 v18, v130, v18
	v_mul_f32_e32 v19, v131, v19
	v_cvt_pk_bf16_f32 v16, v16, v17
	v_cvt_pk_bf16_f32 v17, v18, v19
	ds_write_b64 v177, v[16:17]
	s_waitcnt vmcnt(6)
	v_mul_f32_e32 v20, v132, v20
	v_mul_f32_e32 v21, v133, v21
	v_mul_f32_e32 v22, v134, v22
	v_mul_f32_e32 v23, v135, v23
	v_cvt_pk_bf16_f32 v20, v20, v21
	v_cvt_pk_bf16_f32 v21, v22, v23
	ds_write_b64 v177, v[20:21] offset:16
	s_waitcnt vmcnt(5)
	v_mul_f32_e32 v24, v136, v24
	v_mul_f32_e32 v25, v137, v25
	v_mul_f32_e32 v26, v138, v26
	v_mul_f32_e32 v27, v139, v27
	v_cvt_pk_bf16_f32 v24, v24, v25
	v_cvt_pk_bf16_f32 v25, v26, v27
	ds_write_b64 v177, v[24:25] offset:32
	s_waitcnt vmcnt(4)
	v_mul_f32_e32 v28, v140, v28
	v_mul_f32_e32 v29, v141, v29
	v_mul_f32_e32 v30, v142, v30
	v_mul_f32_e32 v31, v143, v31
	v_cvt_pk_bf16_f32 v28, v28, v29
	v_cvt_pk_bf16_f32 v29, v30, v31
	ds_write_b64 v177, v[28:29] offset:48
	s_waitcnt vmcnt(3)
	v_mul_f32_e32 v0, v144, v0
	v_mul_f32_e32 v1, v145, v1
	v_mul_f32_e32 v2, v146, v2
	v_mul_f32_e32 v3, v147, v3
	v_cvt_pk_bf16_f32 v0, v0, v1
	v_cvt_pk_bf16_f32 v1, v2, v3
	ds_write_b64 v177, v[0:1] offset:64
	s_waitcnt vmcnt(2)
	v_mul_f32_e32 v4, v148, v4
	v_mul_f32_e32 v5, v149, v5
	v_mul_f32_e32 v6, v150, v6
	v_mul_f32_e32 v7, v151, v7
	v_cvt_pk_bf16_f32 v4, v4, v5
	v_cvt_pk_bf16_f32 v5, v6, v7
	ds_write_b64 v177, v[4:5] offset:80
	s_waitcnt vmcnt(1)
	v_mul_f32_e32 v8, v152, v8
	v_mul_f32_e32 v9, v153, v9
	v_mul_f32_e32 v10, v154, v10
	v_mul_f32_e32 v11, v155, v11
	v_cvt_pk_bf16_f32 v8, v8, v9
	v_cvt_pk_bf16_f32 v9, v10, v11
	ds_write_b64 v177, v[8:9] offset:96
	s_waitcnt vmcnt(0)
	v_mul_f32_e32 v12, v156, v12
	v_mul_f32_e32 v13, v157, v13
	v_mul_f32_e32 v14, v158, v14
	v_mul_f32_e32 v15, v159, v15
	v_cvt_pk_bf16_f32 v12, v12, v13
	v_cvt_pk_bf16_f32 v13, v14, v15
	ds_write_b64 v177, v[12:13] offset:112
	ds_read_b128 v[128:131], v179
	ds_read_b128 v[132:135], v179 offset:2176
	ds_read_b128 v[136:139], v179 offset:4352
	ds_read_b128 v[140:143], v179 offset:6528
	s_add_u32 s74, s68, 0x10080
	s_addc_u32 s75, s69, 0
	s_waitcnt lgkmcnt(3)
	global_store_dwordx4 v181, v[128:131], s[74:75]
	s_add_u32 s74, s68, 0x14080
	s_addc_u32 s75, s69, 0
	s_waitcnt lgkmcnt(2)
	global_store_dwordx4 v181, v[132:135], s[74:75]
	s_add_u32 s74, s68, 0x18080
	s_addc_u32 s75, s69, 0
	s_waitcnt lgkmcnt(1)
	global_store_dwordx4 v181, v[136:139], s[74:75]
	s_add_u32 s74, s68, 0x1c080
	s_addc_u32 s75, s69, 0
	s_waitcnt lgkmcnt(0)
	global_store_dwordx4 v181, v[140:143], s[74:75]
	s_load_dwordx2 s[64:65], s[92:93], 0x140
	ds_bpermute_b32 v188, v186, v183
	ds_bpermute_b32 v189, v186, v184
	s_waitcnt lgkmcnt(0)
	s_add_u32 s64, s64, 0x10200
	s_addc_u32 s65, s65, 0
	v_add_f32_e32 v188, v188, v183
	v_add_f32_e32 v189, v189, v184
	s_mov_b32 exec_hi, 0
	s_nop 1
	global_atomic_add_f32 v185, v188, s[64:65]
	global_atomic_add_f32 v185, v189, s[64:65] offset:128
	s_mov_b64 exec, -1
	v_readlane_b32 s64, v187, 0
	v_readlane_b32 s65, v187, 1
	v_readlane_b32 s66, v187, 2
	v_readlane_b32 s67, v187, 3
	v_readlane_b32 s68, v187, 4
	v_readlane_b32 s69, v187, 5
	v_readlane_b32 s70, v187, 6
	v_readlane_b32 s71, v187, 7
	v_readlane_b32 s72, v187, 8
	v_readlane_b32 s73, v187, 9
	v_readlane_b32 s74, v187, 10
	v_readlane_b32 s75, v187, 11
	v_readlane_b32 s76, v187, 12
	v_readlane_b32 s77, v187, 13
	v_readlane_b32 s78, v187, 14
	v_readlane_b32 s79, v187, 15
	s_nop 7
	s_branch .LBB0_1096

; #define MFMA32(a, b, c) __builtin_amdgcn_mfma_f32_32x32x16_bf16((a), (b), (c), 0, 0, 0)
; #define GA_LOAD(pr_) do { _Pragma("unroll") for (int i = 0; i < 4; ++i) ra[i] = *(const u32x4*)(Ab + (i * 32) * lda + (pr_) * 64); } while (0)
; #define GB_LOAD(kt_) do { const bfr* bk_ = Bb + (kt_) * NB * 32; \
;     _Pragma("unroll") for (int i = 0; i < 4; ++i) rb[i] = *(const u32x4*)(bk_ + (i * 64) * 32); } while (0)
; #define G_STORE(kt_) do { bfr* as_ = S0 + ((kt_) & 1) * GSTAGE; bfr* bs_ = as_ + 128 * 40; \
;     if (apar == ((kt_) & 1)) { _Pragma("unroll") for (int i = 0; i < 4; ++i) *(u32x4*)(as_ + asoff + i * 32 * 40) = ra[i]; } \
;     _Pragma("unroll") for (int i = 0; i < 4; ++i) *(u32x4*)(bs_ + bsoff + i * 64 * 40) = rb[i]; } while (0)
; template <int lda>
; DI void gemm_mainloop(const bfr* __restrict__ A, const bfr* __restrict__ Bt, int NB, int K, int m0, int n0, char* smem, f32x16 (&acc)[2][4]) {
;     ...
;   for (int kt = 0; kt < nk; ++kt) {
;     if (kt + 1 < nk) G_STORE(kt + 1);
;     if (kt + 2 < nk) {
;       GB_LOAD(kt + 2);
;       if ((kt & 1) == 0) GA_LOAD((kt >> 1) + 1);
;     }
;     const bfr* As = S0 + (kt & 1) * GSTAGE;
;     const bfr* Bs = As + 128 * 40;
; #pragma unroll
;     for (int ks = 0; ks < 2; ++ks) {
;       bf16x8 af[2], bfg[4];
; #pragma unroll
;       for (int i = 0; i < 2; ++i) af[i] = *(const bf16x8*)(As + (wr * 64 + i * 32 + r) * 40 + ks * 16 + hl * 8);
; #pragma unroll
;       for (int j = 0; j < 4; ++j) bfg[j] = *(const bf16x8*)(Bs + (wc * 128 + j * 32 + r) * 40 + ks * 16 + hl * 8);
; #pragma unroll
;       for (int i = 0; i < 2; ++i)
; #pragma unroll
;         for (int j = 0; j < 4; ++j) acc[i][j] = MFMA32(af[i], bfg[j], acc[i][j]);
;     }
;     __syncthreads();
;   }
.Lp15_loop:
	s_waitcnt vmcnt(6)
	s_barrier
	s_mul_i32 s74, s71, 0x6000
	s_add_u32 s75, s74, 0x2000
	s_cmp_eq_u32 s71, 2
	s_cselect_b32 s75, 0x10000, s75
	v_add_u32_e32 v183, s74, v179
	v_add_u32_e32 v185, s75, v181
	v_add_u32_e32 v184, s74, v180
	v_add_u32_e32 v186, s75, v182
	ds_read_b128 v[128:131], v183
	ds_read_b128 v[144:147], v185
	ds_read_b128 v[148:151], v185 offset:2048
	ds_read_b128 v[152:155], v185 offset:4096
	ds_read_b128 v[156:159], v185 offset:6144
	ds_read_b128 v[132:135], v183 offset:2048
	ds_read_b128 v[136:139], v184
	ds_read_b128 v[160:163], v186
	ds_read_b128 v[164:167], v186 offset:2048
	ds_read_b128 v[168:171], v186 offset:4096
	ds_read_b128 v[172:175], v186 offset:6144
	ds_read_b128 v[140:143], v184 offset:2048
	s_add_u32 s71, s71, 1
	s_cmp_eq_u32 s71, 3
	s_cselect_b32 s71, 0, s71
	s_waitcnt lgkmcnt(10)
	v_mfma_f32_32x32x16_bf16 v[112:127], v[144:147], v[128:131], v[112:127]
	s_mul_i32 s74, s70, 0x6000
	s_add_u32 s75, s74, s68
	s_mov_b32 m0, s75
	s_add_u32 s76, s74, 0x2000
	s_cmp_eq_u32 s70, 2
	s_cselect_b32 s76, 0x10000, s76
	global_load_lds_dwordx4 v176, s[64:65]
	s_waitcnt lgkmcnt(9)
	v_mfma_f32_32x32x16_bf16 v[96:111], v[148:151], v[128:131], v[96:111]
	s_add_u32 m0, s75, 0x400
	s_add_u32 s76, s76, s69
	global_load_lds_dwordx4 v177, s[64:65]
	s_waitcnt lgkmcnt(8)
	v_mfma_f32_32x32x16_bf16 v[80:95], v[152:155], v[128:131], v[80:95]
	s_mov_b32 m0, s76
	s_add_u32 s64, s64, 64
	s_addc_u32 s65, s65, 0
	global_load_lds_dwordx4 v178, s[66:67]
	s_waitcnt lgkmcnt(7)
	v_mfma_f32_32x32x16_bf16 v[64:79], v[156:159], v[128:131], v[64:79]
	global_load_lds_dwordx4 v178, s[66:67] offset:1024
	s_waitcnt lgkmcnt(6)
	v_mfma_f32_32x32x16_bf16 v[48:63], v[144:147], v[132:135], v[48:63]
	global_load_lds_dwordx4 v178, s[66:67] offset:2048
	v_mfma_f32_32x32x16_bf16 v[32:47], v[148:151], v[132:135], v[32:47]
	global_load_lds_dwordx4 v178, s[66:67] offset:3072
	s_add_u32 s66, s66, 0x10000
	s_addc_u32 s67, s67, 0
	v_mfma_f32_32x32x16_bf16 v[16:31], v[152:155], v[132:135], v[16:31]
	s_add_u32 s70, s70, 1
	s_cmp_eq_u32 s70, 3
	s_cselect_b32 s70, 0, s70
	v_mfma_f32_32x32x16_bf16 v[0:15], v[156:159], v[132:135], v[0:15]
	s_waitcnt lgkmcnt(4)
	v_mfma_f32_32x32x16_bf16 v[112:127], v[160:163], v[136:139], v[112:127]
	s_waitcnt lgkmcnt(3)
	v_mfma_f32_32x32x16_bf16 v[96:111], v[164:167], v[136:139], v[96:111]
	s_waitcnt lgkmcnt(2)
	v_mfma_f32_32x32x16_bf16 v[80:95], v[168:171], v[136:139], v[80:95]
	s_waitcnt lgkmcnt(1)
	v_mfma_f32_32x32x16_bf16 v[64:79], v[172:175], v[136:139], v[64:79]
	s_waitcnt lgkmcnt(0)
	v_mfma_f32_32x32x16_bf16 v[48:63], v[160:163], v[140:143], v[48:63]
	v_mfma_f32_32x32x16_bf16 v[32:47], v[164:167], v[140:143], v[32:47]
	v_mfma_f32_32x32x16_bf16 v[16:31], v[168:171], v[140:143], v[16:31]
	v_mfma_f32_32x32x16_bf16 v[0:15], v[172:175], v[140:143], v[0:15]
	s_add_u32 s72, s72, 1
	s_cmp_lt_u32 s72, 30
	s_cbranch_scc1 .Lp15_loop
	s_waitcnt vmcnt(6)
	s_barrier
	s_mul_i32 s74, s71, 0x6000
	s_add_u32 s75, s74, 0x2000
	s_cmp_eq_u32 s71, 2
	s_cselect_b32 s75, 0x10000, s75
	v_add_u32_e32 v183, s74, v179
	v_add_u32_e32 v185, s75, v181
	v_add_u32_e32 v184, s74, v180
	v_add_u32_e32 v186, s75, v182
	ds_read_b128 v[128:131], v183
	ds_read_b128 v[144:147], v185
	ds_read_b128 v[148:151], v185 offset:2048
	ds_read_b128 v[152:155], v185 offset:4096
	ds_read_b128 v[156:159], v185 offset:6144
	ds_read_b128 v[132:135], v183 offset:2048
	ds_read_b128 v[136:139], v184
	ds_read_b128 v[160:163], v186
	ds_read_b128 v[164:167], v186 offset:2048
	ds_read_b128 v[168:171], v186 offset:4096
	ds_read_b128 v[172:175], v186 offset:6144
	ds_read_b128 v[140:143], v184 offset:2048
	s_add_u32 s71, s71, 1
	s_cmp_eq_u32 s71, 3
	s_cselect_b32 s71, 0, s71
	s_waitcnt lgkmcnt(10)
	v_mfma_f32_32x32x16_bf16 v[112:127], v[144:147], v[128:131], v[112:127]
	s_waitcnt lgkmcnt(9)
	v_mfma_f32_32x32x16_bf16 v[96:111], v[148:151], v[128:131], v[96:111]
	s_waitcnt lgkmcnt(8)
	v_mfma_f32_32x32x16_bf16 v[80:95], v[152:155], v[128:131], v[80:95]
	s_waitcnt lgkmcnt(7)
	v_mfma_f32_32x32x16_bf16 v[64:79], v[156:159], v[128:131], v[64:79]
	s_waitcnt lgkmcnt(6)
	v_mfma_f32_32x32x16_bf16 v[48:63], v[144:147], v[132:135], v[48:63]
	v_mfma_f32_32x32x16_bf16 v[32:47], v[148:151], v[132:135], v[32:47]
	v_mfma_f32_32x32x16_bf16 v[16:31], v[152:155], v[132:135], v[16:31]
	v_mfma_f32_32x32x16_bf16 v[0:15], v[156:159], v[132:135], v[0:15]
	s_waitcnt lgkmcnt(4)
	v_mfma_f32_32x32x16_bf16 v[112:127], v[160:163], v[136:139], v[112:127]
	s_waitcnt lgkmcnt(3)
	v_mfma_f32_32x32x16_bf16 v[96:111], v[164:167], v[136:139], v[96:111]
	s_waitcnt lgkmcnt(2)
	v_mfma_f32_32x32x16_bf16 v[80:95], v[168:171], v[136:139], v[80:95]
	s_waitcnt lgkmcnt(1)
	v_mfma_f32_32x32x16_bf16 v[64:79], v[172:175], v[136:139], v[64:79]
	s_waitcnt lgkmcnt(0)
	v_mfma_f32_32x32x16_bf16 v[48:63], v[160:163], v[140:143], v[48:63]
	v_mfma_f32_32x32x16_bf16 v[32:47], v[164:167], v[140:143], v[32:47]
	v_mfma_f32_32x32x16_bf16 v[16:31], v[168:171], v[140:143], v[16:31]
	v_mfma_f32_32x32x16_bf16 v[0:15], v[172:175], v[140:143], v[0:15]
	s_waitcnt vmcnt(0)
	s_barrier
; #define MFMA32(a, b, c) __builtin_amdgcn_mfma_f32_32x32x16_bf16((a), (b), (c), 0, 0, 0)
; DI int crow(int reg, int h) { return (reg & 3) + 8 * (reg >> 2) + 4 * h; }
; template <int lda>
; DI void gemm_mainloop(const bfr* __restrict__ A, const bfr* __restrict__ Bt, int NB, int K, int m0, int n0, char* smem, f32x16 (&acc)[2][4]) {
;     ...
;     const bfr* As = S0 + (kt & 1) * GSTAGE;
;     const bfr* Bs = As + 128 * 40;
; #pragma unroll
;     for (int ks = 0; ks < 2; ++ks) {
;       bf16x8 af[2], bfg[4];
; #pragma unroll
;       for (int i = 0; i < 2; ++i) af[i] = *(const bf16x8*)(As + (wr * 64 + i * 32 + r) * 40 + ks * 16 + hl * 8);
; #pragma unroll
;       for (int j = 0; j < 4; ++j) bfg[j] = *(const bf16x8*)(Bs + (wc * 128 + j * 32 + r) * 40 + ks * 16 + hl * 8);
; #pragma unroll
;       for (int i = 0; i < 2; ++i)
; #pragma unroll
;         for (int j = 0; j < 4; ++j) acc[i][j] = MFMA32(af[i], bfg[j], acc[i][j]);
;     }
; template <bool FIRST, bool HAS_H>
; DI void phase_gemm_resid(const Params& p, const bfr* A, const bfr* Wt, const float* gnext, float* ss, char* smem) {
;     ...
;     int tid2 = threadIdx.x;
;     asm volatile("" : "+v"(tid2));
;     const int lane = tid2 & 63, wid = tid2 >> 6, wr = wid >> 1, wc = wid & 1, r = lane & 31, hl = lane >> 5;
;     const float* xsrc = FIRST ? p.x_prompt : X;
;     const int rbase = m0 + wr * 64 + 4 * hl, cbase = n0 + wc * 128 + r;
; #pragma unroll
;     for (int i = 0; i < 2; ++i) {
; #pragma unroll
;       for (int qh = 0; qh < 2; ++qh) {
;         float rs[8];
; #pragma unroll
;         for (int q = 0; q < 8; ++q) rs[q] = 0.f;
; #pragma unroll
;         for (int jh = 0; jh < 2; ++jh) {
;           float xo[2][8];
; #pragma unroll
;           for (int jj = 0; jj < 2; ++jj)
; #pragma unroll
;             for (int q = 0; q < 8; ++q)
;               xo[jj][q] = xsrc[(rbase + i * 32 + crow(qh * 8 + q, 0)) * 1024 + cbase + (jh * 2 + jj) * 32];
	s_mul_i32 s74, s71, 0x6000
	s_add_u32 s75, s74, 0x2000
	s_cmp_eq_u32 s71, 2
	s_cselect_b32 s75, 0x10000, s75
	v_add_u32_e32 v183, s74, v179
	v_add_u32_e32 v185, s75, v181
	v_add_u32_e32 v184, s74, v180
	v_add_u32_e32 v186, s75, v182
	ds_read_b128 v[128:131], v183
	ds_read_b128 v[144:147], v185
	ds_read_b128 v[148:151], v185 offset:2048
	ds_read_b128 v[152:155], v185 offset:4096
	ds_read_b128 v[156:159], v185 offset:6144
	ds_read_b128 v[132:135], v183 offset:2048
	ds_read_b128 v[136:139], v184
	ds_read_b128 v[160:163], v186
	ds_read_b128 v[164:167], v186 offset:2048
	ds_read_b128 v[168:171], v186 offset:4096
	ds_read_b128 v[172:175], v186 offset:6144
	ds_read_b128 v[140:143], v184 offset:2048
	s_add_u32 s71, s71, 1
	s_cmp_eq_u32 s71, 3
	s_cselect_b32 s71, 0, s71
	s_waitcnt lgkmcnt(10)
	v_mfma_f32_32x32x16_bf16 v[112:127], v[144:147], v[128:131], v[112:127]
	s_waitcnt lgkmcnt(9)
	v_mfma_f32_32x32x16_bf16 v[96:111], v[148:151], v[128:131], v[96:111]
	s_waitcnt lgkmcnt(8)
	v_mfma_f32_32x32x16_bf16 v[80:95], v[152:155], v[128:131], v[80:95]
	s_waitcnt lgkmcnt(7)
	v_mfma_f32_32x32x16_bf16 v[64:79], v[156:159], v[128:131], v[64:79]
	s_waitcnt lgkmcnt(6)
	v_mfma_f32_32x32x16_bf16 v[48:63], v[144:147], v[132:135], v[48:63]
	v_mfma_f32_32x32x16_bf16 v[32:47], v[148:151], v[132:135], v[32:47]
	v_mfma_f32_32x32x16_bf16 v[16:31], v[152:155], v[132:135], v[16:31]
	v_mfma_f32_32x32x16_bf16 v[0:15], v[156:159], v[132:135], v[0:15]
	s_waitcnt lgkmcnt(4)
	v_mfma_f32_32x32x16_bf16 v[112:127], v[160:163], v[136:139], v[112:127]
	s_waitcnt lgkmcnt(3)
	v_mfma_f32_32x32x16_bf16 v[96:111], v[164:167], v[136:139], v[96:111]
	s_waitcnt lgkmcnt(2)
	v_mfma_f32_32x32x16_bf16 v[80:95], v[168:171], v[136:139], v[80:95]
	s_waitcnt lgkmcnt(1)
	v_mfma_f32_32x32x16_bf16 v[64:79], v[172:175], v[136:139], v[64:79]
	s_waitcnt lgkmcnt(0)
	v_mfma_f32_32x32x16_bf16 v[48:63], v[160:163], v[140:143], v[48:63]
	v_mfma_f32_32x32x16_bf16 v[32:47], v[164:167], v[140:143], v[32:47]
	v_mfma_f32_32x32x16_bf16 v[16:31], v[168:171], v[140:143], v[16:31]
	v_mfma_f32_32x32x16_bf16 v[0:15], v[172:175], v[140:143], v[0:15]
	s_nop 7
	s_nop 3
	s_barrier
	s_load_dwordx2 s[64:65], s[92:93], 0x100
	s_load_dwordx2 s[66:67], s[92:93], 0x100
	s_load_dwordx2 s[68:69], s[92:93], 0x148
	s_load_dwordx2 s[70:71], s[92:93], 0x50
	s_mul_i32 s76, s73, 8704
	s_lshr_b32 s74, s73, 1
	s_lshl_b32 s74, s74, 6
	s_add_u32 s74, s74, s77
	s_and_b32 s75, s73, 1
	s_lshl_b32 s75, s75, 7
	s_add_u32 s75, s75, s78
	v_and_b32_e32 v188, 31, v196
	v_bfe_u32 v189, v196, 5, 1
	v_mul_u32_u24_e32 v190, 272, v188
	v_add_u32_e32 v190, s76, v190
	v_lshl_add_u32 v176, v189, 4, v190
	v_lshl_add_u32 v177, v189, 3, v190
	v_lshlrev_b32_e32 v190, 2, v189
	v_add_lshl_u32 v182, v190, s75, 2
	v_add_lshl_u32 v185, v188, s74, 2
	v_and_b32_e32 v190, 63, v196
	v_xor_b32_e32 v190, 32, v190
	v_lshlrev_b32_e32 v186, 2, v190
	v_bfe_u32 v188, v196, 4, 2
	v_and_b32_e32 v189, 15, v196
	v_mul_u32_u24_e32 v190, 272, v188
	v_lshl_add_u32 v190, v189, 4, v190
	v_add_u32_e32 v178, s76, v190
	v_add_u32_e32 v190, s74, v188
	v_lshlrev_b32_e32 v190, 10, v190
	v_lshl_add_u32 v190, v189, 2, v190
	v_add_lshl_u32 v180, v190, s75, 2
	v_bfe_u32 v188, v196, 3, 3
	v_and_b32_e32 v189, 7, v196
	v_mul_u32_u24_e32 v190, 272, v188
	v_lshl_add_u32 v190, v189, 4, v190
	v_add_u32_e32 v179, s76, v190
	v_add_u32_e32 v190, s74, v188
	v_lshlrev_b32_e32 v190, 10, v190
	v_lshl_add_u32 v190, v189, 3, v190
	v_add_lshl_u32 v181, v190, s75, 1
	v_mov_b32_e32 v183, 0
	v_mov_b32_e32 v184, 0
	s_waitcnt lgkmcnt(0)
	s_add_u32 s70, s70, 0x1000
	s_addc_u32 s71, s71, 0
	s_add_u32 s74, s64, 0x0
	s_addc_u32 s75, s65, 0
	global_load_dwordx4 v[128:131], v180, s[74:75]
	s_add_u32 s74, s64, 0x4000
	s_addc_u32 s75, s65, 0
	global_load_dwordx4 v[132:135], v180, s[74:75]
	s_add_u32 s74, s64, 0x8000
	s_addc_u32 s75, s65, 0
	global_load_dwordx4 v[136:139], v180, s[74:75]
	s_add_u32 s74, s64, 0xc000
	s_addc_u32 s75, s65, 0
	global_load_dwordx4 v[140:143], v180, s[74:75]
	s_add_u32 s74, s64, 0x10000
	s_addc_u32 s75, s65, 0
	global_load_dwordx4 v[144:147], v180, s[74:75]
	s_add_u32 s74, s64, 0x14000
	s_addc_u32 s75, s65, 0
	global_load_dwordx4 v[148:151], v180, s[74:75]
	s_add_u32 s74, s64, 0x18000
	s_addc_u32 s75, s65, 0
	global_load_dwordx4 v[152:155], v180, s[74:75]
	s_add_u32 s74, s64, 0x1c000
	s_addc_u32 s75, s65, 0
	global_load_dwordx4 v[156:159], v180, s[74:75]
	s_waitcnt vmcnt(7)
	ds_write_b128 v178, v[128:131]
	s_waitcnt vmcnt(6)
	ds_write_b128 v178, v[132:135] offset:1088
	s_waitcnt vmcnt(5)
	ds_write_b128 v178, v[136:139] offset:2176
	s_waitcnt vmcnt(4)
	ds_write_b128 v178, v[140:143] offset:3264
	s_waitcnt vmcnt(3)
	ds_write_b128 v178, v[144:147] offset:4352
	s_waitcnt vmcnt(2)
	ds_write_b128 v178, v[148:151] offset:5440
	s_waitcnt vmcnt(1)
	ds_write_b128 v178, v[152:155] offset:6528
	s_waitcnt vmcnt(0)
	ds_write_b128 v178, v[156:159] offset:7616
	ds_read_b128 v[128:131], v176
	ds_read_b128 v[132:135], v176 offset:32
	ds_read_b128 v[136:139], v176 offset:64
	ds_read_b128 v[140:143], v176 offset:96
	ds_read_b128 v[144:147], v176 offset:128
	ds_read_b128 v[148:151], v176 offset:160
	ds_read_b128 v[152:155], v176 offset:192
	ds_read_b128 v[156:159], v176 offset:224
	s_waitcnt lgkmcnt(7)
	v_add_f32_e32 v112, v128, v112
	v_add_f32_e32 v113, v129, v113
	v_add_f32_e32 v114, v130, v114
	v_add_f32_e32 v115, v131, v115
	v_fmac_f32_e32 v183, v112, v112
	v_fmac_f32_e32 v183, v113, v113
	v_fmac_f32_e32 v183, v114, v114
	v_fmac_f32_e32 v183, v115, v115
	ds_write_b128 v176, v[112:115]
	s_waitcnt lgkmcnt(7)
; DI bfr f2bf(float a) { return (bfr)(pack2(a, 0.f) & 0xffffu); }
; DI int crow(int reg, int h) { return (reg & 3) + 8 * (reg >> 2) + 4 * h; }
; template <bool FIRST, bool HAS_H>
; DI void phase_gemm_resid(const Params& p, const bfr* A, const bfr* Wt, const float* gnext, float* ss, char* smem) {
;     ...
;     const float* xsrc = FIRST ? p.x_prompt : X;
;     const int rbase = m0 + wr * 64 + 4 * hl, cbase = n0 + wc * 128 + r;
; #pragma unroll
;     for (int i = 0; i < 2; ++i) {
; #pragma unroll
;       for (int qh = 0; qh < 2; ++qh) {
;         float rs[8];
; #pragma unroll
;         for (int q = 0; q < 8; ++q) rs[q] = 0.f;
; #pragma unroll
;         for (int jh = 0; jh < 2; ++jh) {
;           float xo[2][8];
; #pragma unroll
;           for (int jj = 0; jj < 2; ++jj)
; #pragma unroll
;             for (int q = 0; q < 8; ++q)
;               xo[jj][q] = xsrc[(rbase + i * 32 + crow(qh * 8 + q, 0)) * 1024 + cbase + (jh * 2 + jj) * 32];
; #pragma unroll
;           for (int q = 0; q < 8; ++q) {
;             const int o = (rbase + i * 32 + crow(qh * 8 + q, 0)) * 1024 + cbase;
; #pragma unroll
;             for (int jj = 0; jj < 2; ++jj) {
;               const int j = jh * 2 + jj;
;               const float xn = xo[jj][q] + acc[i][j][qh * 8 + q];
;               X[o + j * 32] = xn;
;               if (HAS_H) Hn[o + j * 32] = f2bf(xn * gnext[cbase + j * 32]);
;               rs[q] += xn * xn;
	v_add_f32_e32 v116, v132, v116
	v_add_f32_e32 v117, v133, v117
	v_add_f32_e32 v118, v134, v118
	v_add_f32_e32 v119, v135, v119
	v_fmac_f32_e32 v183, v116, v116
	v_fmac_f32_e32 v183, v117, v117
	v_fmac_f32_e32 v183, v118, v118
	v_fmac_f32_e32 v183, v119, v119
	ds_write_b128 v176, v[116:119] offset:32
	s_waitcnt lgkmcnt(7)
	v_add_f32_e32 v120, v136, v120
	v_add_f32_e32 v121, v137, v121
	v_add_f32_e32 v122, v138, v122
	v_add_f32_e32 v123, v139, v123
	v_fmac_f32_e32 v183, v120, v120
	v_fmac_f32_e32 v183, v121, v121
	v_fmac_f32_e32 v183, v122, v122
	v_fmac_f32_e32 v183, v123, v123
	ds_write_b128 v176, v[120:123] offset:64
	s_waitcnt lgkmcnt(7)
	v_add_f32_e32 v124, v140, v124
	v_add_f32_e32 v125, v141, v125
	v_add_f32_e32 v126, v142, v126
	v_add_f32_e32 v127, v143, v127
	v_fmac_f32_e32 v183, v124, v124
	v_fmac_f32_e32 v183, v125, v125
	v_fmac_f32_e32 v183, v126, v126
	v_fmac_f32_e32 v183, v127, v127
	ds_write_b128 v176, v[124:127] offset:96
	s_waitcnt lgkmcnt(7)
	v_add_f32_e32 v96, v144, v96
	v_add_f32_e32 v97, v145, v97
	v_add_f32_e32 v98, v146, v98
	v_add_f32_e32 v99, v147, v99
	v_fmac_f32_e32 v183, v96, v96
	v_fmac_f32_e32 v183, v97, v97
	v_fmac_f32_e32 v183, v98, v98
	v_fmac_f32_e32 v183, v99, v99
	ds_write_b128 v176, v[96:99] offset:128
	s_waitcnt lgkmcnt(7)
	v_add_f32_e32 v100, v148, v100
	v_add_f32_e32 v101, v149, v101
	v_add_f32_e32 v102, v150, v102
	v_add_f32_e32 v103, v151, v103
	v_fmac_f32_e32 v183, v100, v100
	v_fmac_f32_e32 v183, v101, v101
	v_fmac_f32_e32 v183, v102, v102
	v_fmac_f32_e32 v183, v103, v103
	ds_write_b128 v176, v[100:103] offset:160
	s_waitcnt lgkmcnt(7)
	v_add_f32_e32 v104, v152, v104
	v_add_f32_e32 v105, v153, v105
	v_add_f32_e32 v106, v154, v106
	v_add_f32_e32 v107, v155, v107
	v_fmac_f32_e32 v183, v104, v104
	v_fmac_f32_e32 v183, v105, v105
	v_fmac_f32_e32 v183, v106, v106
	v_fmac_f32_e32 v183, v107, v107
	ds_write_b128 v176, v[104:107] offset:192
	s_waitcnt lgkmcnt(7)
	v_add_f32_e32 v108, v156, v108
	v_add_f32_e32 v109, v157, v109
	v_add_f32_e32 v110, v158, v110
	v_add_f32_e32 v111, v159, v111
	v_fmac_f32_e32 v183, v108, v108
	v_fmac_f32_e32 v183, v109, v109
	v_fmac_f32_e32 v183, v110, v110
	v_fmac_f32_e32 v183, v111, v111
	ds_write_b128 v176, v[108:111] offset:224
	ds_read_b128 v[128:131], v178
	ds_read_b128 v[132:135], v178 offset:1088
	ds_read_b128 v[136:139], v178 offset:2176
	ds_read_b128 v[140:143], v178 offset:3264
	ds_read_b128 v[144:147], v178 offset:4352
	ds_read_b128 v[148:151], v178 offset:5440
	ds_read_b128 v[152:155], v178 offset:6528
	ds_read_b128 v[156:159], v178 offset:7616
	s_add_u32 s74, s66, 0x0
	s_addc_u32 s75, s67, 0
	s_waitcnt lgkmcnt(7)
	global_store_dwordx4 v180, v[128:131], s[74:75]
	s_add_u32 s74, s66, 0x4000
	s_addc_u32 s75, s67, 0
	s_waitcnt lgkmcnt(6)
	global_store_dwordx4 v180, v[132:135], s[74:75]
	s_add_u32 s74, s66, 0x8000
	s_addc_u32 s75, s67, 0
	s_waitcnt lgkmcnt(5)
	global_store_dwordx4 v180, v[136:139], s[74:75]
	s_add_u32 s74, s66, 0xc000
	s_addc_u32 s75, s67, 0
	s_waitcnt lgkmcnt(4)
	global_store_dwordx4 v180, v[140:143], s[74:75]
	s_add_u32 s74, s66, 0x10000
	s_addc_u32 s75, s67, 0
	s_waitcnt lgkmcnt(3)
	global_store_dwordx4 v180, v[144:147], s[74:75]
	s_add_u32 s74, s66, 0x14000
	s_addc_u32 s75, s67, 0
	s_waitcnt lgkmcnt(2)
	global_store_dwordx4 v180, v[148:151], s[74:75]
	s_add_u32 s74, s66, 0x18000
	s_addc_u32 s75, s67, 0
	s_waitcnt lgkmcnt(1)
	global_store_dwordx4 v180, v[152:155], s[74:75]
	s_add_u32 s74, s66, 0x1c000
	s_addc_u32 s75, s67, 0
	s_waitcnt lgkmcnt(0)
	global_store_dwordx4 v180, v[156:159], s[74:75]
	global_load_dwordx4 v[128:131], v182, s[70:71]
	global_load_dwordx4 v[132:135], v182, s[70:71] offset:32
	global_load_dwordx4 v[136:139], v182, s[70:71] offset:64
	global_load_dwordx4 v[140:143], v182, s[70:71] offset:96
	global_load_dwordx4 v[144:147], v182, s[70:71] offset:128
	global_load_dwordx4 v[148:151], v182, s[70:71] offset:160
	global_load_dwordx4 v[152:155], v182, s[70:71] offset:192
	global_load_dwordx4 v[156:159], v182, s[70:71] offset:224
	s_waitcnt vmcnt(7)
	v_mul_f32_e32 v112, v128, v112
	v_mul_f32_e32 v113, v129, v113
	v_mul_f32_e32 v114, v130, v114
	v_mul_f32_e32 v115, v131, v115
	v_cvt_pk_bf16_f32 v112, v112, v113
	v_cvt_pk_bf16_f32 v113, v114, v115
	ds_write_b64 v177, v[112:113]
	s_waitcnt vmcnt(6)
	v_mul_f32_e32 v116, v132, v116
	v_mul_f32_e32 v117, v133, v117
	v_mul_f32_e32 v118, v134, v118
	v_mul_f32_e32 v119, v135, v119
	v_cvt_pk_bf16_f32 v116, v116, v117
	v_cvt_pk_bf16_f32 v117, v118, v119
	ds_write_b64 v177, v[116:117] offset:16
	s_waitcnt vmcnt(5)
	v_mul_f32_e32 v120, v136, v120
	v_mul_f32_e32 v121, v137, v121
	v_mul_f32_e32 v122, v138, v122
	v_mul_f32_e32 v123, v139, v123
	v_cvt_pk_bf16_f32 v120, v120, v121
	v_cvt_pk_bf16_f32 v121, v122, v123
	ds_write_b64 v177, v[120:121] offset:32
	s_waitcnt vmcnt(4)
	v_mul_f32_e32 v124, v140, v124
	v_mul_f32_e32 v125, v141, v125
	v_mul_f32_e32 v126, v142, v126
	v_mul_f32_e32 v127, v143, v127
	v_cvt_pk_bf16_f32 v124, v124, v125
	v_cvt_pk_bf16_f32 v125, v126, v127
	ds_write_b64 v177, v[124:125] offset:48
	s_waitcnt vmcnt(3)
	v_mul_f32_e32 v96, v144, v96
	v_mul_f32_e32 v97, v145, v97
	v_mul_f32_e32 v98, v146, v98
	v_mul_f32_e32 v99, v147, v99
	v_cvt_pk_bf16_f32 v96, v96, v97
	v_cvt_pk_bf16_f32 v97, v98, v99
	ds_write_b64 v177, v[96:97] offset:64
	s_waitcnt vmcnt(2)
	v_mul_f32_e32 v100, v148, v100
	v_mul_f32_e32 v101, v149, v101
	v_mul_f32_e32 v102, v150, v102
	v_mul_f32_e32 v103, v151, v103
	v_cvt_pk_bf16_f32 v100, v100, v101
	v_cvt_pk_bf16_f32 v101, v102, v103
	ds_write_b64 v177, v[100:101] offset:80
	s_waitcnt vmcnt(1)
; DI bfr f2bf(float a) { return (bfr)(pack2(a, 0.f) & 0xffffu); }
; DI int crow(int reg, int h) { return (reg & 3) + 8 * (reg >> 2) + 4 * h; }
; template <bool FIRST, bool HAS_H>
; DI void phase_gemm_resid(const Params& p, const bfr* A, const bfr* Wt, const float* gnext, float* ss, char* smem) {
;     ...
;         for (int jh = 0; jh < 2; ++jh) {
;           float xo[2][8];
; #pragma unroll
;           for (int jj = 0; jj < 2; ++jj)
; #pragma unroll
;             for (int q = 0; q < 8; ++q)
;               xo[jj][q] = xsrc[(rbase + i * 32 + crow(qh * 8 + q, 0)) * 1024 + cbase + (jh * 2 + jj) * 32];
; #pragma unroll
;           for (int q = 0; q < 8; ++q) {
;             const int o = (rbase + i * 32 + crow(qh * 8 + q, 0)) * 1024 + cbase;
; #pragma unroll
;             for (int jj = 0; jj < 2; ++jj) {
;               const int j = jh * 2 + jj;
;               const float xn = xo[jj][q] + acc[i][j][qh * 8 + q];
;               X[o + j * 32] = xn;
;               if (HAS_H) Hn[o + j * 32] = f2bf(xn * gnext[cbase + j * 32]);
;               rs[q] += xn * xn;
	v_mul_f32_e32 v104, v152, v104
	v_mul_f32_e32 v105, v153, v105
	v_mul_f32_e32 v106, v154, v106
	v_mul_f32_e32 v107, v155, v107
	v_cvt_pk_bf16_f32 v104, v104, v105
	v_cvt_pk_bf16_f32 v105, v106, v107
	ds_write_b64 v177, v[104:105] offset:96
	s_waitcnt vmcnt(0)
	v_mul_f32_e32 v108, v156, v108
	v_mul_f32_e32 v109, v157, v109
	v_mul_f32_e32 v110, v158, v110
	v_mul_f32_e32 v111, v159, v111
	v_cvt_pk_bf16_f32 v108, v108, v109
	v_cvt_pk_bf16_f32 v109, v110, v111
	ds_write_b64 v177, v[108:109] offset:112
	ds_read_b128 v[128:131], v179
	ds_read_b128 v[132:135], v179 offset:2176
	ds_read_b128 v[136:139], v179 offset:4352
	ds_read_b128 v[140:143], v179 offset:6528
	s_add_u32 s74, s68, 0x0
	s_addc_u32 s75, s69, 0
	s_waitcnt lgkmcnt(3)
	global_store_dwordx4 v181, v[128:131], s[74:75]
	s_add_u32 s74, s68, 0x4000
	s_addc_u32 s75, s69, 0
	s_waitcnt lgkmcnt(2)
	global_store_dwordx4 v181, v[132:135], s[74:75]
	s_add_u32 s74, s68, 0x8000
	s_addc_u32 s75, s69, 0
	s_waitcnt lgkmcnt(1)
	global_store_dwordx4 v181, v[136:139], s[74:75]
	s_add_u32 s74, s68, 0xc000
	s_addc_u32 s75, s69, 0
	s_waitcnt lgkmcnt(0)
	global_store_dwordx4 v181, v[140:143], s[74:75]
	s_add_u32 s74, s64, 0x100
	s_addc_u32 s75, s65, 0
	global_load_dwordx4 v[128:131], v180, s[74:75]
	s_add_u32 s74, s64, 0x4100
	s_addc_u32 s75, s65, 0
	global_load_dwordx4 v[132:135], v180, s[74:75]
	s_add_u32 s74, s64, 0x8100
	s_addc_u32 s75, s65, 0
	global_load_dwordx4 v[136:139], v180, s[74:75]
	s_add_u32 s74, s64, 0xc100
	s_addc_u32 s75, s65, 0
	global_load_dwordx4 v[140:143], v180, s[74:75]
	s_add_u32 s74, s64, 0x10100
	s_addc_u32 s75, s65, 0
	global_load_dwordx4 v[144:147], v180, s[74:75]
	s_add_u32 s74, s64, 0x14100
	s_addc_u32 s75, s65, 0
	global_load_dwordx4 v[148:151], v180, s[74:75]
	s_add_u32 s74, s64, 0x18100
	s_addc_u32 s75, s65, 0
	global_load_dwordx4 v[152:155], v180, s[74:75]
	s_add_u32 s74, s64, 0x1c100
	s_addc_u32 s75, s65, 0
	global_load_dwordx4 v[156:159], v180, s[74:75]
	s_waitcnt vmcnt(7)
	ds_write_b128 v178, v[128:131]
	s_waitcnt vmcnt(6)
	ds_write_b128 v178, v[132:135] offset:1088
	s_waitcnt vmcnt(5)
	ds_write_b128 v178, v[136:139] offset:2176
	s_waitcnt vmcnt(4)
	ds_write_b128 v178, v[140:143] offset:3264
	s_waitcnt vmcnt(3)
	ds_write_b128 v178, v[144:147] offset:4352
	s_waitcnt vmcnt(2)
	ds_write_b128 v178, v[148:151] offset:5440
	s_waitcnt vmcnt(1)
	ds_write_b128 v178, v[152:155] offset:6528
	s_waitcnt vmcnt(0)
	ds_write_b128 v178, v[156:159] offset:7616
	ds_read_b128 v[128:131], v176
	ds_read_b128 v[132:135], v176 offset:32
	ds_read_b128 v[136:139], v176 offset:64
	ds_read_b128 v[140:143], v176 offset:96
	ds_read_b128 v[144:147], v176 offset:128
	ds_read_b128 v[148:151], v176 offset:160
	ds_read_b128 v[152:155], v176 offset:192
	ds_read_b128 v[156:159], v176 offset:224
	s_waitcnt lgkmcnt(7)
	v_add_f32_e32 v80, v128, v80
	v_add_f32_e32 v81, v129, v81
	v_add_f32_e32 v82, v130, v82
	v_add_f32_e32 v83, v131, v83
	v_fmac_f32_e32 v183, v80, v80
	v_fmac_f32_e32 v183, v81, v81
	v_fmac_f32_e32 v183, v82, v82
	v_fmac_f32_e32 v183, v83, v83
	ds_write_b128 v176, v[80:83]
	s_waitcnt lgkmcnt(7)
	v_add_f32_e32 v84, v132, v84
	v_add_f32_e32 v85, v133, v85
	v_add_f32_e32 v86, v134, v86
	v_add_f32_e32 v87, v135, v87
	v_fmac_f32_e32 v183, v84, v84
	v_fmac_f32_e32 v183, v85, v85
	v_fmac_f32_e32 v183, v86, v86
	v_fmac_f32_e32 v183, v87, v87
	ds_write_b128 v176, v[84:87] offset:32
	s_waitcnt lgkmcnt(7)
	v_add_f32_e32 v88, v136, v88
	v_add_f32_e32 v89, v137, v89
	v_add_f32_e32 v90, v138, v90
	v_add_f32_e32 v91, v139, v91
	v_fmac_f32_e32 v183, v88, v88
	v_fmac_f32_e32 v183, v89, v89
	v_fmac_f32_e32 v183, v90, v90
	v_fmac_f32_e32 v183, v91, v91
	ds_write_b128 v176, v[88:91] offset:64
	s_waitcnt lgkmcnt(7)
	v_add_f32_e32 v92, v140, v92
	v_add_f32_e32 v93, v141, v93
	v_add_f32_e32 v94, v142, v94
	v_add_f32_e32 v95, v143, v95
	v_fmac_f32_e32 v183, v92, v92
	v_fmac_f32_e32 v183, v93, v93
	v_fmac_f32_e32 v183, v94, v94
	v_fmac_f32_e32 v183, v95, v95
	ds_write_b128 v176, v[92:95] offset:96
	s_waitcnt lgkmcnt(7)
	v_add_f32_e32 v64, v144, v64
	v_add_f32_e32 v65, v145, v65
	v_add_f32_e32 v66, v146, v66
	v_add_f32_e32 v67, v147, v67
	v_fmac_f32_e32 v183, v64, v64
	v_fmac_f32_e32 v183, v65, v65
	v_fmac_f32_e32 v183, v66, v66
	v_fmac_f32_e32 v183, v67, v67
	ds_write_b128 v176, v[64:67] offset:128
	s_waitcnt lgkmcnt(7)
	v_add_f32_e32 v68, v148, v68
	v_add_f32_e32 v69, v149, v69
	v_add_f32_e32 v70, v150, v70
	v_add_f32_e32 v71, v151, v71
	v_fmac_f32_e32 v183, v68, v68
	v_fmac_f32_e32 v183, v69, v69
	v_fmac_f32_e32 v183, v70, v70
	v_fmac_f32_e32 v183, v71, v71
	ds_write_b128 v176, v[68:71] offset:160
	s_waitcnt lgkmcnt(7)
	v_add_f32_e32 v72, v152, v72
	v_add_f32_e32 v73, v153, v73
	v_add_f32_e32 v74, v154, v74
	v_add_f32_e32 v75, v155, v75
	v_fmac_f32_e32 v183, v72, v72
	v_fmac_f32_e32 v183, v73, v73
	v_fmac_f32_e32 v183, v74, v74
	v_fmac_f32_e32 v183, v75, v75
	ds_write_b128 v176, v[72:75] offset:192
	s_waitcnt lgkmcnt(7)
	v_add_f32_e32 v76, v156, v76
	v_add_f32_e32 v77, v157, v77
	v_add_f32_e32 v78, v158, v78
	v_add_f32_e32 v79, v159, v79
	v_fmac_f32_e32 v183, v76, v76
	v_fmac_f32_e32 v183, v77, v77
	v_fmac_f32_e32 v183, v78, v78
	v_fmac_f32_e32 v183, v79, v79
	ds_write_b128 v176, v[76:79] offset:224
	ds_read_b128 v[128:131], v178
	ds_read_b128 v[132:135], v178 offset:1088
	ds_read_b128 v[136:139], v178 offset:2176
	ds_read_b128 v[140:143], v178 offset:3264
	ds_read_b128 v[144:147], v178 offset:4352
	ds_read_b128 v[148:151], v178 offset:5440
	ds_read_b128 v[152:155], v178 offset:6528
	ds_read_b128 v[156:159], v178 offset:7616
	s_add_u32 s74, s66, 0x100
	s_addc_u32 s75, s67, 0
	s_waitcnt lgkmcnt(7)
; DI bfr f2bf(float a) { return (bfr)(pack2(a, 0.f) & 0xffffu); }
; DI int crow(int reg, int h) { return (reg & 3) + 8 * (reg >> 2) + 4 * h; }
; template <bool FIRST, bool HAS_H>
; DI void phase_gemm_resid(const Params& p, const bfr* A, const bfr* Wt, const float* gnext, float* ss, char* smem) {
;     ...
;         for (int jh = 0; jh < 2; ++jh) {
;           float xo[2][8];
; #pragma unroll
;           for (int jj = 0; jj < 2; ++jj)
; #pragma unroll
;             for (int q = 0; q < 8; ++q)
;               xo[jj][q] = xsrc[(rbase + i * 32 + crow(qh * 8 + q, 0)) * 1024 + cbase + (jh * 2 + jj) * 32];
; #pragma unroll
;           for (int q = 0; q < 8; ++q) {
;             const int o = (rbase + i * 32 + crow(qh * 8 + q, 0)) * 1024 + cbase;
; #pragma unroll
;             for (int jj = 0; jj < 2; ++jj) {
;               const int j = jh * 2 + jj;
;               const float xn = xo[jj][q] + acc[i][j][qh * 8 + q];
;               X[o + j * 32] = xn;
;               if (HAS_H) Hn[o + j * 32] = f2bf(xn * gnext[cbase + j * 32]);
;               rs[q] += xn * xn;
	global_store_dwordx4 v180, v[128:131], s[74:75]
	s_add_u32 s74, s66, 0x4100
	s_addc_u32 s75, s67, 0
	s_waitcnt lgkmcnt(6)
	global_store_dwordx4 v180, v[132:135], s[74:75]
	s_add_u32 s74, s66, 0x8100
	s_addc_u32 s75, s67, 0
	s_waitcnt lgkmcnt(5)
	global_store_dwordx4 v180, v[136:139], s[74:75]
	s_add_u32 s74, s66, 0xc100
	s_addc_u32 s75, s67, 0
	s_waitcnt lgkmcnt(4)
	global_store_dwordx4 v180, v[140:143], s[74:75]
	s_add_u32 s74, s66, 0x10100
	s_addc_u32 s75, s67, 0
	s_waitcnt lgkmcnt(3)
	global_store_dwordx4 v180, v[144:147], s[74:75]
	s_add_u32 s74, s66, 0x14100
	s_addc_u32 s75, s67, 0
	s_waitcnt lgkmcnt(2)
	global_store_dwordx4 v180, v[148:151], s[74:75]
	s_add_u32 s74, s66, 0x18100
	s_addc_u32 s75, s67, 0
	s_waitcnt lgkmcnt(1)
	global_store_dwordx4 v180, v[152:155], s[74:75]
	s_add_u32 s74, s66, 0x1c100
	s_addc_u32 s75, s67, 0
	s_waitcnt lgkmcnt(0)
	global_store_dwordx4 v180, v[156:159], s[74:75]
	global_load_dwordx4 v[128:131], v182, s[70:71] offset:256
	global_load_dwordx4 v[132:135], v182, s[70:71] offset:288
	global_load_dwordx4 v[136:139], v182, s[70:71] offset:320
	global_load_dwordx4 v[140:143], v182, s[70:71] offset:352
	global_load_dwordx4 v[144:147], v182, s[70:71] offset:384
	global_load_dwordx4 v[148:151], v182, s[70:71] offset:416
	global_load_dwordx4 v[152:155], v182, s[70:71] offset:448
	global_load_dwordx4 v[156:159], v182, s[70:71] offset:480
	s_waitcnt vmcnt(7)
	v_mul_f32_e32 v80, v128, v80
	v_mul_f32_e32 v81, v129, v81
	v_mul_f32_e32 v82, v130, v82
	v_mul_f32_e32 v83, v131, v83
	v_cvt_pk_bf16_f32 v80, v80, v81
	v_cvt_pk_bf16_f32 v81, v82, v83
	ds_write_b64 v177, v[80:81]
	s_waitcnt vmcnt(6)
	v_mul_f32_e32 v84, v132, v84
	v_mul_f32_e32 v85, v133, v85
	v_mul_f32_e32 v86, v134, v86
	v_mul_f32_e32 v87, v135, v87
	v_cvt_pk_bf16_f32 v84, v84, v85
	v_cvt_pk_bf16_f32 v85, v86, v87
	ds_write_b64 v177, v[84:85] offset:16
	s_waitcnt vmcnt(5)
	v_mul_f32_e32 v88, v136, v88
	v_mul_f32_e32 v89, v137, v89
	v_mul_f32_e32 v90, v138, v90
	v_mul_f32_e32 v91, v139, v91
	v_cvt_pk_bf16_f32 v88, v88, v89
	v_cvt_pk_bf16_f32 v89, v90, v91
	ds_write_b64 v177, v[88:89] offset:32
	s_waitcnt vmcnt(4)
	v_mul_f32_e32 v92, v140, v92
	v_mul_f32_e32 v93, v141, v93
	v_mul_f32_e32 v94, v142, v94
	v_mul_f32_e32 v95, v143, v95
	v_cvt_pk_bf16_f32 v92, v92, v93
	v_cvt_pk_bf16_f32 v93, v94, v95
	ds_write_b64 v177, v[92:93] offset:48
	s_waitcnt vmcnt(3)
	v_mul_f32_e32 v64, v144, v64
	v_mul_f32_e32 v65, v145, v65
	v_mul_f32_e32 v66, v146, v66
	v_mul_f32_e32 v67, v147, v67
	v_cvt_pk_bf16_f32 v64, v64, v65
	v_cvt_pk_bf16_f32 v65, v66, v67
	ds_write_b64 v177, v[64:65] offset:64
	s_waitcnt vmcnt(2)
	v_mul_f32_e32 v68, v148, v68
	v_mul_f32_e32 v69, v149, v69
	v_mul_f32_e32 v70, v150, v70
	v_mul_f32_e32 v71, v151, v71
	v_cvt_pk_bf16_f32 v68, v68, v69
	v_cvt_pk_bf16_f32 v69, v70, v71
	ds_write_b64 v177, v[68:69] offset:80
	s_waitcnt vmcnt(1)
	v_mul_f32_e32 v72, v152, v72
	v_mul_f32_e32 v73, v153, v73
	v_mul_f32_e32 v74, v154, v74
	v_mul_f32_e32 v75, v155, v75
	v_cvt_pk_bf16_f32 v72, v72, v73
	v_cvt_pk_bf16_f32 v73, v74, v75
	ds_write_b64 v177, v[72:73] offset:96
	s_waitcnt vmcnt(0)
	v_mul_f32_e32 v76, v156, v76
	v_mul_f32_e32 v77, v157, v77
	v_mul_f32_e32 v78, v158, v78
	v_mul_f32_e32 v79, v159, v79
	v_cvt_pk_bf16_f32 v76, v76, v77
	v_cvt_pk_bf16_f32 v77, v78, v79
	ds_write_b64 v177, v[76:77] offset:112
	ds_read_b128 v[128:131], v179
	ds_read_b128 v[132:135], v179 offset:2176
	ds_read_b128 v[136:139], v179 offset:4352
	ds_read_b128 v[140:143], v179 offset:6528
	s_add_u32 s74, s68, 0x80
	s_addc_u32 s75, s69, 0
	s_waitcnt lgkmcnt(3)
	global_store_dwordx4 v181, v[128:131], s[74:75]
	s_add_u32 s74, s68, 0x4080
	s_addc_u32 s75, s69, 0
	s_waitcnt lgkmcnt(2)
	global_store_dwordx4 v181, v[132:135], s[74:75]
	s_add_u32 s74, s68, 0x8080
	s_addc_u32 s75, s69, 0
	s_waitcnt lgkmcnt(1)
	global_store_dwordx4 v181, v[136:139], s[74:75]
	s_add_u32 s74, s68, 0xc080
	s_addc_u32 s75, s69, 0
	s_waitcnt lgkmcnt(0)
	global_store_dwordx4 v181, v[140:143], s[74:75]
	s_add_u32 s74, s64, 0x20000
	s_addc_u32 s75, s65, 0
	global_load_dwordx4 v[128:131], v180, s[74:75]
	s_add_u32 s74, s64, 0x24000
	s_addc_u32 s75, s65, 0
	global_load_dwordx4 v[132:135], v180, s[74:75]
	s_add_u32 s74, s64, 0x28000
	s_addc_u32 s75, s65, 0
	global_load_dwordx4 v[136:139], v180, s[74:75]
	s_add_u32 s74, s64, 0x2c000
	s_addc_u32 s75, s65, 0
	global_load_dwordx4 v[140:143], v180, s[74:75]
	s_add_u32 s74, s64, 0x30000
	s_addc_u32 s75, s65, 0
	global_load_dwordx4 v[144:147], v180, s[74:75]
	s_add_u32 s74, s64, 0x34000
	s_addc_u32 s75, s65, 0
	global_load_dwordx4 v[148:151], v180, s[74:75]
	s_add_u32 s74, s64, 0x38000
	s_addc_u32 s75, s65, 0
	global_load_dwordx4 v[152:155], v180, s[74:75]
	s_add_u32 s74, s64, 0x3c000
	s_addc_u32 s75, s65, 0
	global_load_dwordx4 v[156:159], v180, s[74:75]
	s_waitcnt vmcnt(7)
	ds_write_b128 v178, v[128:131]
	s_waitcnt vmcnt(6)
	ds_write_b128 v178, v[132:135] offset:1088
	s_waitcnt vmcnt(5)
	ds_write_b128 v178, v[136:139] offset:2176
	s_waitcnt vmcnt(4)
	ds_write_b128 v178, v[140:143] offset:3264
	s_waitcnt vmcnt(3)
	ds_write_b128 v178, v[144:147] offset:4352
	s_waitcnt vmcnt(2)
	ds_write_b128 v178, v[148:151] offset:5440
	s_waitcnt vmcnt(1)
	ds_write_b128 v178, v[152:155] offset:6528
	s_waitcnt vmcnt(0)
	ds_write_b128 v178, v[156:159] offset:7616
	ds_read_b128 v[128:131], v176
	ds_read_b128 v[132:135], v176 offset:32
	ds_read_b128 v[136:139], v176 offset:64
	ds_read_b128 v[140:143], v176 offset:96
	ds_read_b128 v[144:147], v176 offset:128
	ds_read_b128 v[148:151], v176 offset:160
	ds_read_b128 v[152:155], v176 offset:192
	ds_read_b128 v[156:159], v176 offset:224
	s_waitcnt lgkmcnt(7)
; DI bfr f2bf(float a) { return (bfr)(pack2(a, 0.f) & 0xffffu); }
; DI int crow(int reg, int h) { return (reg & 3) + 8 * (reg >> 2) + 4 * h; }
; template <bool FIRST, bool HAS_H>
; DI void phase_gemm_resid(const Params& p, const bfr* A, const bfr* Wt, const float* gnext, float* ss, char* smem) {
;     ...
;         for (int jh = 0; jh < 2; ++jh) {
;           float xo[2][8];
; #pragma unroll
;           for (int jj = 0; jj < 2; ++jj)
; #pragma unroll
;             for (int q = 0; q < 8; ++q)
;               xo[jj][q] = xsrc[(rbase + i * 32 + crow(qh * 8 + q, 0)) * 1024 + cbase + (jh * 2 + jj) * 32];
; #pragma unroll
;           for (int q = 0; q < 8; ++q) {
;             const int o = (rbase + i * 32 + crow(qh * 8 + q, 0)) * 1024 + cbase;
; #pragma unroll
;             for (int jj = 0; jj < 2; ++jj) {
;               const int j = jh * 2 + jj;
;               const float xn = xo[jj][q] + acc[i][j][qh * 8 + q];
;               X[o + j * 32] = xn;
;               if (HAS_H) Hn[o + j * 32] = f2bf(xn * gnext[cbase + j * 32]);
;               rs[q] += xn * xn;
	v_add_f32_e32 v48, v128, v48
	v_add_f32_e32 v49, v129, v49
	v_add_f32_e32 v50, v130, v50
	v_add_f32_e32 v51, v131, v51
	v_fmac_f32_e32 v184, v48, v48
	v_fmac_f32_e32 v184, v49, v49
	v_fmac_f32_e32 v184, v50, v50
	v_fmac_f32_e32 v184, v51, v51
	ds_write_b128 v176, v[48:51]
	s_waitcnt lgkmcnt(7)
	v_add_f32_e32 v52, v132, v52
	v_add_f32_e32 v53, v133, v53
	v_add_f32_e32 v54, v134, v54
	v_add_f32_e32 v55, v135, v55
	v_fmac_f32_e32 v184, v52, v52
	v_fmac_f32_e32 v184, v53, v53
	v_fmac_f32_e32 v184, v54, v54
	v_fmac_f32_e32 v184, v55, v55
	ds_write_b128 v176, v[52:55] offset:32
	s_waitcnt lgkmcnt(7)
	v_add_f32_e32 v56, v136, v56
	v_add_f32_e32 v57, v137, v57
	v_add_f32_e32 v58, v138, v58
	v_add_f32_e32 v59, v139, v59
	v_fmac_f32_e32 v184, v56, v56
	v_fmac_f32_e32 v184, v57, v57
	v_fmac_f32_e32 v184, v58, v58
	v_fmac_f32_e32 v184, v59, v59
	ds_write_b128 v176, v[56:59] offset:64
	s_waitcnt lgkmcnt(7)
	v_add_f32_e32 v60, v140, v60
	v_add_f32_e32 v61, v141, v61
	v_add_f32_e32 v62, v142, v62
	v_add_f32_e32 v63, v143, v63
	v_fmac_f32_e32 v184, v60, v60
	v_fmac_f32_e32 v184, v61, v61
	v_fmac_f32_e32 v184, v62, v62
	v_fmac_f32_e32 v184, v63, v63
	ds_write_b128 v176, v[60:63] offset:96
	s_waitcnt lgkmcnt(7)
	v_add_f32_e32 v32, v144, v32
	v_add_f32_e32 v33, v145, v33
	v_add_f32_e32 v34, v146, v34
	v_add_f32_e32 v35, v147, v35
	v_fmac_f32_e32 v184, v32, v32
	v_fmac_f32_e32 v184, v33, v33
	v_fmac_f32_e32 v184, v34, v34
	v_fmac_f32_e32 v184, v35, v35
	ds_write_b128 v176, v[32:35] offset:128
	s_waitcnt lgkmcnt(7)
	v_add_f32_e32 v36, v148, v36
	v_add_f32_e32 v37, v149, v37
	v_add_f32_e32 v38, v150, v38
	v_add_f32_e32 v39, v151, v39
	v_fmac_f32_e32 v184, v36, v36
	v_fmac_f32_e32 v184, v37, v37
	v_fmac_f32_e32 v184, v38, v38
	v_fmac_f32_e32 v184, v39, v39
	ds_write_b128 v176, v[36:39] offset:160
	s_waitcnt lgkmcnt(7)
	v_add_f32_e32 v40, v152, v40
	v_add_f32_e32 v41, v153, v41
	v_add_f32_e32 v42, v154, v42
	v_add_f32_e32 v43, v155, v43
	v_fmac_f32_e32 v184, v40, v40
	v_fmac_f32_e32 v184, v41, v41
	v_fmac_f32_e32 v184, v42, v42
	v_fmac_f32_e32 v184, v43, v43
	ds_write_b128 v176, v[40:43] offset:192
	s_waitcnt lgkmcnt(7)
	v_add_f32_e32 v44, v156, v44
	v_add_f32_e32 v45, v157, v45
	v_add_f32_e32 v46, v158, v46
	v_add_f32_e32 v47, v159, v47
	v_fmac_f32_e32 v184, v44, v44
	v_fmac_f32_e32 v184, v45, v45
	v_fmac_f32_e32 v184, v46, v46
	v_fmac_f32_e32 v184, v47, v47
	ds_write_b128 v176, v[44:47] offset:224
	ds_read_b128 v[128:131], v178
	ds_read_b128 v[132:135], v178 offset:1088
	ds_read_b128 v[136:139], v178 offset:2176
	ds_read_b128 v[140:143], v178 offset:3264
	ds_read_b128 v[144:147], v178 offset:4352
	ds_read_b128 v[148:151], v178 offset:5440
	ds_read_b128 v[152:155], v178 offset:6528
	ds_read_b128 v[156:159], v178 offset:7616
	s_add_u32 s74, s66, 0x20000
	s_addc_u32 s75, s67, 0
	s_waitcnt lgkmcnt(7)
	global_store_dwordx4 v180, v[128:131], s[74:75]
	s_add_u32 s74, s66, 0x24000
	s_addc_u32 s75, s67, 0
	s_waitcnt lgkmcnt(6)
	global_store_dwordx4 v180, v[132:135], s[74:75]
	s_add_u32 s74, s66, 0x28000
	s_addc_u32 s75, s67, 0
	s_waitcnt lgkmcnt(5)
	global_store_dwordx4 v180, v[136:139], s[74:75]
	s_add_u32 s74, s66, 0x2c000
	s_addc_u32 s75, s67, 0
	s_waitcnt lgkmcnt(4)
	global_store_dwordx4 v180, v[140:143], s[74:75]
	s_add_u32 s74, s66, 0x30000
	s_addc_u32 s75, s67, 0
	s_waitcnt lgkmcnt(3)
	global_store_dwordx4 v180, v[144:147], s[74:75]
	s_add_u32 s74, s66, 0x34000
	s_addc_u32 s75, s67, 0
	s_waitcnt lgkmcnt(2)
	global_store_dwordx4 v180, v[148:151], s[74:75]
	s_add_u32 s74, s66, 0x38000
	s_addc_u32 s75, s67, 0
	s_waitcnt lgkmcnt(1)
	global_store_dwordx4 v180, v[152:155], s[74:75]
	s_add_u32 s74, s66, 0x3c000
	s_addc_u32 s75, s67, 0
	s_waitcnt lgkmcnt(0)
	global_store_dwordx4 v180, v[156:159], s[74:75]
	global_load_dwordx4 v[128:131], v182, s[70:71]
	global_load_dwordx4 v[132:135], v182, s[70:71] offset:32
	global_load_dwordx4 v[136:139], v182, s[70:71] offset:64
	global_load_dwordx4 v[140:143], v182, s[70:71] offset:96
	global_load_dwordx4 v[144:147], v182, s[70:71] offset:128
	global_load_dwordx4 v[148:151], v182, s[70:71] offset:160
	global_load_dwordx4 v[152:155], v182, s[70:71] offset:192
	global_load_dwordx4 v[156:159], v182, s[70:71] offset:224
	s_waitcnt vmcnt(7)
	v_mul_f32_e32 v48, v128, v48
	v_mul_f32_e32 v49, v129, v49
	v_mul_f32_e32 v50, v130, v50
	v_mul_f32_e32 v51, v131, v51
	v_cvt_pk_bf16_f32 v48, v48, v49
	v_cvt_pk_bf16_f32 v49, v50, v51
	ds_write_b64 v177, v[48:49]
	s_waitcnt vmcnt(6)
	v_mul_f32_e32 v52, v132, v52
	v_mul_f32_e32 v53, v133, v53
	v_mul_f32_e32 v54, v134, v54
	v_mul_f32_e32 v55, v135, v55
	v_cvt_pk_bf16_f32 v52, v52, v53
	v_cvt_pk_bf16_f32 v53, v54, v55
	ds_write_b64 v177, v[52:53] offset:16
	s_waitcnt vmcnt(5)
	v_mul_f32_e32 v56, v136, v56
	v_mul_f32_e32 v57, v137, v57
	v_mul_f32_e32 v58, v138, v58
	v_mul_f32_e32 v59, v139, v59
	v_cvt_pk_bf16_f32 v56, v56, v57
	v_cvt_pk_bf16_f32 v57, v58, v59
	ds_write_b64 v177, v[56:57] offset:32
	s_waitcnt vmcnt(4)
	v_mul_f32_e32 v60, v140, v60
	v_mul_f32_e32 v61, v141, v61
	v_mul_f32_e32 v62, v142, v62
	v_mul_f32_e32 v63, v143, v63
	v_cvt_pk_bf16_f32 v60, v60, v61
	v_cvt_pk_bf16_f32 v61, v62, v63
	ds_write_b64 v177, v[60:61] offset:48
	s_waitcnt vmcnt(3)
	v_mul_f32_e32 v32, v144, v32
	v_mul_f32_e32 v33, v145, v33
	v_mul_f32_e32 v34, v146, v34
	v_mul_f32_e32 v35, v147, v35
	v_cvt_pk_bf16_f32 v32, v32, v33
	v_cvt_pk_bf16_f32 v33, v34, v35
	ds_write_b64 v177, v[32:33] offset:64
	s_waitcnt vmcnt(2)
	v_mul_f32_e32 v36, v148, v36
	v_mul_f32_e32 v37, v149, v37
	v_mul_f32_e32 v38, v150, v38
	v_mul_f32_e32 v39, v151, v39
	v_cvt_pk_bf16_f32 v36, v36, v37
	v_cvt_pk_bf16_f32 v37, v38, v39
	ds_write_b64 v177, v[36:37] offset:80
	s_waitcnt vmcnt(1)
; DI bfr f2bf(float a) { return (bfr)(pack2(a, 0.f) & 0xffffu); }
; DI int crow(int reg, int h) { return (reg & 3) + 8 * (reg >> 2) + 4 * h; }
; template <bool FIRST, bool HAS_H>
; DI void phase_gemm_resid(const Params& p, const bfr* A, const bfr* Wt, const float* gnext, float* ss, char* smem) {
;     ...
;         for (int jh = 0; jh < 2; ++jh) {
;           float xo[2][8];
; #pragma unroll
;           for (int jj = 0; jj < 2; ++jj)
; #pragma unroll
;             for (int q = 0; q < 8; ++q)
;               xo[jj][q] = xsrc[(rbase + i * 32 + crow(qh * 8 + q, 0)) * 1024 + cbase + (jh * 2 + jj) * 32];
; #pragma unroll
;           for (int q = 0; q < 8; ++q) {
;             const int o = (rbase + i * 32 + crow(qh * 8 + q, 0)) * 1024 + cbase;
; #pragma unroll
;             for (int jj = 0; jj < 2; ++jj) {
;               const int j = jh * 2 + jj;
;               const float xn = xo[jj][q] + acc[i][j][qh * 8 + q];
;               X[o + j * 32] = xn;
;               if (HAS_H) Hn[o + j * 32] = f2bf(xn * gnext[cbase + j * 32]);
;               rs[q] += xn * xn;
	v_mul_f32_e32 v40, v152, v40
	v_mul_f32_e32 v41, v153, v41
	v_mul_f32_e32 v42, v154, v42
	v_mul_f32_e32 v43, v155, v43
	v_cvt_pk_bf16_f32 v40, v40, v41
	v_cvt_pk_bf16_f32 v41, v42, v43
	ds_write_b64 v177, v[40:41] offset:96
	s_waitcnt vmcnt(0)
	v_mul_f32_e32 v44, v156, v44
	v_mul_f32_e32 v45, v157, v45
	v_mul_f32_e32 v46, v158, v46
	v_mul_f32_e32 v47, v159, v47
	v_cvt_pk_bf16_f32 v44, v44, v45
	v_cvt_pk_bf16_f32 v45, v46, v47
	ds_write_b64 v177, v[44:45] offset:112
	ds_read_b128 v[128:131], v179
	ds_read_b128 v[132:135], v179 offset:2176
	ds_read_b128 v[136:139], v179 offset:4352
	ds_read_b128 v[140:143], v179 offset:6528
	s_add_u32 s74, s68, 0x10000
	s_addc_u32 s75, s69, 0
	s_waitcnt lgkmcnt(3)
	global_store_dwordx4 v181, v[128:131], s[74:75]
	s_add_u32 s74, s68, 0x14000
	s_addc_u32 s75, s69, 0
	s_waitcnt lgkmcnt(2)
	global_store_dwordx4 v181, v[132:135], s[74:75]
	s_add_u32 s74, s68, 0x18000
	s_addc_u32 s75, s69, 0
	s_waitcnt lgkmcnt(1)
	global_store_dwordx4 v181, v[136:139], s[74:75]
	s_add_u32 s74, s68, 0x1c000
	s_addc_u32 s75, s69, 0
	s_waitcnt lgkmcnt(0)
	global_store_dwordx4 v181, v[140:143], s[74:75]
	s_add_u32 s74, s64, 0x20100
	s_addc_u32 s75, s65, 0
	global_load_dwordx4 v[128:131], v180, s[74:75]
	s_add_u32 s74, s64, 0x24100
	s_addc_u32 s75, s65, 0
	global_load_dwordx4 v[132:135], v180, s[74:75]
	s_add_u32 s74, s64, 0x28100
	s_addc_u32 s75, s65, 0
	global_load_dwordx4 v[136:139], v180, s[74:75]
	s_add_u32 s74, s64, 0x2c100
	s_addc_u32 s75, s65, 0
	global_load_dwordx4 v[140:143], v180, s[74:75]
	s_add_u32 s74, s64, 0x30100
	s_addc_u32 s75, s65, 0
	global_load_dwordx4 v[144:147], v180, s[74:75]
	s_add_u32 s74, s64, 0x34100
	s_addc_u32 s75, s65, 0
	global_load_dwordx4 v[148:151], v180, s[74:75]
	s_add_u32 s74, s64, 0x38100
	s_addc_u32 s75, s65, 0
	global_load_dwordx4 v[152:155], v180, s[74:75]
	s_add_u32 s74, s64, 0x3c100
	s_addc_u32 s75, s65, 0
	global_load_dwordx4 v[156:159], v180, s[74:75]
	s_waitcnt vmcnt(7)
	ds_write_b128 v178, v[128:131]
	s_waitcnt vmcnt(6)
	ds_write_b128 v178, v[132:135] offset:1088
	s_waitcnt vmcnt(5)
	ds_write_b128 v178, v[136:139] offset:2176
	s_waitcnt vmcnt(4)
	ds_write_b128 v178, v[140:143] offset:3264
	s_waitcnt vmcnt(3)
	ds_write_b128 v178, v[144:147] offset:4352
	s_waitcnt vmcnt(2)
	ds_write_b128 v178, v[148:151] offset:5440
	s_waitcnt vmcnt(1)
	ds_write_b128 v178, v[152:155] offset:6528
	s_waitcnt vmcnt(0)
	ds_write_b128 v178, v[156:159] offset:7616
	ds_read_b128 v[128:131], v176
	ds_read_b128 v[132:135], v176 offset:32
	ds_read_b128 v[136:139], v176 offset:64
	ds_read_b128 v[140:143], v176 offset:96
	ds_read_b128 v[144:147], v176 offset:128
	ds_read_b128 v[148:151], v176 offset:160
	ds_read_b128 v[152:155], v176 offset:192
	ds_read_b128 v[156:159], v176 offset:224
	s_waitcnt lgkmcnt(7)
	v_add_f32_e32 v16, v128, v16
	v_add_f32_e32 v17, v129, v17
	v_add_f32_e32 v18, v130, v18
	v_add_f32_e32 v19, v131, v19
	v_fmac_f32_e32 v184, v16, v16
	v_fmac_f32_e32 v184, v17, v17
	v_fmac_f32_e32 v184, v18, v18
	v_fmac_f32_e32 v184, v19, v19
	ds_write_b128 v176, v[16:19]
	s_waitcnt lgkmcnt(7)
	v_add_f32_e32 v20, v132, v20
	v_add_f32_e32 v21, v133, v21
	v_add_f32_e32 v22, v134, v22
	v_add_f32_e32 v23, v135, v23
	v_fmac_f32_e32 v184, v20, v20
	v_fmac_f32_e32 v184, v21, v21
	v_fmac_f32_e32 v184, v22, v22
	v_fmac_f32_e32 v184, v23, v23
	ds_write_b128 v176, v[20:23] offset:32
	s_waitcnt lgkmcnt(7)
	v_add_f32_e32 v24, v136, v24
	v_add_f32_e32 v25, v137, v25
	v_add_f32_e32 v26, v138, v26
	v_add_f32_e32 v27, v139, v27
	v_fmac_f32_e32 v184, v24, v24
	v_fmac_f32_e32 v184, v25, v25
	v_fmac_f32_e32 v184, v26, v26
	v_fmac_f32_e32 v184, v27, v27
	ds_write_b128 v176, v[24:27] offset:64
	s_waitcnt lgkmcnt(7)
	v_add_f32_e32 v28, v140, v28
	v_add_f32_e32 v29, v141, v29
	v_add_f32_e32 v30, v142, v30
	v_add_f32_e32 v31, v143, v31
	v_fmac_f32_e32 v184, v28, v28
	v_fmac_f32_e32 v184, v29, v29
	v_fmac_f32_e32 v184, v30, v30
	v_fmac_f32_e32 v184, v31, v31
	ds_write_b128 v176, v[28:31] offset:96
	s_waitcnt lgkmcnt(7)
	v_add_f32_e32 v0, v144, v0
	v_add_f32_e32 v1, v145, v1
	v_add_f32_e32 v2, v146, v2
	v_add_f32_e32 v3, v147, v3
	v_fmac_f32_e32 v184, v0, v0
	v_fmac_f32_e32 v184, v1, v1
	v_fmac_f32_e32 v184, v2, v2
	v_fmac_f32_e32 v184, v3, v3
	ds_write_b128 v176, v[0:3] offset:128
	s_waitcnt lgkmcnt(7)
	v_add_f32_e32 v4, v148, v4
	v_add_f32_e32 v5, v149, v5
	v_add_f32_e32 v6, v150, v6
	v_add_f32_e32 v7, v151, v7
	v_fmac_f32_e32 v184, v4, v4
	v_fmac_f32_e32 v184, v5, v5
	v_fmac_f32_e32 v184, v6, v6
	v_fmac_f32_e32 v184, v7, v7
	ds_write_b128 v176, v[4:7] offset:160
	s_waitcnt lgkmcnt(7)
	v_add_f32_e32 v8, v152, v8
	v_add_f32_e32 v9, v153, v9
	v_add_f32_e32 v10, v154, v10
	v_add_f32_e32 v11, v155, v11
	v_fmac_f32_e32 v184, v8, v8
	v_fmac_f32_e32 v184, v9, v9
	v_fmac_f32_e32 v184, v10, v10
	v_fmac_f32_e32 v184, v11, v11
	ds_write_b128 v176, v[8:11] offset:192
	s_waitcnt lgkmcnt(7)
; DI bfr f2bf(float a) { return (bfr)(pack2(a, 0.f) & 0xffffu); }
; DI int crow(int reg, int h) { return (reg & 3) + 8 * (reg >> 2) + 4 * h; }
; template <bool FIRST, bool HAS_H>
; DI void phase_gemm_resid(const Params& p, const bfr* A, const bfr* Wt, const float* gnext, float* ss, char* smem) {
;     ...
;         for (int jh = 0; jh < 2; ++jh) {
;           float xo[2][8];
; #pragma unroll
;           for (int jj = 0; jj < 2; ++jj)
; #pragma unroll
;             for (int q = 0; q < 8; ++q)
;               xo[jj][q] = xsrc[(rbase + i * 32 + crow(qh * 8 + q, 0)) * 1024 + cbase + (jh * 2 + jj) * 32];
; #pragma unroll
;           for (int q = 0; q < 8; ++q) {
;             const int o = (rbase + i * 32 + crow(qh * 8 + q, 0)) * 1024 + cbase;
; #pragma unroll
;             for (int jj = 0; jj < 2; ++jj) {
;               const int j = jh * 2 + jj;
;               const float xn = xo[jj][q] + acc[i][j][qh * 8 + q];
;               X[o + j * 32] = xn;
;               if (HAS_H) Hn[o + j * 32] = f2bf(xn * gnext[cbase + j * 32]);
;               rs[q] += xn * xn;
;             }
;           }
;         }
; #pragma unroll
;         for (int q = 0; q < 8; ++q) rs[q] = half32_sum_hi(rs[q]);
;         if (r == 31) {
; #pragma unroll
;           for (int q = 0; q < 8; ++q) unsafeAtomicAdd(ss + rbase + i * 32 + crow(qh * 8 + q, 0), rs[q]);
;         }
	v_add_f32_e32 v12, v156, v12
	v_add_f32_e32 v13, v157, v13
	v_add_f32_e32 v14, v158, v14
	v_add_f32_e32 v15, v159, v15
	v_fmac_f32_e32 v184, v12, v12
	v_fmac_f32_e32 v184, v13, v13
	v_fmac_f32_e32 v184, v14, v14
	v_fmac_f32_e32 v184, v15, v15
	ds_write_b128 v176, v[12:15] offset:224
	ds_read_b128 v[128:131], v178
	ds_read_b128 v[132:135], v178 offset:1088
	ds_read_b128 v[136:139], v178 offset:2176
	ds_read_b128 v[140:143], v178 offset:3264
	ds_read_b128 v[144:147], v178 offset:4352
	ds_read_b128 v[148:151], v178 offset:5440
	ds_read_b128 v[152:155], v178 offset:6528
	ds_read_b128 v[156:159], v178 offset:7616
	s_add_u32 s74, s66, 0x20100
	s_addc_u32 s75, s67, 0
	s_waitcnt lgkmcnt(7)
	global_store_dwordx4 v180, v[128:131], s[74:75]
	s_add_u32 s74, s66, 0x24100
	s_addc_u32 s75, s67, 0
	s_waitcnt lgkmcnt(6)
	global_store_dwordx4 v180, v[132:135], s[74:75]
	s_add_u32 s74, s66, 0x28100
	s_addc_u32 s75, s67, 0
	s_waitcnt lgkmcnt(5)
	global_store_dwordx4 v180, v[136:139], s[74:75]
	s_add_u32 s74, s66, 0x2c100
	s_addc_u32 s75, s67, 0
	s_waitcnt lgkmcnt(4)
	global_store_dwordx4 v180, v[140:143], s[74:75]
	s_add_u32 s74, s66, 0x30100
	s_addc_u32 s75, s67, 0
	s_waitcnt lgkmcnt(3)
	global_store_dwordx4 v180, v[144:147], s[74:75]
	s_add_u32 s74, s66, 0x34100
	s_addc_u32 s75, s67, 0
	s_waitcnt lgkmcnt(2)
	global_store_dwordx4 v180, v[148:151], s[74:75]
	s_add_u32 s74, s66, 0x38100
	s_addc_u32 s75, s67, 0
	s_waitcnt lgkmcnt(1)
	global_store_dwordx4 v180, v[152:155], s[74:75]
	s_add_u32 s74, s66, 0x3c100
	s_addc_u32 s75, s67, 0
	s_waitcnt lgkmcnt(0)
	global_store_dwordx4 v180, v[156:159], s[74:75]
	global_load_dwordx4 v[128:131], v182, s[70:71] offset:256
	global_load_dwordx4 v[132:135], v182, s[70:71] offset:288
	global_load_dwordx4 v[136:139], v182, s[70:71] offset:320
	global_load_dwordx4 v[140:143], v182, s[70:71] offset:352
	global_load_dwordx4 v[144:147], v182, s[70:71] offset:384
	global_load_dwordx4 v[148:151], v182, s[70:71] offset:416
	global_load_dwordx4 v[152:155], v182, s[70:71] offset:448
	global_load_dwordx4 v[156:159], v182, s[70:71] offset:480
	s_waitcnt vmcnt(7)
	v_mul_f32_e32 v16, v128, v16
	v_mul_f32_e32 v17, v129, v17
	v_mul_f32_e32 v18, v130, v18
	v_mul_f32_e32 v19, v131, v19
	v_cvt_pk_bf16_f32 v16, v16, v17
	v_cvt_pk_bf16_f32 v17, v18, v19
	ds_write_b64 v177, v[16:17]
	s_waitcnt vmcnt(6)
	v_mul_f32_e32 v20, v132, v20
	v_mul_f32_e32 v21, v133, v21
	v_mul_f32_e32 v22, v134, v22
	v_mul_f32_e32 v23, v135, v23
	v_cvt_pk_bf16_f32 v20, v20, v21
	v_cvt_pk_bf16_f32 v21, v22, v23
	ds_write_b64 v177, v[20:21] offset:16
	s_waitcnt vmcnt(5)
	v_mul_f32_e32 v24, v136, v24
	v_mul_f32_e32 v25, v137, v25
	v_mul_f32_e32 v26, v138, v26
	v_mul_f32_e32 v27, v139, v27
	v_cvt_pk_bf16_f32 v24, v24, v25
	v_cvt_pk_bf16_f32 v25, v26, v27
	ds_write_b64 v177, v[24:25] offset:32
	s_waitcnt vmcnt(4)
	v_mul_f32_e32 v28, v140, v28
	v_mul_f32_e32 v29, v141, v29
	v_mul_f32_e32 v30, v142, v30
	v_mul_f32_e32 v31, v143, v31
	v_cvt_pk_bf16_f32 v28, v28, v29
	v_cvt_pk_bf16_f32 v29, v30, v31
	ds_write_b64 v177, v[28:29] offset:48
	s_waitcnt vmcnt(3)
	v_mul_f32_e32 v0, v144, v0
	v_mul_f32_e32 v1, v145, v1
	v_mul_f32_e32 v2, v146, v2
	v_mul_f32_e32 v3, v147, v3
	v_cvt_pk_bf16_f32 v0, v0, v1
	v_cvt_pk_bf16_f32 v1, v2, v3
	ds_write_b64 v177, v[0:1] offset:64
	s_waitcnt vmcnt(2)
	v_mul_f32_e32 v4, v148, v4
	v_mul_f32_e32 v5, v149, v5
	v_mul_f32_e32 v6, v150, v6
	v_mul_f32_e32 v7, v151, v7
	v_cvt_pk_bf16_f32 v4, v4, v5
	v_cvt_pk_bf16_f32 v5, v6, v7
	ds_write_b64 v177, v[4:5] offset:80
	s_waitcnt vmcnt(1)
	v_mul_f32_e32 v8, v152, v8
	v_mul_f32_e32 v9, v153, v9
	v_mul_f32_e32 v10, v154, v10
	v_mul_f32_e32 v11, v155, v11
	v_cvt_pk_bf16_f32 v8, v8, v9
	v_cvt_pk_bf16_f32 v9, v10, v11
	ds_write_b64 v177, v[8:9] offset:96
	s_waitcnt vmcnt(0)
	v_mul_f32_e32 v12, v156, v12
	v_mul_f32_e32 v13, v157, v13
	v_mul_f32_e32 v14, v158, v14
	v_mul_f32_e32 v15, v159, v15
	v_cvt_pk_bf16_f32 v12, v12, v13
	v_cvt_pk_bf16_f32 v13, v14, v15
	ds_write_b64 v177, v[12:13] offset:112
	ds_read_b128 v[128:131], v179
	ds_read_b128 v[132:135], v179 offset:2176
	ds_read_b128 v[136:139], v179 offset:4352
	ds_read_b128 v[140:143], v179 offset:6528
	s_add_u32 s74, s68, 0x10080
	s_addc_u32 s75, s69, 0
	s_waitcnt lgkmcnt(3)
	global_store_dwordx4 v181, v[128:131], s[74:75]
	s_add_u32 s74, s68, 0x14080
	s_addc_u32 s75, s69, 0
	s_waitcnt lgkmcnt(2)
	global_store_dwordx4 v181, v[132:135], s[74:75]
	s_add_u32 s74, s68, 0x18080
	s_addc_u32 s75, s69, 0
	s_waitcnt lgkmcnt(1)
	global_store_dwordx4 v181, v[136:139], s[74:75]
	s_add_u32 s74, s68, 0x1c080
	s_addc_u32 s75, s69, 0
	s_waitcnt lgkmcnt(0)
	global_store_dwordx4 v181, v[140:143], s[74:75]
	s_load_dwordx2 s[64:65], s[92:93], 0x140
	ds_bpermute_b32 v188, v186, v183
	ds_bpermute_b32 v189, v186, v184
	s_waitcnt lgkmcnt(0)
	s_add_u32 s64, s64, 0x20400
	s_addc_u32 s65, s65, 0
	v_add_f32_e32 v188, v188, v183
	v_add_f32_e32 v189, v189, v184
	s_mov_b32 exec_hi, 0
	s_nop 1
	global_atomic_add_f32 v185, v188, s[64:65]
	global_atomic_add_f32 v185, v189, s[64:65] offset:128
	s_mov_b64 exec, -1
	v_readlane_b32 s64, v187, 0
	v_readlane_b32 s65, v187, 1
	v_readlane_b32 s66, v187, 2
	v_readlane_b32 s67, v187, 3
	v_readlane_b32 s68, v187, 4
	v_readlane_b32 s69, v187, 5
	v_readlane_b32 s70, v187, 6
	v_readlane_b32 s71, v187, 7
	v_readlane_b32 s72, v187, 8
	v_readlane_b32 s73, v187, 9
	v_readlane_b32 s74, v187, 10
	v_readlane_b32 s75, v187, 11
	v_readlane_b32 s76, v187, 12
	v_readlane_b32 s77, v187, 13
	v_readlane_b32 s78, v187, 14
	v_readlane_b32 s79, v187, 15
	s_nop 7
	s_branch .LBB0_1463

; #define GA_LOAD(pr_) do { _Pragma("unroll") for (int i = 0; i < 4; ++i) ra[i] = *(const u32x4*)(Ab + (i * 32) * lda + (pr_) * 64); } while (0)
; #define GB_LOAD(kt_) do { const bfr* bk_ = Bb + (kt_) * NB * 32; \
;     _Pragma("unroll") for (int i = 0; i < 4; ++i) rb[i] = *(const u32x4*)(bk_ + (i * 64) * 32); } while (0)
; #define G_STORE(kt_) do { bfr* as_ = S0 + ((kt_) & 1) * GSTAGE; bfr* bs_ = as_ + 128 * 40; \
;     if (apar == ((kt_) & 1)) { _Pragma("unroll") for (int i = 0; i < 4; ++i) *(u32x4*)(as_ + asoff + i * 32 * 40) = ra[i]; } \
;     _Pragma("unroll") for (int i = 0; i < 4; ++i) *(u32x4*)(bs_ + bsoff + i * 64 * 40) = rb[i]; } while (0)
; template <int lda>
; DI void gemm_mainloop(const bfr* __restrict__ A, const bfr* __restrict__ Bt, int NB, int K, int m0, int n0, char* smem, f32x16 (&acc)[2][4]) {
;   bfr* S0 = (bfr*)smem;
;   int tid = threadIdx.x;
;   asm volatile("" : "+v"(tid));
;   const int lane = tid & 63, wid = tid >> 6, wr = wid >> 1, wc = wid & 1;
;   const int r = lane & 31, hl = lane >> 5;
; #pragma unroll
;   for (int i = 0; i < 2; ++i)
; #pragma unroll
;     for (int j = 0; j < 4; ++j)
; #pragma unroll
;       for (int q = 0; q < 16; ++q) acc[i][j][q] = 0.f;
;   u32x4 ra[4], rb[4];
;   const int nk = K >> 5;
;   const int arow = tid >> 3, ac8 = tid & 7, apar = ac8 >> 2;
;   const bfr* Ab = A + (m0 + arow) * lda + ac8 * 8;
;   const int asoff = arow * 40 + (ac8 & 3) * 8;
;   const int brow = tid >> 2, bc4 = tid & 3;
;   const bfr* Bb = Bt + (n0 + brow) * 32 + bc4 * 8;
;   const int bsoff = brow * 40 + bc4 * 8;
;     ...
;   GA_LOAD(0);
;   GB_LOAD(0);
;   G_STORE(0);
;   GB_LOAD(1);
;   __syncthreads();
; template <bool FIRST, bool HAS_H>
; DI void phase_gemm_resid(const Params& p, const bfr* A, const bfr* Wt, const float* gnext, float* ss, char* smem) {
;     ...
;     const int t = ((gridDim.x & 7) == 0) ? xcd_tile(t0, 4) : t0;
;     const int mt = t >> 2, nt = t & 3, m0 = mt * 128, n0 = nt * 256;
;     f32x16 acc[2][4];
;     gemm_mainloop<1024>(A, Wt, 1024, 1024, m0, n0, smem, acc);
.LBB0_1721:
	s_lshl_b32 s5, s4, 5
	s_and_b32 s59, s5, 0xffffff80
	s_lshl_b32 s4, s4, 8
	s_and_b32 s58, s4, 0x300
	s_mov_b32 s60, 0
	s_mov_b64 s[16:17], 0
	s_lshl_b32 s98, s59, 11
	s_add_u32 s98, s6, s98
	s_addc_u32 s99, s7, 0
	s_lshl_b32 s100, s58, 6
	s_add_u32 s100, s2, s100
	s_addc_u32 s101, s3, 0
	v_writelane_b32 v188, s64, 0
	v_writelane_b32 v188, s65, 1
	v_writelane_b32 v188, s66, 2
	v_writelane_b32 v188, s67, 3
	v_writelane_b32 v188, s68, 4
	v_writelane_b32 v188, s69, 5
	v_writelane_b32 v188, s70, 6
	v_writelane_b32 v188, s71, 7
	v_writelane_b32 v188, s72, 8
	v_writelane_b32 v188, s73, 9
	v_writelane_b32 v188, s74, 10
	v_writelane_b32 v188, s75, 11
	v_writelane_b32 v188, s76, 12
	v_writelane_b32 v188, s77, 13
	v_writelane_b32 v188, s78, 14
	v_writelane_b32 v188, s79, 15
	s_mov_b32 s77, s59
	s_mov_b32 s78, s58
	v_lshrrev_b32_e32 v189, 6, v196
	v_and_b32_e32 v190, 63, v196
	v_readfirstlane_b32 s73, v189
	v_lshrrev_b32_e32 v191, 2, v190
	v_bfe_u32 v192, v190, 4, 2
	v_and_b32_e32 v189, 3, v190
	v_xor_b32_e32 v189, v189, v192
	v_lshlrev_b32_e32 v189, 4, v189
	v_lshl_add_u32 v176, v191, 11, v189
	v_add_u32_e32 v177, 0x8000, v176
	v_lshl_add_u32 v178, v191, 6, v189
	v_and_b32_e32 v191, 31, v190
	v_lshrrev_b32_e32 v192, 5, v190
	v_bfe_u32 v189, v190, 2, 2
	v_xor_b32_e32 v189, v189, v192
	v_lshlrev_b32_e32 v189, 4, v189
	v_lshl_add_u32 v179, v191, 6, v189
	s_lshr_b32 s74, s73, 1
	s_lshl_b32 s74, s74, 12
	s_and_b32 s75, s73, 1
	s_lshl_b32 s75, s75, 13
	v_add_u32_e32 v182, s75, v179
	v_add_u32_e32 v179, s74, v179
	v_xor_b32_e32 v183, 32, v182
	v_xor_b32_e32 v180, 32, v179
	s_lshl_b32 s74, s73, 16
	s_add_u32 s64, s98, s74
	s_addc_u32 s65, s99, 0
	s_lshl_b32 s74, s73, 12
	s_add_u32 s66, s100, s74
	s_addc_u32 s67, s101, 0
	s_lshl_b32 s68, s73, 11
	s_lshl_b32 s69, s73, 12
	s_mov_b32 s70, 0
	s_mov_b32 s71, 0
	s_mov_b32 s72, 0
	s_waitcnt lgkmcnt(0)
	s_barrier
	s_mul_i32 s74, s70, 0x6000
	s_add_u32 s75, s74, s68
	s_mov_b32 m0, s75
	s_add_u32 s76, s74, 0x2000
	s_cmp_eq_u32 s70, 2
	s_cselect_b32 s76, 0x10000, s76
	global_load_lds_dwordx4 v176, s[64:65]
	s_add_u32 m0, s75, 0x400
	s_add_u32 s76, s76, s69
	global_load_lds_dwordx4 v177, s[64:65]
	s_mov_b32 m0, s76
	s_add_u32 s64, s64, 64
	s_addc_u32 s65, s65, 0
	global_load_lds_dwordx4 v178, s[66:67]
	global_load_lds_dwordx4 v178, s[66:67] offset:1024
	global_load_lds_dwordx4 v178, s[66:67] offset:2048
	global_load_lds_dwordx4 v178, s[66:67] offset:3072
	s_add_u32 s66, s66, 0x10000
	s_addc_u32 s67, s67, 0
	s_add_u32 s70, s70, 1
	s_cmp_eq_u32 s70, 3
	s_cselect_b32 s70, 0, s70
	s_mul_i32 s74, s70, 0x6000
	s_add_u32 s75, s74, s68
	s_mov_b32 m0, s75
	s_add_u32 s76, s74, 0x2000
	s_cmp_eq_u32 s70, 2
	s_cselect_b32 s76, 0x10000, s76
	global_load_lds_dwordx4 v176, s[64:65]
	s_add_u32 m0, s75, 0x400
	s_add_u32 s76, s76, s69
	global_load_lds_dwordx4 v177, s[64:65]
	s_mov_b32 m0, s76
	s_add_u32 s64, s64, 64
	s_addc_u32 s65, s65, 0
	global_load_lds_dwordx4 v178, s[66:67]
	global_load_lds_dwordx4 v178, s[66:67] offset:1024
	global_load_lds_dwordx4 v178, s[66:67] offset:2048
	global_load_lds_dwordx4 v178, s[66:67] offset:3072
	s_add_u32 s66, s66, 0x10000
	s_addc_u32 s67, s67, 0
	s_add_u32 s70, s70, 1
	s_cmp_eq_u32 s70, 3
	s_cselect_b32 s70, 0, s70
	s_cmp_lt_u32 s46, 0x100
	s_cbranch_scc1 .Lp19_nostag
	s_sleep 8

; #define MFMA32(a, b, c) __builtin_amdgcn_mfma_f32_32x32x16_bf16((a), (b), (c), 0, 0, 0)
; #define GA_LOAD(pr_) do { _Pragma("unroll") for (int i = 0; i < 4; ++i) ra[i] = *(const u32x4*)(Ab + (i * 32) * lda + (pr_) * 64); } while (0)
; #define GB_LOAD(kt_) do { const bfr* bk_ = Bb + (kt_) * NB * 32; \
;     _Pragma("unroll") for (int i = 0; i < 4; ++i) rb[i] = *(const u32x4*)(bk_ + (i * 64) * 32); } while (0)
; #define G_STORE(kt_) do { bfr* as_ = S0 + ((kt_) & 1) * GSTAGE; bfr* bs_ = as_ + 128 * 40; \
;     if (apar == ((kt_) & 1)) { _Pragma("unroll") for (int i = 0; i < 4; ++i) *(u32x4*)(as_ + asoff + i * 32 * 40) = ra[i]; } \
;     _Pragma("unroll") for (int i = 0; i < 4; ++i) *(u32x4*)(bs_ + bsoff + i * 64 * 40) = rb[i]; } while (0)
; template <int lda>
; DI void gemm_mainloop(const bfr* __restrict__ A, const bfr* __restrict__ Bt, int NB, int K, int m0, int n0, char* smem, f32x16 (&acc)[2][4]) {
;     ...
;   for (int kt = 0; kt < nk; ++kt) {
;     if (kt + 1 < nk) G_STORE(kt + 1);
;     if (kt + 2 < nk) {
;       GB_LOAD(kt + 2);
;       if ((kt & 1) == 0) GA_LOAD((kt >> 1) + 1);
;     }
;     const bfr* As = S0 + (kt & 1) * GSTAGE;
;     const bfr* Bs = As + 128 * 40;
; #pragma unroll
;     for (int ks = 0; ks < 2; ++ks) {
;       bf16x8 af[2], bfg[4];
; #pragma unroll
;       for (int i = 0; i < 2; ++i) af[i] = *(const bf16x8*)(As + (wr * 64 + i * 32 + r) * 40 + ks * 16 + hl * 8);
; #pragma unroll
;       for (int j = 0; j < 4; ++j) bfg[j] = *(const bf16x8*)(Bs + (wc * 128 + j * 32 + r) * 40 + ks * 16 + hl * 8);
; #pragma unroll
;       for (int i = 0; i < 2; ++i)
; #pragma unroll
;         for (int j = 0; j < 4; ++j) acc[i][j] = MFMA32(af[i], bfg[j], acc[i][j]);
;     }
;     __syncthreads();
;   }
.Lp19_loop:
	s_waitcnt vmcnt(6)
	s_barrier
	s_mul_i32 s74, s71, 0x6000
	s_add_u32 s75, s74, 0x2000
	s_cmp_eq_u32 s71, 2
	s_cselect_b32 s75, 0x10000, s75
	v_add_u32_e32 v184, s74, v179
	v_add_u32_e32 v186, s75, v182
	v_add_u32_e32 v185, s74, v180
	v_add_u32_e32 v187, s75, v183
	ds_read_b128 v[128:131], v184
	ds_read_b128 v[144:147], v186
	ds_read_b128 v[148:151], v186 offset:2048
	ds_read_b128 v[152:155], v186 offset:4096
	ds_read_b128 v[156:159], v186 offset:6144
	ds_read_b128 v[132:135], v184 offset:2048
	ds_read_b128 v[136:139], v185
	ds_read_b128 v[160:163], v187
	ds_read_b128 v[164:167], v187 offset:2048
	ds_read_b128 v[168:171], v187 offset:4096
	ds_read_b128 v[172:175], v187 offset:6144
	ds_read_b128 v[140:143], v185 offset:2048
	s_add_u32 s71, s71, 1
	s_cmp_eq_u32 s71, 3
	s_cselect_b32 s71, 0, s71
	s_waitcnt lgkmcnt(10)
	v_mfma_f32_32x32x16_bf16 v[112:127], v[144:147], v[128:131], v[112:127]
	s_mul_i32 s74, s70, 0x6000
	s_add_u32 s75, s74, s68
	s_mov_b32 m0, s75
	s_add_u32 s76, s74, 0x2000
	s_cmp_eq_u32 s70, 2
	s_cselect_b32 s76, 0x10000, s76
	global_load_lds_dwordx4 v176, s[64:65]
	s_waitcnt lgkmcnt(9)
	v_mfma_f32_32x32x16_bf16 v[96:111], v[148:151], v[128:131], v[96:111]
	s_add_u32 m0, s75, 0x400
	s_add_u32 s76, s76, s69
	global_load_lds_dwordx4 v177, s[64:65]
	s_waitcnt lgkmcnt(8)
	v_mfma_f32_32x32x16_bf16 v[80:95], v[152:155], v[128:131], v[80:95]
	s_mov_b32 m0, s76
	s_add_u32 s64, s64, 64
	s_addc_u32 s65, s65, 0
	global_load_lds_dwordx4 v178, s[66:67]
	s_waitcnt lgkmcnt(7)
	v_mfma_f32_32x32x16_bf16 v[64:79], v[156:159], v[128:131], v[64:79]
	global_load_lds_dwordx4 v178, s[66:67] offset:1024
	s_waitcnt lgkmcnt(6)
	v_mfma_f32_32x32x16_bf16 v[48:63], v[144:147], v[132:135], v[48:63]
	global_load_lds_dwordx4 v178, s[66:67] offset:2048
	v_mfma_f32_32x32x16_bf16 v[32:47], v[148:151], v[132:135], v[32:47]
	global_load_lds_dwordx4 v178, s[66:67] offset:3072
	s_add_u32 s66, s66, 0x10000
	s_addc_u32 s67, s67, 0
	v_mfma_f32_32x32x16_bf16 v[16:31], v[152:155], v[132:135], v[16:31]
	s_add_u32 s70, s70, 1
	s_cmp_eq_u32 s70, 3
	s_cselect_b32 s70, 0, s70
	v_mfma_f32_32x32x16_bf16 v[0:15], v[156:159], v[132:135], v[0:15]
	s_waitcnt lgkmcnt(4)
	v_mfma_f32_32x32x16_bf16 v[112:127], v[160:163], v[136:139], v[112:127]
	s_waitcnt lgkmcnt(3)
	v_mfma_f32_32x32x16_bf16 v[96:111], v[164:167], v[136:139], v[96:111]
	s_waitcnt lgkmcnt(2)
	v_mfma_f32_32x32x16_bf16 v[80:95], v[168:171], v[136:139], v[80:95]
	s_waitcnt lgkmcnt(1)
	v_mfma_f32_32x32x16_bf16 v[64:79], v[172:175], v[136:139], v[64:79]
	s_waitcnt lgkmcnt(0)
	v_mfma_f32_32x32x16_bf16 v[48:63], v[160:163], v[140:143], v[48:63]
	v_mfma_f32_32x32x16_bf16 v[32:47], v[164:167], v[140:143], v[32:47]
	v_mfma_f32_32x32x16_bf16 v[16:31], v[168:171], v[140:143], v[16:31]
	v_mfma_f32_32x32x16_bf16 v[0:15], v[172:175], v[140:143], v[0:15]
	s_add_u32 s72, s72, 1
	s_cmp_lt_u32 s72, 30
	s_cbranch_scc1 .Lp19_loop
	s_waitcnt vmcnt(6)
	s_barrier
	s_mul_i32 s74, s71, 0x6000
	s_add_u32 s75, s74, 0x2000
	s_cmp_eq_u32 s71, 2
	s_cselect_b32 s75, 0x10000, s75
	v_add_u32_e32 v184, s74, v179
	v_add_u32_e32 v186, s75, v182
	v_add_u32_e32 v185, s74, v180
	v_add_u32_e32 v187, s75, v183
	ds_read_b128 v[128:131], v184
	ds_read_b128 v[144:147], v186
	ds_read_b128 v[148:151], v186 offset:2048
	ds_read_b128 v[152:155], v186 offset:4096
	ds_read_b128 v[156:159], v186 offset:6144
	ds_read_b128 v[132:135], v184 offset:2048
	ds_read_b128 v[136:139], v185
	ds_read_b128 v[160:163], v187
	ds_read_b128 v[164:167], v187 offset:2048
	ds_read_b128 v[168:171], v187 offset:4096
	ds_read_b128 v[172:175], v187 offset:6144
	ds_read_b128 v[140:143], v185 offset:2048
	s_add_u32 s71, s71, 1
	s_cmp_eq_u32 s71, 3
	s_cselect_b32 s71, 0, s71
	s_waitcnt lgkmcnt(10)
	v_mfma_f32_32x32x16_bf16 v[112:127], v[144:147], v[128:131], v[112:127]
	s_waitcnt lgkmcnt(9)
	v_mfma_f32_32x32x16_bf16 v[96:111], v[148:151], v[128:131], v[96:111]
	s_waitcnt lgkmcnt(8)
	v_mfma_f32_32x32x16_bf16 v[80:95], v[152:155], v[128:131], v[80:95]
	s_waitcnt lgkmcnt(7)
	v_mfma_f32_32x32x16_bf16 v[64:79], v[156:159], v[128:131], v[64:79]
	s_waitcnt lgkmcnt(6)
	v_mfma_f32_32x32x16_bf16 v[48:63], v[144:147], v[132:135], v[48:63]
	v_mfma_f32_32x32x16_bf16 v[32:47], v[148:151], v[132:135], v[32:47]
	v_mfma_f32_32x32x16_bf16 v[16:31], v[152:155], v[132:135], v[16:31]
	v_mfma_f32_32x32x16_bf16 v[0:15], v[156:159], v[132:135], v[0:15]
	s_waitcnt lgkmcnt(4)
	v_mfma_f32_32x32x16_bf16 v[112:127], v[160:163], v[136:139], v[112:127]
	s_waitcnt lgkmcnt(3)
	v_mfma_f32_32x32x16_bf16 v[96:111], v[164:167], v[136:139], v[96:111]
	s_waitcnt lgkmcnt(2)
	v_mfma_f32_32x32x16_bf16 v[80:95], v[168:171], v[136:139], v[80:95]
	s_waitcnt lgkmcnt(1)
	v_mfma_f32_32x32x16_bf16 v[64:79], v[172:175], v[136:139], v[64:79]
	s_waitcnt lgkmcnt(0)
	v_mfma_f32_32x32x16_bf16 v[48:63], v[160:163], v[140:143], v[48:63]
	v_mfma_f32_32x32x16_bf16 v[32:47], v[164:167], v[140:143], v[32:47]
	v_mfma_f32_32x32x16_bf16 v[16:31], v[168:171], v[140:143], v[16:31]
	v_mfma_f32_32x32x16_bf16 v[0:15], v[172:175], v[140:143], v[0:15]
	s_waitcnt vmcnt(0)
	s_barrier
; template <int lda>
; DI void gemm_mainloop(const bfr* __restrict__ A, const bfr* __restrict__ Bt, int NB, int K, int m0, int n0, char* smem, f32x16 (&acc)[2][4]) {
;     ...
;   for (int kt = 0; kt < nk; ++kt) {
;     if (kt + 1 < nk) G_STORE(kt + 1);
;     if (kt + 2 < nk) {
;       GB_LOAD(kt + 2);
;       if ((kt & 1) == 0) GA_LOAD((kt >> 1) + 1);
;     }
;     const bfr* As = S0 + (kt & 1) * GSTAGE;
;     const bfr* Bs = As + 128 * 40;
; #pragma unroll
;     for (int ks = 0; ks < 2; ++ks) {
;       bf16x8 af[2], bfg[4];
; #pragma unroll
;       for (int i = 0; i < 2; ++i) af[i] = *(const bf16x8*)(As + (wr * 64 + i * 32 + r) * 40 + ks * 16 + hl * 8);
; #pragma unroll
;       for (int j = 0; j < 4; ++j) bfg[j] = *(const bf16x8*)(Bs + (wc * 128 + j * 32 + r) * 40 + ks * 16 + hl * 8);
; #pragma unroll
;       for (int i = 0; i < 2; ++i)
; #pragma unroll
;         for (int j = 0; j < 4; ++j) acc[i][j] = MFMA32(af[i], bfg[j], acc[i][j]);
;     }
;     __syncthreads();
;   }
; template <bool FIRST, bool HAS_H>
; DI void phase_gemm_resid(const Params& p, const bfr* A, const bfr* Wt, const float* gnext, float* ss, char* smem) {
;     ...
;     int tid2 = threadIdx.x;
;     asm volatile("" : "+v"(tid2));
;     const int lane = tid2 & 63, wid = tid2 >> 6, wr = wid >> 1, wc = wid & 1, r = lane & 31, hl = lane >> 5;
;     const float* xsrc = FIRST ? p.x_prompt : X;
;     const int rbase = m0 + wr * 64 + 4 * hl, cbase = n0 + wc * 128 + r;
; #pragma unroll
;     for (int i = 0; i < 2; ++i) {
; #pragma unroll
;       for (int qh = 0; qh < 2; ++qh) {
;         float rs[8];
; #pragma unroll
;         for (int q = 0; q < 8; ++q) rs[q] = 0.f;
; #pragma unroll
;         for (int jh = 0; jh < 2; ++jh) {
;           float xo[2][8];
; #pragma unroll
;           for (int jj = 0; jj < 2; ++jj)
; #pragma unroll
;             for (int q = 0; q < 8; ++q)
;               xo[jj][q] = xsrc[(rbase + i * 32 + crow(qh * 8 + q, 0)) * 1024 + cbase + (jh * 2 + jj) * 32];
; #pragma unroll
;           for (int q = 0; q < 8; ++q) {
;             const int o = (rbase + i * 32 + crow(qh * 8 + q, 0)) * 1024 + cbase;
; #pragma unroll
;             for (int jj = 0; jj < 2; ++jj) {
;               const int j = jh * 2 + jj;
;               const float xn = xo[jj][q] + acc[i][j][qh * 8 + q];
;               X[o + j * 32] = xn;
;               if (HAS_H) Hn[o + j * 32] = f2bf(xn * gnext[cbase + j * 32]);
	s_mul_i32 s74, s71, 0x6000
	s_add_u32 s75, s74, 0x2000
	s_cmp_eq_u32 s71, 2
	s_cselect_b32 s75, 0x10000, s75
	v_add_u32_e32 v184, s74, v179
	v_add_u32_e32 v186, s75, v182
	v_add_u32_e32 v185, s74, v180
	v_add_u32_e32 v187, s75, v183
	ds_read_b128 v[128:131], v184
	ds_read_b128 v[144:147], v186
	ds_read_b128 v[148:151], v186 offset:2048
	ds_read_b128 v[152:155], v186 offset:4096
	ds_read_b128 v[156:159], v186 offset:6144
	ds_read_b128 v[132:135], v184 offset:2048
	ds_read_b128 v[136:139], v185
	ds_read_b128 v[160:163], v187
	ds_read_b128 v[164:167], v187 offset:2048
	ds_read_b128 v[168:171], v187 offset:4096
	ds_read_b128 v[172:175], v187 offset:6144
	ds_read_b128 v[140:143], v185 offset:2048
	s_add_u32 s71, s71, 1
	s_cmp_eq_u32 s71, 3
	s_cselect_b32 s71, 0, s71
	s_waitcnt lgkmcnt(10)
	v_mfma_f32_32x32x16_bf16 v[112:127], v[144:147], v[128:131], v[112:127]
	s_waitcnt lgkmcnt(9)
	v_mfma_f32_32x32x16_bf16 v[96:111], v[148:151], v[128:131], v[96:111]
	s_waitcnt lgkmcnt(8)
	v_mfma_f32_32x32x16_bf16 v[80:95], v[152:155], v[128:131], v[80:95]
	s_waitcnt lgkmcnt(7)
	v_mfma_f32_32x32x16_bf16 v[64:79], v[156:159], v[128:131], v[64:79]
	s_waitcnt lgkmcnt(6)
	v_mfma_f32_32x32x16_bf16 v[48:63], v[144:147], v[132:135], v[48:63]
	v_mfma_f32_32x32x16_bf16 v[32:47], v[148:151], v[132:135], v[32:47]
	v_mfma_f32_32x32x16_bf16 v[16:31], v[152:155], v[132:135], v[16:31]
	v_mfma_f32_32x32x16_bf16 v[0:15], v[156:159], v[132:135], v[0:15]
	s_waitcnt lgkmcnt(4)
	v_mfma_f32_32x32x16_bf16 v[112:127], v[160:163], v[136:139], v[112:127]
	s_waitcnt lgkmcnt(3)
	v_mfma_f32_32x32x16_bf16 v[96:111], v[164:167], v[136:139], v[96:111]
	s_waitcnt lgkmcnt(2)
	v_mfma_f32_32x32x16_bf16 v[80:95], v[168:171], v[136:139], v[80:95]
	s_waitcnt lgkmcnt(1)
	v_mfma_f32_32x32x16_bf16 v[64:79], v[172:175], v[136:139], v[64:79]
	s_waitcnt lgkmcnt(0)
	v_mfma_f32_32x32x16_bf16 v[48:63], v[160:163], v[140:143], v[48:63]
	v_mfma_f32_32x32x16_bf16 v[32:47], v[164:167], v[140:143], v[32:47]
	v_mfma_f32_32x32x16_bf16 v[16:31], v[168:171], v[140:143], v[16:31]
	v_mfma_f32_32x32x16_bf16 v[0:15], v[172:175], v[140:143], v[0:15]
	s_nop 7
	s_nop 3
	s_barrier
	s_load_dwordx2 s[64:65], s[92:93], 0x100
	s_load_dwordx2 s[66:67], s[92:93], 0x100
	s_mul_i32 s76, s73, 8704
	s_lshr_b32 s74, s73, 1
	s_lshl_b32 s74, s74, 6
	s_add_u32 s74, s74, s77
	s_and_b32 s75, s73, 1
	s_lshl_b32 s75, s75, 7
	s_add_u32 s75, s75, s78
	v_and_b32_e32 v189, 31, v196
	v_bfe_u32 v190, v196, 5, 1
	v_mul_u32_u24_e32 v191, 272, v189
	v_add_u32_e32 v191, s76, v191
	v_lshl_add_u32 v176, v190, 4, v191
	v_lshl_add_u32 v177, v190, 3, v191
	v_lshlrev_b32_e32 v191, 2, v190
	v_add_lshl_u32 v183, v191, s75, 2
	v_add_lshl_u32 v186, v189, s74, 2
	v_and_b32_e32 v191, 63, v196
	v_xor_b32_e32 v191, 32, v191
	v_lshlrev_b32_e32 v187, 2, v191
	v_bfe_u32 v189, v196, 4, 2
	v_and_b32_e32 v190, 15, v196
	v_mul_u32_u24_e32 v191, 272, v189
	v_lshl_add_u32 v191, v190, 4, v191
	v_add_u32_e32 v178, s76, v191
	v_add_u32_e32 v191, s74, v189
	v_lshlrev_b32_e32 v191, 10, v191
	v_lshl_add_u32 v191, v190, 2, v191
	v_add_lshl_u32 v180, v191, s75, 2
	v_bfe_u32 v189, v196, 3, 3
	v_and_b32_e32 v190, 7, v196
	v_mul_u32_u24_e32 v191, 272, v189
	v_lshl_add_u32 v191, v190, 4, v191
	v_add_u32_e32 v179, s76, v191
	v_add_u32_e32 v191, s74, v189
	v_lshlrev_b32_e32 v191, 10, v191
	v_lshl_add_u32 v191, v190, 3, v191
	v_add_lshl_u32 v182, v191, s75, 1
	v_mov_b32_e32 v184, 0
	v_mov_b32_e32 v185, 0
	s_waitcnt lgkmcnt(0)
	s_add_u32 s74, s64, 0x0
	s_addc_u32 s75, s65, 0
	global_load_dwordx4 v[128:131], v180, s[74:75]
	s_add_u32 s74, s64, 0x4000
	s_addc_u32 s75, s65, 0
	global_load_dwordx4 v[132:135], v180, s[74:75]
	s_add_u32 s74, s64, 0x8000
	s_addc_u32 s75, s65, 0
	global_load_dwordx4 v[136:139], v180, s[74:75]
	s_add_u32 s74, s64, 0xc000
	s_addc_u32 s75, s65, 0
	global_load_dwordx4 v[140:143], v180, s[74:75]
	s_add_u32 s74, s64, 0x10000
	s_addc_u32 s75, s65, 0
	global_load_dwordx4 v[144:147], v180, s[74:75]
	s_add_u32 s74, s64, 0x14000
	s_addc_u32 s75, s65, 0
	global_load_dwordx4 v[148:151], v180, s[74:75]
	s_add_u32 s74, s64, 0x18000
	s_addc_u32 s75, s65, 0
	global_load_dwordx4 v[152:155], v180, s[74:75]
	s_add_u32 s74, s64, 0x1c000
	s_addc_u32 s75, s65, 0
	global_load_dwordx4 v[156:159], v180, s[74:75]
	s_waitcnt vmcnt(7)
	ds_write_b128 v178, v[128:131]
	s_waitcnt vmcnt(6)
	ds_write_b128 v178, v[132:135] offset:1088
	s_waitcnt vmcnt(5)
	ds_write_b128 v178, v[136:139] offset:2176
	s_waitcnt vmcnt(4)
	ds_write_b128 v178, v[140:143] offset:3264
	s_waitcnt vmcnt(3)
	ds_write_b128 v178, v[144:147] offset:4352
	s_waitcnt vmcnt(2)
	ds_write_b128 v178, v[148:151] offset:5440
	s_waitcnt vmcnt(1)
	ds_write_b128 v178, v[152:155] offset:6528
	s_waitcnt vmcnt(0)
	ds_write_b128 v178, v[156:159] offset:7616
	ds_read_b128 v[128:131], v176
	ds_read_b128 v[132:135], v176 offset:32
	ds_read_b128 v[136:139], v176 offset:64
	ds_read_b128 v[140:143], v176 offset:96
	ds_read_b128 v[144:147], v176 offset:128
	ds_read_b128 v[148:151], v176 offset:160
	ds_read_b128 v[152:155], v176 offset:192
	ds_read_b128 v[156:159], v176 offset:224
	s_waitcnt lgkmcnt(7)
	v_add_f32_e32 v112, v128, v112
	v_add_f32_e32 v113, v129, v113
	v_add_f32_e32 v114, v130, v114
	v_add_f32_e32 v115, v131, v115
	v_fmac_f32_e32 v184, v112, v112
	v_fmac_f32_e32 v184, v113, v113
	v_fmac_f32_e32 v184, v114, v114
	v_fmac_f32_e32 v184, v115, v115
	ds_write_b128 v176, v[112:115]
	s_waitcnt lgkmcnt(7)
	v_add_f32_e32 v116, v132, v116
	v_add_f32_e32 v117, v133, v117
	v_add_f32_e32 v118, v134, v118
	v_add_f32_e32 v119, v135, v119
	v_fmac_f32_e32 v184, v116, v116
	v_fmac_f32_e32 v184, v117, v117
	v_fmac_f32_e32 v184, v118, v118
	v_fmac_f32_e32 v184, v119, v119
	ds_write_b128 v176, v[116:119] offset:32
	s_waitcnt lgkmcnt(7)
; DI bfr f2bf(float a) { return (bfr)(pack2(a, 0.f) & 0xffffu); }
; DI int crow(int reg, int h) { return (reg & 3) + 8 * (reg >> 2) + 4 * h; }
; template <bool FIRST, bool HAS_H>
; DI void phase_gemm_resid(const Params& p, const bfr* A, const bfr* Wt, const float* gnext, float* ss, char* smem) {
;     ...
;         for (int jh = 0; jh < 2; ++jh) {
;           float xo[2][8];
; #pragma unroll
;           for (int jj = 0; jj < 2; ++jj)
; #pragma unroll
;             for (int q = 0; q < 8; ++q)
;               xo[jj][q] = xsrc[(rbase + i * 32 + crow(qh * 8 + q, 0)) * 1024 + cbase + (jh * 2 + jj) * 32];
; #pragma unroll
;           for (int q = 0; q < 8; ++q) {
;             const int o = (rbase + i * 32 + crow(qh * 8 + q, 0)) * 1024 + cbase;
; #pragma unroll
;             for (int jj = 0; jj < 2; ++jj) {
;               const int j = jh * 2 + jj;
;               const float xn = xo[jj][q] + acc[i][j][qh * 8 + q];
;               X[o + j * 32] = xn;
;               if (HAS_H) Hn[o + j * 32] = f2bf(xn * gnext[cbase + j * 32]);
;               rs[q] += xn * xn;
;             }
;           }
	v_add_f32_e32 v120, v136, v120
	v_add_f32_e32 v121, v137, v121
	v_add_f32_e32 v122, v138, v122
	v_add_f32_e32 v123, v139, v123
	v_fmac_f32_e32 v184, v120, v120
	v_fmac_f32_e32 v184, v121, v121
	v_fmac_f32_e32 v184, v122, v122
	v_fmac_f32_e32 v184, v123, v123
	ds_write_b128 v176, v[120:123] offset:64
	s_waitcnt lgkmcnt(7)
	v_add_f32_e32 v124, v140, v124
	v_add_f32_e32 v125, v141, v125
	v_add_f32_e32 v126, v142, v126
	v_add_f32_e32 v127, v143, v127
	v_fmac_f32_e32 v184, v124, v124
	v_fmac_f32_e32 v184, v125, v125
	v_fmac_f32_e32 v184, v126, v126
	v_fmac_f32_e32 v184, v127, v127
	ds_write_b128 v176, v[124:127] offset:96
	s_waitcnt lgkmcnt(7)
	v_add_f32_e32 v96, v144, v96
	v_add_f32_e32 v97, v145, v97
	v_add_f32_e32 v98, v146, v98
	v_add_f32_e32 v99, v147, v99
	v_fmac_f32_e32 v184, v96, v96
	v_fmac_f32_e32 v184, v97, v97
	v_fmac_f32_e32 v184, v98, v98
	v_fmac_f32_e32 v184, v99, v99
	ds_write_b128 v176, v[96:99] offset:128
	s_waitcnt lgkmcnt(7)
	v_add_f32_e32 v100, v148, v100
	v_add_f32_e32 v101, v149, v101
	v_add_f32_e32 v102, v150, v102
	v_add_f32_e32 v103, v151, v103
	v_fmac_f32_e32 v184, v100, v100
	v_fmac_f32_e32 v184, v101, v101
	v_fmac_f32_e32 v184, v102, v102
	v_fmac_f32_e32 v184, v103, v103
	ds_write_b128 v176, v[100:103] offset:160
	s_waitcnt lgkmcnt(7)
	v_add_f32_e32 v104, v152, v104
	v_add_f32_e32 v105, v153, v105
	v_add_f32_e32 v106, v154, v106
	v_add_f32_e32 v107, v155, v107
	v_fmac_f32_e32 v184, v104, v104
	v_fmac_f32_e32 v184, v105, v105
	v_fmac_f32_e32 v184, v106, v106
	v_fmac_f32_e32 v184, v107, v107
	ds_write_b128 v176, v[104:107] offset:192
	s_waitcnt lgkmcnt(7)
	v_add_f32_e32 v108, v156, v108
	v_add_f32_e32 v109, v157, v109
	v_add_f32_e32 v110, v158, v110
	v_add_f32_e32 v111, v159, v111
	v_fmac_f32_e32 v184, v108, v108
	v_fmac_f32_e32 v184, v109, v109
	v_fmac_f32_e32 v184, v110, v110
	v_fmac_f32_e32 v184, v111, v111
	ds_write_b128 v176, v[108:111] offset:224
	ds_read_b128 v[128:131], v178
	ds_read_b128 v[132:135], v178 offset:1088
	ds_read_b128 v[136:139], v178 offset:2176
	ds_read_b128 v[140:143], v178 offset:3264
	ds_read_b128 v[144:147], v178 offset:4352
	ds_read_b128 v[148:151], v178 offset:5440
	ds_read_b128 v[152:155], v178 offset:6528
	ds_read_b128 v[156:159], v178 offset:7616
	s_add_u32 s74, s66, 0x0
	s_addc_u32 s75, s67, 0
	s_waitcnt lgkmcnt(7)
	global_store_dwordx4 v180, v[128:131], s[74:75]
	s_add_u32 s74, s66, 0x4000
	s_addc_u32 s75, s67, 0
	s_waitcnt lgkmcnt(6)
	global_store_dwordx4 v180, v[132:135], s[74:75]
	s_add_u32 s74, s66, 0x8000
	s_addc_u32 s75, s67, 0
	s_waitcnt lgkmcnt(5)
	global_store_dwordx4 v180, v[136:139], s[74:75]
	s_add_u32 s74, s66, 0xc000
	s_addc_u32 s75, s67, 0
	s_waitcnt lgkmcnt(4)
	global_store_dwordx4 v180, v[140:143], s[74:75]
	s_add_u32 s74, s66, 0x10000
	s_addc_u32 s75, s67, 0
	s_waitcnt lgkmcnt(3)
	global_store_dwordx4 v180, v[144:147], s[74:75]
	s_add_u32 s74, s66, 0x14000
	s_addc_u32 s75, s67, 0
	s_waitcnt lgkmcnt(2)
	global_store_dwordx4 v180, v[148:151], s[74:75]
	s_add_u32 s74, s66, 0x18000
	s_addc_u32 s75, s67, 0
	s_waitcnt lgkmcnt(1)
	global_store_dwordx4 v180, v[152:155], s[74:75]
	s_add_u32 s74, s66, 0x1c000
	s_addc_u32 s75, s67, 0
	s_waitcnt lgkmcnt(0)
	global_store_dwordx4 v180, v[156:159], s[74:75]
	s_add_u32 s74, s64, 0x100
	s_addc_u32 s75, s65, 0
	global_load_dwordx4 v[128:131], v180, s[74:75]
	s_add_u32 s74, s64, 0x4100
	s_addc_u32 s75, s65, 0
	global_load_dwordx4 v[132:135], v180, s[74:75]
	s_add_u32 s74, s64, 0x8100
	s_addc_u32 s75, s65, 0
	global_load_dwordx4 v[136:139], v180, s[74:75]
	s_add_u32 s74, s64, 0xc100
	s_addc_u32 s75, s65, 0
	global_load_dwordx4 v[140:143], v180, s[74:75]
	s_add_u32 s74, s64, 0x10100
	s_addc_u32 s75, s65, 0
	global_load_dwordx4 v[144:147], v180, s[74:75]
	s_add_u32 s74, s64, 0x14100
	s_addc_u32 s75, s65, 0
	global_load_dwordx4 v[148:151], v180, s[74:75]
	s_add_u32 s74, s64, 0x18100
	s_addc_u32 s75, s65, 0
	global_load_dwordx4 v[152:155], v180, s[74:75]
	s_add_u32 s74, s64, 0x1c100
	s_addc_u32 s75, s65, 0
	global_load_dwordx4 v[156:159], v180, s[74:75]
	s_waitcnt vmcnt(7)
	ds_write_b128 v178, v[128:131]
	s_waitcnt vmcnt(6)
	ds_write_b128 v178, v[132:135] offset:1088
	s_waitcnt vmcnt(5)
	ds_write_b128 v178, v[136:139] offset:2176
	s_waitcnt vmcnt(4)
	ds_write_b128 v178, v[140:143] offset:3264
	s_waitcnt vmcnt(3)
	ds_write_b128 v178, v[144:147] offset:4352
	s_waitcnt vmcnt(2)
	ds_write_b128 v178, v[148:151] offset:5440
	s_waitcnt vmcnt(1)
	ds_write_b128 v178, v[152:155] offset:6528
	s_waitcnt vmcnt(0)
	ds_write_b128 v178, v[156:159] offset:7616
	ds_read_b128 v[128:131], v176
	ds_read_b128 v[132:135], v176 offset:32
	ds_read_b128 v[136:139], v176 offset:64
	ds_read_b128 v[140:143], v176 offset:96
	ds_read_b128 v[144:147], v176 offset:128
	ds_read_b128 v[148:151], v176 offset:160
	ds_read_b128 v[152:155], v176 offset:192
	ds_read_b128 v[156:159], v176 offset:224
	s_waitcnt lgkmcnt(7)
	v_add_f32_e32 v80, v128, v80
	v_add_f32_e32 v81, v129, v81
	v_add_f32_e32 v82, v130, v82
	v_add_f32_e32 v83, v131, v83
	v_fmac_f32_e32 v184, v80, v80
	v_fmac_f32_e32 v184, v81, v81
	v_fmac_f32_e32 v184, v82, v82
	v_fmac_f32_e32 v184, v83, v83
	ds_write_b128 v176, v[80:83]
	s_waitcnt lgkmcnt(7)
	v_add_f32_e32 v84, v132, v84
	v_add_f32_e32 v85, v133, v85
	v_add_f32_e32 v86, v134, v86
	v_add_f32_e32 v87, v135, v87
	v_fmac_f32_e32 v184, v84, v84
	v_fmac_f32_e32 v184, v85, v85
	v_fmac_f32_e32 v184, v86, v86
	v_fmac_f32_e32 v184, v87, v87
	ds_write_b128 v176, v[84:87] offset:32
	s_waitcnt lgkmcnt(7)
	v_add_f32_e32 v88, v136, v88
	v_add_f32_e32 v89, v137, v89
	v_add_f32_e32 v90, v138, v90
	v_add_f32_e32 v91, v139, v91
	v_fmac_f32_e32 v184, v88, v88
	v_fmac_f32_e32 v184, v89, v89
	v_fmac_f32_e32 v184, v90, v90
	v_fmac_f32_e32 v184, v91, v91
	ds_write_b128 v176, v[88:91] offset:64
	s_waitcnt lgkmcnt(7)
; DI bfr f2bf(float a) { return (bfr)(pack2(a, 0.f) & 0xffffu); }
; DI int crow(int reg, int h) { return (reg & 3) + 8 * (reg >> 2) + 4 * h; }
; template <bool FIRST, bool HAS_H>
; DI void phase_gemm_resid(const Params& p, const bfr* A, const bfr* Wt, const float* gnext, float* ss, char* smem) {
;     ...
;         for (int jh = 0; jh < 2; ++jh) {
;           float xo[2][8];
; #pragma unroll
;           for (int jj = 0; jj < 2; ++jj)
; #pragma unroll
;             for (int q = 0; q < 8; ++q)
;               xo[jj][q] = xsrc[(rbase + i * 32 + crow(qh * 8 + q, 0)) * 1024 + cbase + (jh * 2 + jj) * 32];
; #pragma unroll
;           for (int q = 0; q < 8; ++q) {
;             const int o = (rbase + i * 32 + crow(qh * 8 + q, 0)) * 1024 + cbase;
; #pragma unroll
;             for (int jj = 0; jj < 2; ++jj) {
;               const int j = jh * 2 + jj;
;               const float xn = xo[jj][q] + acc[i][j][qh * 8 + q];
;               X[o + j * 32] = xn;
;               if (HAS_H) Hn[o + j * 32] = f2bf(xn * gnext[cbase + j * 32]);
;               rs[q] += xn * xn;
;             }
;           }
	v_add_f32_e32 v92, v140, v92
	v_add_f32_e32 v93, v141, v93
	v_add_f32_e32 v94, v142, v94
	v_add_f32_e32 v95, v143, v95
	v_fmac_f32_e32 v184, v92, v92
	v_fmac_f32_e32 v184, v93, v93
	v_fmac_f32_e32 v184, v94, v94
	v_fmac_f32_e32 v184, v95, v95
	ds_write_b128 v176, v[92:95] offset:96
	s_waitcnt lgkmcnt(7)
	v_add_f32_e32 v64, v144, v64
	v_add_f32_e32 v65, v145, v65
	v_add_f32_e32 v66, v146, v66
	v_add_f32_e32 v67, v147, v67
	v_fmac_f32_e32 v184, v64, v64
	v_fmac_f32_e32 v184, v65, v65
	v_fmac_f32_e32 v184, v66, v66
	v_fmac_f32_e32 v184, v67, v67
	ds_write_b128 v176, v[64:67] offset:128
	s_waitcnt lgkmcnt(7)
	v_add_f32_e32 v68, v148, v68
	v_add_f32_e32 v69, v149, v69
	v_add_f32_e32 v70, v150, v70
	v_add_f32_e32 v71, v151, v71
	v_fmac_f32_e32 v184, v68, v68
	v_fmac_f32_e32 v184, v69, v69
	v_fmac_f32_e32 v184, v70, v70
	v_fmac_f32_e32 v184, v71, v71
	ds_write_b128 v176, v[68:71] offset:160
	s_waitcnt lgkmcnt(7)
	v_add_f32_e32 v72, v152, v72
	v_add_f32_e32 v73, v153, v73
	v_add_f32_e32 v74, v154, v74
	v_add_f32_e32 v75, v155, v75
	v_fmac_f32_e32 v184, v72, v72
	v_fmac_f32_e32 v184, v73, v73
	v_fmac_f32_e32 v184, v74, v74
	v_fmac_f32_e32 v184, v75, v75
	ds_write_b128 v176, v[72:75] offset:192
	s_waitcnt lgkmcnt(7)
	v_add_f32_e32 v76, v156, v76
	v_add_f32_e32 v77, v157, v77
	v_add_f32_e32 v78, v158, v78
	v_add_f32_e32 v79, v159, v79
	v_fmac_f32_e32 v184, v76, v76
	v_fmac_f32_e32 v184, v77, v77
	v_fmac_f32_e32 v184, v78, v78
	v_fmac_f32_e32 v184, v79, v79
	ds_write_b128 v176, v[76:79] offset:224
	ds_read_b128 v[128:131], v178
	ds_read_b128 v[132:135], v178 offset:1088
	ds_read_b128 v[136:139], v178 offset:2176
	ds_read_b128 v[140:143], v178 offset:3264
	ds_read_b128 v[144:147], v178 offset:4352
	ds_read_b128 v[148:151], v178 offset:5440
	ds_read_b128 v[152:155], v178 offset:6528
	ds_read_b128 v[156:159], v178 offset:7616
	s_add_u32 s74, s66, 0x100
	s_addc_u32 s75, s67, 0
	s_waitcnt lgkmcnt(7)
	global_store_dwordx4 v180, v[128:131], s[74:75]
	s_add_u32 s74, s66, 0x4100
	s_addc_u32 s75, s67, 0
	s_waitcnt lgkmcnt(6)
	global_store_dwordx4 v180, v[132:135], s[74:75]
	s_add_u32 s74, s66, 0x8100
	s_addc_u32 s75, s67, 0
	s_waitcnt lgkmcnt(5)
	global_store_dwordx4 v180, v[136:139], s[74:75]
	s_add_u32 s74, s66, 0xc100
	s_addc_u32 s75, s67, 0
	s_waitcnt lgkmcnt(4)
	global_store_dwordx4 v180, v[140:143], s[74:75]
	s_add_u32 s74, s66, 0x10100
	s_addc_u32 s75, s67, 0
	s_waitcnt lgkmcnt(3)
	global_store_dwordx4 v180, v[144:147], s[74:75]
	s_add_u32 s74, s66, 0x14100
	s_addc_u32 s75, s67, 0
	s_waitcnt lgkmcnt(2)
	global_store_dwordx4 v180, v[148:151], s[74:75]
	s_add_u32 s74, s66, 0x18100
	s_addc_u32 s75, s67, 0
	s_waitcnt lgkmcnt(1)
	global_store_dwordx4 v180, v[152:155], s[74:75]
	s_add_u32 s74, s66, 0x1c100
	s_addc_u32 s75, s67, 0
	s_waitcnt lgkmcnt(0)
	global_store_dwordx4 v180, v[156:159], s[74:75]
	s_add_u32 s74, s64, 0x20000
	s_addc_u32 s75, s65, 0
	global_load_dwordx4 v[128:131], v180, s[74:75]
	s_add_u32 s74, s64, 0x24000
	s_addc_u32 s75, s65, 0
	global_load_dwordx4 v[132:135], v180, s[74:75]
	s_add_u32 s74, s64, 0x28000
	s_addc_u32 s75, s65, 0
	global_load_dwordx4 v[136:139], v180, s[74:75]
	s_add_u32 s74, s64, 0x2c000
	s_addc_u32 s75, s65, 0
	global_load_dwordx4 v[140:143], v180, s[74:75]
	s_add_u32 s74, s64, 0x30000
	s_addc_u32 s75, s65, 0
	global_load_dwordx4 v[144:147], v180, s[74:75]
	s_add_u32 s74, s64, 0x34000
	s_addc_u32 s75, s65, 0
	global_load_dwordx4 v[148:151], v180, s[74:75]
	s_add_u32 s74, s64, 0x38000
	s_addc_u32 s75, s65, 0
	global_load_dwordx4 v[152:155], v180, s[74:75]
	s_add_u32 s74, s64, 0x3c000
	s_addc_u32 s75, s65, 0
	global_load_dwordx4 v[156:159], v180, s[74:75]
	s_waitcnt vmcnt(7)
	ds_write_b128 v178, v[128:131]
	s_waitcnt vmcnt(6)
	ds_write_b128 v178, v[132:135] offset:1088
	s_waitcnt vmcnt(5)
	ds_write_b128 v178, v[136:139] offset:2176
	s_waitcnt vmcnt(4)
	ds_write_b128 v178, v[140:143] offset:3264
	s_waitcnt vmcnt(3)
	ds_write_b128 v178, v[144:147] offset:4352
	s_waitcnt vmcnt(2)
	ds_write_b128 v178, v[148:151] offset:5440
	s_waitcnt vmcnt(1)
	ds_write_b128 v178, v[152:155] offset:6528
	s_waitcnt vmcnt(0)
	ds_write_b128 v178, v[156:159] offset:7616
	ds_read_b128 v[128:131], v176
	ds_read_b128 v[132:135], v176 offset:32
	ds_read_b128 v[136:139], v176 offset:64
	ds_read_b128 v[140:143], v176 offset:96
	ds_read_b128 v[144:147], v176 offset:128
	ds_read_b128 v[148:151], v176 offset:160
	ds_read_b128 v[152:155], v176 offset:192
	ds_read_b128 v[156:159], v176 offset:224
	s_waitcnt lgkmcnt(7)
	v_add_f32_e32 v48, v128, v48
	v_add_f32_e32 v49, v129, v49
	v_add_f32_e32 v50, v130, v50
	v_add_f32_e32 v51, v131, v51
	v_fmac_f32_e32 v185, v48, v48
	v_fmac_f32_e32 v185, v49, v49
	v_fmac_f32_e32 v185, v50, v50
	v_fmac_f32_e32 v185, v51, v51
	ds_write_b128 v176, v[48:51]
	s_waitcnt lgkmcnt(7)
	v_add_f32_e32 v52, v132, v52
	v_add_f32_e32 v53, v133, v53
	v_add_f32_e32 v54, v134, v54
	v_add_f32_e32 v55, v135, v55
	v_fmac_f32_e32 v185, v52, v52
	v_fmac_f32_e32 v185, v53, v53
	v_fmac_f32_e32 v185, v54, v54
	v_fmac_f32_e32 v185, v55, v55
	ds_write_b128 v176, v[52:55] offset:32
	s_waitcnt lgkmcnt(7)
	v_add_f32_e32 v56, v136, v56
	v_add_f32_e32 v57, v137, v57
	v_add_f32_e32 v58, v138, v58
	v_add_f32_e32 v59, v139, v59
	v_fmac_f32_e32 v185, v56, v56
	v_fmac_f32_e32 v185, v57, v57
	v_fmac_f32_e32 v185, v58, v58
	v_fmac_f32_e32 v185, v59, v59
	ds_write_b128 v176, v[56:59] offset:64
	s_waitcnt lgkmcnt(7)
	v_add_f32_e32 v60, v140, v60
	v_add_f32_e32 v61, v141, v61
	v_add_f32_e32 v62, v142, v62
	v_add_f32_e32 v63, v143, v63
	v_fmac_f32_e32 v185, v60, v60
	v_fmac_f32_e32 v185, v61, v61
	v_fmac_f32_e32 v185, v62, v62
	v_fmac_f32_e32 v185, v63, v63
	ds_write_b128 v176, v[60:63] offset:96
	s_waitcnt lgkmcnt(7)
; DI bfr f2bf(float a) { return (bfr)(pack2(a, 0.f) & 0xffffu); }
; DI int crow(int reg, int h) { return (reg & 3) + 8 * (reg >> 2) + 4 * h; }
; template <bool FIRST, bool HAS_H>
; DI void phase_gemm_resid(const Params& p, const bfr* A, const bfr* Wt, const float* gnext, float* ss, char* smem) {
;     ...
;         for (int jh = 0; jh < 2; ++jh) {
;           float xo[2][8];
; #pragma unroll
;           for (int jj = 0; jj < 2; ++jj)
; #pragma unroll
;             for (int q = 0; q < 8; ++q)
;               xo[jj][q] = xsrc[(rbase + i * 32 + crow(qh * 8 + q, 0)) * 1024 + cbase + (jh * 2 + jj) * 32];
; #pragma unroll
;           for (int q = 0; q < 8; ++q) {
;             const int o = (rbase + i * 32 + crow(qh * 8 + q, 0)) * 1024 + cbase;
; #pragma unroll
;             for (int jj = 0; jj < 2; ++jj) {
;               const int j = jh * 2 + jj;
;               const float xn = xo[jj][q] + acc[i][j][qh * 8 + q];
;               X[o + j * 32] = xn;
;               if (HAS_H) Hn[o + j * 32] = f2bf(xn * gnext[cbase + j * 32]);
;               rs[q] += xn * xn;
;             }
;           }
	v_add_f32_e32 v32, v144, v32
	v_add_f32_e32 v33, v145, v33
	v_add_f32_e32 v34, v146, v34
	v_add_f32_e32 v35, v147, v35
	v_fmac_f32_e32 v185, v32, v32
	v_fmac_f32_e32 v185, v33, v33
	v_fmac_f32_e32 v185, v34, v34
	v_fmac_f32_e32 v185, v35, v35
	ds_write_b128 v176, v[32:35] offset:128
	s_waitcnt lgkmcnt(7)
	v_add_f32_e32 v36, v148, v36
	v_add_f32_e32 v37, v149, v37
	v_add_f32_e32 v38, v150, v38
	v_add_f32_e32 v39, v151, v39
	v_fmac_f32_e32 v185, v36, v36
	v_fmac_f32_e32 v185, v37, v37
	v_fmac_f32_e32 v185, v38, v38
	v_fmac_f32_e32 v185, v39, v39
	ds_write_b128 v176, v[36:39] offset:160
	s_waitcnt lgkmcnt(7)
	v_add_f32_e32 v40, v152, v40
	v_add_f32_e32 v41, v153, v41
	v_add_f32_e32 v42, v154, v42
	v_add_f32_e32 v43, v155, v43
	v_fmac_f32_e32 v185, v40, v40
	v_fmac_f32_e32 v185, v41, v41
	v_fmac_f32_e32 v185, v42, v42
	v_fmac_f32_e32 v185, v43, v43
	ds_write_b128 v176, v[40:43] offset:192
	s_waitcnt lgkmcnt(7)
	v_add_f32_e32 v44, v156, v44
	v_add_f32_e32 v45, v157, v45
	v_add_f32_e32 v46, v158, v46
	v_add_f32_e32 v47, v159, v47
	v_fmac_f32_e32 v185, v44, v44
	v_fmac_f32_e32 v185, v45, v45
	v_fmac_f32_e32 v185, v46, v46
	v_fmac_f32_e32 v185, v47, v47
	ds_write_b128 v176, v[44:47] offset:224
	ds_read_b128 v[128:131], v178
	ds_read_b128 v[132:135], v178 offset:1088
	ds_read_b128 v[136:139], v178 offset:2176
	ds_read_b128 v[140:143], v178 offset:3264
	ds_read_b128 v[144:147], v178 offset:4352
	ds_read_b128 v[148:151], v178 offset:5440
	ds_read_b128 v[152:155], v178 offset:6528
	ds_read_b128 v[156:159], v178 offset:7616
	s_add_u32 s74, s66, 0x20000
	s_addc_u32 s75, s67, 0
	s_waitcnt lgkmcnt(7)
	global_store_dwordx4 v180, v[128:131], s[74:75]
	s_add_u32 s74, s66, 0x24000
	s_addc_u32 s75, s67, 0
	s_waitcnt lgkmcnt(6)
	global_store_dwordx4 v180, v[132:135], s[74:75]
	s_add_u32 s74, s66, 0x28000
	s_addc_u32 s75, s67, 0
	s_waitcnt lgkmcnt(5)
	global_store_dwordx4 v180, v[136:139], s[74:75]
	s_add_u32 s74, s66, 0x2c000
	s_addc_u32 s75, s67, 0
	s_waitcnt lgkmcnt(4)
	global_store_dwordx4 v180, v[140:143], s[74:75]
	s_add_u32 s74, s66, 0x30000
	s_addc_u32 s75, s67, 0
	s_waitcnt lgkmcnt(3)
	global_store_dwordx4 v180, v[144:147], s[74:75]
	s_add_u32 s74, s66, 0x34000
	s_addc_u32 s75, s67, 0
	s_waitcnt lgkmcnt(2)
	global_store_dwordx4 v180, v[148:151], s[74:75]
	s_add_u32 s74, s66, 0x38000
	s_addc_u32 s75, s67, 0
	s_waitcnt lgkmcnt(1)
	global_store_dwordx4 v180, v[152:155], s[74:75]
	s_add_u32 s74, s66, 0x3c000
	s_addc_u32 s75, s67, 0
	s_waitcnt lgkmcnt(0)
	global_store_dwordx4 v180, v[156:159], s[74:75]
	s_add_u32 s74, s64, 0x20100
	s_addc_u32 s75, s65, 0
	global_load_dwordx4 v[128:131], v180, s[74:75]
	s_add_u32 s74, s64, 0x24100
	s_addc_u32 s75, s65, 0
	global_load_dwordx4 v[132:135], v180, s[74:75]
	s_add_u32 s74, s64, 0x28100
	s_addc_u32 s75, s65, 0
	global_load_dwordx4 v[136:139], v180, s[74:75]
	s_add_u32 s74, s64, 0x2c100
	s_addc_u32 s75, s65, 0
	global_load_dwordx4 v[140:143], v180, s[74:75]
	s_add_u32 s74, s64, 0x30100
	s_addc_u32 s75, s65, 0
	global_load_dwordx4 v[144:147], v180, s[74:75]
	s_add_u32 s74, s64, 0x34100
	s_addc_u32 s75, s65, 0
	global_load_dwordx4 v[148:151], v180, s[74:75]
	s_add_u32 s74, s64, 0x38100
	s_addc_u32 s75, s65, 0
	global_load_dwordx4 v[152:155], v180, s[74:75]
	s_add_u32 s74, s64, 0x3c100
	s_addc_u32 s75, s65, 0
	global_load_dwordx4 v[156:159], v180, s[74:75]
	s_waitcnt vmcnt(7)
	ds_write_b128 v178, v[128:131]
	s_waitcnt vmcnt(6)
	ds_write_b128 v178, v[132:135] offset:1088
	s_waitcnt vmcnt(5)
	ds_write_b128 v178, v[136:139] offset:2176
	s_waitcnt vmcnt(4)
	ds_write_b128 v178, v[140:143] offset:3264
	s_waitcnt vmcnt(3)
	ds_write_b128 v178, v[144:147] offset:4352
	s_waitcnt vmcnt(2)
	ds_write_b128 v178, v[148:151] offset:5440
	s_waitcnt vmcnt(1)
	ds_write_b128 v178, v[152:155] offset:6528
	s_waitcnt vmcnt(0)
	ds_write_b128 v178, v[156:159] offset:7616
	ds_read_b128 v[128:131], v176
	ds_read_b128 v[132:135], v176 offset:32
	ds_read_b128 v[136:139], v176 offset:64
	ds_read_b128 v[140:143], v176 offset:96
	ds_read_b128 v[144:147], v176 offset:128
	ds_read_b128 v[148:151], v176 offset:160
	ds_read_b128 v[152:155], v176 offset:192
	ds_read_b128 v[156:159], v176 offset:224
	s_waitcnt lgkmcnt(7)
	v_add_f32_e32 v16, v128, v16
	v_add_f32_e32 v17, v129, v17
	v_add_f32_e32 v18, v130, v18
	v_add_f32_e32 v19, v131, v19
	v_fmac_f32_e32 v185, v16, v16
	v_fmac_f32_e32 v185, v17, v17
	v_fmac_f32_e32 v185, v18, v18
	v_fmac_f32_e32 v185, v19, v19
	ds_write_b128 v176, v[16:19]
	s_waitcnt lgkmcnt(7)
; DI bfr f2bf(float a) { return (bfr)(pack2(a, 0.f) & 0xffffu); }
; DI int crow(int reg, int h) { return (reg & 3) + 8 * (reg >> 2) + 4 * h; }
; template <bool FIRST, bool HAS_H>
; DI void phase_gemm_resid(const Params& p, const bfr* A, const bfr* Wt, const float* gnext, float* ss, char* smem) {
;     ...
;         for (int jh = 0; jh < 2; ++jh) {
;           float xo[2][8];
; #pragma unroll
;           for (int jj = 0; jj < 2; ++jj)
; #pragma unroll
;             for (int q = 0; q < 8; ++q)
;               xo[jj][q] = xsrc[(rbase + i * 32 + crow(qh * 8 + q, 0)) * 1024 + cbase + (jh * 2 + jj) * 32];
; #pragma unroll
;           for (int q = 0; q < 8; ++q) {
;             const int o = (rbase + i * 32 + crow(qh * 8 + q, 0)) * 1024 + cbase;
; #pragma unroll
;             for (int jj = 0; jj < 2; ++jj) {
;               const int j = jh * 2 + jj;
;               const float xn = xo[jj][q] + acc[i][j][qh * 8 + q];
;               X[o + j * 32] = xn;
;               if (HAS_H) Hn[o + j * 32] = f2bf(xn * gnext[cbase + j * 32]);
;               rs[q] += xn * xn;
;             }
;           }
;         }
; #pragma unroll
;         for (int q = 0; q < 8; ++q) rs[q] = half32_sum_hi(rs[q]);
;         if (r == 31) {
; #pragma unroll
;           for (int q = 0; q < 8; ++q) unsafeAtomicAdd(ss + rbase + i * 32 + crow(qh * 8 + q, 0), rs[q]);
;         }
	v_add_f32_e32 v20, v132, v20
	v_add_f32_e32 v21, v133, v21
	v_add_f32_e32 v22, v134, v22
	v_add_f32_e32 v23, v135, v23
	v_fmac_f32_e32 v185, v20, v20
	v_fmac_f32_e32 v185, v21, v21
	v_fmac_f32_e32 v185, v22, v22
	v_fmac_f32_e32 v185, v23, v23
	ds_write_b128 v176, v[20:23] offset:32
	s_waitcnt lgkmcnt(7)
	v_add_f32_e32 v24, v136, v24
	v_add_f32_e32 v25, v137, v25
	v_add_f32_e32 v26, v138, v26
	v_add_f32_e32 v27, v139, v27
	v_fmac_f32_e32 v185, v24, v24
	v_fmac_f32_e32 v185, v25, v25
	v_fmac_f32_e32 v185, v26, v26
	v_fmac_f32_e32 v185, v27, v27
	ds_write_b128 v176, v[24:27] offset:64
	s_waitcnt lgkmcnt(7)
	v_add_f32_e32 v28, v140, v28
	v_add_f32_e32 v29, v141, v29
	v_add_f32_e32 v30, v142, v30
	v_add_f32_e32 v31, v143, v31
	v_fmac_f32_e32 v185, v28, v28
	v_fmac_f32_e32 v185, v29, v29
	v_fmac_f32_e32 v185, v30, v30
	v_fmac_f32_e32 v185, v31, v31
	ds_write_b128 v176, v[28:31] offset:96
	s_waitcnt lgkmcnt(7)
	v_add_f32_e32 v0, v144, v0
	v_add_f32_e32 v1, v145, v1
	v_add_f32_e32 v2, v146, v2
	v_add_f32_e32 v3, v147, v3
	v_fmac_f32_e32 v185, v0, v0
	v_fmac_f32_e32 v185, v1, v1
	v_fmac_f32_e32 v185, v2, v2
	v_fmac_f32_e32 v185, v3, v3
	ds_write_b128 v176, v[0:3] offset:128
	s_waitcnt lgkmcnt(7)
	v_add_f32_e32 v4, v148, v4
	v_add_f32_e32 v5, v149, v5
	v_add_f32_e32 v6, v150, v6
	v_add_f32_e32 v7, v151, v7
	v_fmac_f32_e32 v185, v4, v4
	v_fmac_f32_e32 v185, v5, v5
	v_fmac_f32_e32 v185, v6, v6
	v_fmac_f32_e32 v185, v7, v7
	ds_write_b128 v176, v[4:7] offset:160
	s_waitcnt lgkmcnt(7)
	v_add_f32_e32 v8, v152, v8
	v_add_f32_e32 v9, v153, v9
	v_add_f32_e32 v10, v154, v10
	v_add_f32_e32 v11, v155, v11
	v_fmac_f32_e32 v185, v8, v8
	v_fmac_f32_e32 v185, v9, v9
	v_fmac_f32_e32 v185, v10, v10
	v_fmac_f32_e32 v185, v11, v11
	ds_write_b128 v176, v[8:11] offset:192
	s_waitcnt lgkmcnt(7)
	v_add_f32_e32 v12, v156, v12
	v_add_f32_e32 v13, v157, v13
	v_add_f32_e32 v14, v158, v14
	v_add_f32_e32 v15, v159, v15
	v_fmac_f32_e32 v185, v12, v12
	v_fmac_f32_e32 v185, v13, v13
	v_fmac_f32_e32 v185, v14, v14
	v_fmac_f32_e32 v185, v15, v15
	ds_write_b128 v176, v[12:15] offset:224
	ds_read_b128 v[128:131], v178
	ds_read_b128 v[132:135], v178 offset:1088
	ds_read_b128 v[136:139], v178 offset:2176
	ds_read_b128 v[140:143], v178 offset:3264
	ds_read_b128 v[144:147], v178 offset:4352
	ds_read_b128 v[148:151], v178 offset:5440
	ds_read_b128 v[152:155], v178 offset:6528
	ds_read_b128 v[156:159], v178 offset:7616
	s_add_u32 s74, s66, 0x20100
	s_addc_u32 s75, s67, 0
	s_waitcnt lgkmcnt(7)
	global_store_dwordx4 v180, v[128:131], s[74:75]
	s_add_u32 s74, s66, 0x24100
	s_addc_u32 s75, s67, 0
	s_waitcnt lgkmcnt(6)
	global_store_dwordx4 v180, v[132:135], s[74:75]
	s_add_u32 s74, s66, 0x28100
	s_addc_u32 s75, s67, 0
	s_waitcnt lgkmcnt(5)
	global_store_dwordx4 v180, v[136:139], s[74:75]
	s_add_u32 s74, s66, 0x2c100
	s_addc_u32 s75, s67, 0
	s_waitcnt lgkmcnt(4)
	global_store_dwordx4 v180, v[140:143], s[74:75]
	s_add_u32 s74, s66, 0x30100
	s_addc_u32 s75, s67, 0
	s_waitcnt lgkmcnt(3)
	global_store_dwordx4 v180, v[144:147], s[74:75]
	s_add_u32 s74, s66, 0x34100
	s_addc_u32 s75, s67, 0
	s_waitcnt lgkmcnt(2)
	global_store_dwordx4 v180, v[148:151], s[74:75]
	s_add_u32 s74, s66, 0x38100
	s_addc_u32 s75, s67, 0
	s_waitcnt lgkmcnt(1)
	global_store_dwordx4 v180, v[152:155], s[74:75]
	s_add_u32 s74, s66, 0x3c100
	s_addc_u32 s75, s67, 0
	s_waitcnt lgkmcnt(0)
	global_store_dwordx4 v180, v[156:159], s[74:75]
	s_load_dwordx2 s[64:65], s[92:93], 0x140
	ds_bpermute_b32 v189, v187, v184
	ds_bpermute_b32 v190, v187, v185
	s_waitcnt lgkmcnt(0)
	s_add_u32 s64, s64, 0x30600
	s_addc_u32 s65, s65, 0
	v_add_f32_e32 v189, v189, v184
	v_add_f32_e32 v190, v190, v185
	s_mov_b32 exec_hi, 0
	s_nop 1
	global_atomic_add_f32 v186, v189, s[64:65]
	global_atomic_add_f32 v186, v190, s[64:65] offset:128
	s_mov_b64 exec, -1
	v_readlane_b32 s64, v188, 0
	v_readlane_b32 s65, v188, 1
	v_readlane_b32 s66, v188, 2
	v_readlane_b32 s67, v188, 3
	v_readlane_b32 s68, v188, 4
	v_readlane_b32 s69, v188, 5
	v_readlane_b32 s70, v188, 6
	v_readlane_b32 s71, v188, 7
	v_readlane_b32 s72, v188, 8
	v_readlane_b32 s73, v188, 9
	v_readlane_b32 s74, v188, 10
	v_readlane_b32 s75, v188, 11
	v_readlane_b32 s76, v188, 12
	v_readlane_b32 s77, v188, 13
	v_readlane_b32 s78, v188, 14
	v_readlane_b32 s79, v188, 15
	s_nop 7
	s_branch .LBB0_1718
